# w_in GEMM on the hand-written 272x128 tile routine with fragment-major weights and rotary epilogues; co-resident blocks share the A row tile
# speedup vs baseline: 1.1142x; 1.0497x over previous
.Lg2_ff2_entry:
	s_waitcnt vmcnt(0) lgkmcnt(0)
	s_barrier
	v_mov_b32_e32 v2, 0x10200
	ds_read_b64 v[2:3], v2
	v_readlane_b32 s0, v246, 0
	v_lshrrev_b32_e32 v4, 6, v163
	v_and_b32_e32 v5, 63, v163
	s_and_b32 s1, s0, 7
	s_lshr_b32 s0, s0, 3
	s_lshr_b32 s68, s0, 3
	s_and_b32 s0, s0, 7
	s_lshl_b32 s0, s0, 3
	s_add_i32 s0, s0, s1
	s_cmp_lt_u32 s0, 32
	s_cselect_b32 s43, 1, 0
	s_min_u32 s1, s0, 32
	s_lshl_b32 s0, s0, 4
	s_add_i32 s0, s0, s1
	s_lshl_b32 s42, s0, 4
	v_readfirstlane_b32 s70, v4
	v_and_b32_e32 v6, 15, v5
	v_lshrrev_b32_e32 v7, 4, v5
	s_waitcnt lgkmcnt(0)
	v_readfirstlane_b32 s66, v2
	v_readfirstlane_b32 s67, v3
	s_lshl_b32 s62, s70, 10
	v_and_b32_e32 v8, 7, v6
	v_xor_b32_e32 v9, v7, v8
	v_lshlrev_b32_e32 v9, 4, v9
	v_lshl_add_u32 v156, v6, 7, v9
	v_add_u32_e32 v10, 4, v7
	v_xor_b32_e32 v10, v10, v8
	v_lshlrev_b32_e32 v10, 4, v10
	v_lshl_add_u32 v157, v6, 7, v10
	v_add_u32_e32 v158, 0x8800, v156
	v_add_u32_e32 v159, 0x8800, v157
	v_lshrrev_b32_e32 v11, 3, v163
	v_and_b32_e32 v12, 7, v163
	v_and_b32_e32 v13, 7, v11
	v_xor_b32_e32 v12, v12, v13
	v_lshlrev_b32_e32 v12, 4, v12
	s_mov_b32 s2, 0x2000
	v_mul_lo_u32 v11, v11, s2
	v_add_u32_e32 v162, v11, v12
	v_lshrrev_b32_e32 v11, 4, v163
	v_and_b32_e32 v12, 15, v163
	v_xor_b32_e32 v13, v12, v11
	v_lshlrev_b32_e32 v13, 4, v13
	v_lshl_add_u32 v247, v11, 8, v13
	s_mov_b32 s2, 0x800
	v_mul_lo_u32 v11, v11, s2
	v_lshl_add_u32 v252, v12, 4, v11
	v_add_u32_e32 v255, 0x8000, v247
	v_lshlrev_b32_e32 v11, 1, v4
	s_mov_b32 s2, 0x20000
	v_mul_lo_u32 v12, v11, s2
	v_lshl_add_u32 v160, v5, 4, v12
	v_add_u32_e32 v161, 0x20000, v160
	v_lshrrev_b32_e32 v12, 1, v7
	v_lshl_add_u32 v12, v11, 1, v12
	v_and_b32_e32 v13, 1, v7
	v_lshlrev_b32_e32 v13, 3, v13
	v_lshl_add_u32 v14, v6, 8, v13
	v_xor_b32_e32 v15, v12, v6
	v_lshlrev_b32_e32 v15, 4, v15
	v_add_u32_e32 v212, v14, v15
	v_add_u32_e32 v12, 2, v12
	v_xor_b32_e32 v15, v12, v6
	v_lshlrev_b32_e32 v15, 4, v15
	v_add_u32_e32 v213, v14, v15
	v_add_u32_e32 v253, 0x8000, v212
	v_add_u32_e32 v254, 0x8000, v213
	s_mov_b32 s64, 0
.Lg2_ff2_tile:
	s_lshl_b32 s0, s64, 3
	s_add_i32 s38, s0, s68
	s_mov_b32 s69, s42
	s_mov_b32 s65, s43
	s_lshl_b32 s0, s38, 7
	s_mul_i32 s2, s69, 0x2000
	s_mul_hi_u32 s3, s69, 0x2000
	s_add_u32 s56, s26, s2
	s_addc_u32 s57, s27, s3
	s_add_u32 s56, s56, 0x0
	s_addc_u32 s57, s57, 0
	s_mul_i32 s2, s0, 0x2000
	s_mul_hi_u32 s3, s0, 0x2000
	s_add_u32 s58, s26, s2
	s_addc_u32 s59, s27, s3
	s_add_u32 s58, s58, 0x10740000
	s_addc_u32 s59, s59, 0
	s_mul_i32 s2, s69, 0x800
	s_mul_hi_u32 s3, s69, 0x800
	s_lshl_b32 s0, s0, 1
	s_add_u32 s2, s2, s0
	s_addc_u32 s3, s3, 0
	s_add_u32 s60, s26, s2
	s_addc_u32 s61, s27, s3
	s_add_u32 s60, s60, 0x11140000
	s_addc_u32 s61, s61, 0
	s_cmp_eq_u32 s65, 0
	s_cbranch_scc1 .Lg2_ff2_k16
	v_mov_b32_e32 v0, 0
	v_mov_b32_e32 v1, 0
	v_mov_b32_e32 v2, 0
	v_mov_b32_e32 v3, 0
	v_mov_b32_e32 v4, 0
	v_mov_b32_e32 v5, 0
	v_mov_b32_e32 v6, 0
	v_mov_b32_e32 v7, 0
	v_mov_b32_e32 v8, 0
	v_mov_b32_e32 v9, 0
	v_mov_b32_e32 v10, 0
	v_mov_b32_e32 v11, 0
	v_mov_b32_e32 v12, 0
	v_mov_b32_e32 v13, 0
	v_mov_b32_e32 v14, 0
	v_mov_b32_e32 v15, 0
	v_mov_b32_e32 v16, 0
	v_mov_b32_e32 v17, 0
	v_mov_b32_e32 v18, 0
	v_mov_b32_e32 v19, 0
	v_mov_b32_e32 v20, 0
	v_mov_b32_e32 v21, 0
	v_mov_b32_e32 v22, 0
	v_mov_b32_e32 v23, 0
	v_mov_b32_e32 v24, 0
	v_mov_b32_e32 v25, 0
	v_mov_b32_e32 v26, 0
	v_mov_b32_e32 v27, 0
	v_mov_b32_e32 v28, 0
	v_mov_b32_e32 v29, 0
	v_mov_b32_e32 v30, 0
	v_mov_b32_e32 v31, 0
	v_mov_b32_e32 v32, 0
	v_mov_b32_e32 v33, 0
	v_mov_b32_e32 v34, 0
	v_mov_b32_e32 v35, 0
	v_mov_b32_e32 v36, 0
	v_mov_b32_e32 v37, 0
	v_mov_b32_e32 v38, 0
	v_mov_b32_e32 v39, 0
	v_mov_b32_e32 v40, 0
	v_mov_b32_e32 v41, 0
	v_mov_b32_e32 v42, 0
	v_mov_b32_e32 v43, 0
	v_mov_b32_e32 v44, 0
	v_mov_b32_e32 v45, 0
	v_mov_b32_e32 v46, 0
	v_mov_b32_e32 v47, 0
	v_mov_b32_e32 v48, 0
	v_mov_b32_e32 v49, 0
	v_mov_b32_e32 v50, 0
	v_mov_b32_e32 v51, 0
	v_mov_b32_e32 v52, 0
	v_mov_b32_e32 v53, 0
	v_mov_b32_e32 v54, 0
	v_mov_b32_e32 v55, 0
	v_mov_b32_e32 v56, 0
	v_mov_b32_e32 v57, 0
	v_mov_b32_e32 v58, 0
	v_mov_b32_e32 v59, 0
	v_mov_b32_e32 v60, 0
	v_mov_b32_e32 v61, 0
	v_mov_b32_e32 v62, 0
	v_mov_b32_e32 v63, 0
	v_mov_b32_e32 v64, 0
	v_mov_b32_e32 v65, 0
	v_mov_b32_e32 v66, 0
	v_mov_b32_e32 v67, 0
	v_mov_b32_e32 v68, 0
	v_mov_b32_e32 v69, 0
	v_mov_b32_e32 v70, 0
	v_mov_b32_e32 v71, 0
	v_mov_b32_e32 v72, 0
	v_mov_b32_e32 v73, 0
	v_mov_b32_e32 v74, 0
	v_mov_b32_e32 v75, 0
	v_mov_b32_e32 v76, 0
	v_mov_b32_e32 v77, 0
	v_mov_b32_e32 v78, 0
	v_mov_b32_e32 v79, 0
	v_mov_b32_e32 v80, 0
	v_mov_b32_e32 v81, 0
	v_mov_b32_e32 v82, 0
	v_mov_b32_e32 v83, 0
	v_mov_b32_e32 v84, 0
	v_mov_b32_e32 v85, 0
	v_mov_b32_e32 v86, 0
	v_mov_b32_e32 v87, 0
	v_mov_b32_e32 v88, 0
	v_mov_b32_e32 v89, 0
	v_mov_b32_e32 v90, 0
	v_mov_b32_e32 v91, 0
	v_mov_b32_e32 v92, 0
	v_mov_b32_e32 v93, 0
	v_mov_b32_e32 v94, 0
	v_mov_b32_e32 v95, 0
	v_mov_b32_e32 v96, 0
	v_mov_b32_e32 v97, 0
	v_mov_b32_e32 v98, 0
	v_mov_b32_e32 v99, 0
	v_mov_b32_e32 v100, 0
	v_mov_b32_e32 v101, 0
	v_mov_b32_e32 v102, 0
	v_mov_b32_e32 v103, 0
	v_mov_b32_e32 v104, 0
	v_mov_b32_e32 v105, 0
	v_mov_b32_e32 v106, 0
	v_mov_b32_e32 v107, 0
	v_mov_b32_e32 v108, 0
	v_mov_b32_e32 v109, 0
	v_mov_b32_e32 v110, 0
	v_mov_b32_e32 v111, 0
	v_mov_b32_e32 v112, 0
	v_mov_b32_e32 v113, 0
	v_mov_b32_e32 v114, 0
	v_mov_b32_e32 v115, 0
	v_mov_b32_e32 v116, 0
	v_mov_b32_e32 v117, 0
	v_mov_b32_e32 v118, 0
	v_mov_b32_e32 v119, 0
	v_mov_b32_e32 v120, 0
	v_mov_b32_e32 v121, 0
	v_mov_b32_e32 v122, 0
	v_mov_b32_e32 v123, 0
	v_mov_b32_e32 v124, 0
	v_mov_b32_e32 v125, 0
	v_mov_b32_e32 v126, 0
	v_mov_b32_e32 v127, 0
	v_mov_b32_e32 v128, 0
	v_mov_b32_e32 v129, 0
	v_mov_b32_e32 v130, 0
	v_mov_b32_e32 v131, 0
	v_mov_b32_e32 v132, 0
	v_mov_b32_e32 v133, 0
	v_mov_b32_e32 v134, 0
	v_mov_b32_e32 v135, 0
	s_add_u32 s4, s56, 0x0
	s_addc_u32 s5, s57, 0
	s_add_u32 m0, s62, 0x0
	s_nop 0
	global_load_lds_dwordx4 v162, s[4:5]
	s_add_u32 s4, s56, 0x40000
	s_addc_u32 s5, s57, 0
	s_add_u32 m0, s62, 0x1000
	s_nop 0
	global_load_lds_dwordx4 v162, s[4:5]
	s_add_u32 s4, s56, 0x80000
	s_addc_u32 s5, s57, 0
	s_add_u32 m0, s62, 0x2000
	s_nop 0
	global_load_lds_dwordx4 v162, s[4:5]
	s_add_u32 s4, s56, 0xc0000
	s_addc_u32 s5, s57, 0
	s_add_u32 m0, s62, 0x3000
	s_nop 0
	global_load_lds_dwordx4 v162, s[4:5]
	s_add_u32 s4, s56, 0x100000
	s_addc_u32 s5, s57, 0
	s_add_u32 m0, s62, 0x4000
	s_nop 0
	global_load_lds_dwordx4 v162, s[4:5]
	s_add_u32 s4, s56, 0x140000
	s_addc_u32 s5, s57, 0
	s_add_u32 m0, s62, 0x5000
	s_nop 0
	global_load_lds_dwordx4 v162, s[4:5]
	s_add_u32 s4, s56, 0x180000
	s_addc_u32 s5, s57, 0
	s_add_u32 m0, s62, 0x6000
	s_nop 0
	global_load_lds_dwordx4 v162, s[4:5]
	s_add_u32 s4, s56, 0x1c0000
	s_addc_u32 s5, s57, 0
	s_add_u32 m0, s62, 0x7000
	s_nop 0
	global_load_lds_dwordx4 v162, s[4:5]
	s_cmp_gt_u32 s70, 1
	s_cbranch_scc1 .Lg2_ff2_nodma_0
	s_add_u32 s4, s56, 0x200000
	s_addc_u32 s5, s57, 0
	s_add_u32 m0, s62, 0x8000
	s_nop 0
	global_load_lds_dwordx4 v162, s[4:5]
.Lg2_ff2_nodma_0:
	global_load_dwordx4 v[184:187], v160, s[58:59] offset:0
	global_load_dwordx4 v[188:191], v160, s[58:59] offset:1024
	global_load_dwordx4 v[192:195], v161, s[58:59] offset:0
	global_load_dwordx4 v[196:199], v161, s[58:59] offset:1024
	s_mov_b32 s63, 0
.Lg2_ff2_loop17:
	s_waitcnt vmcnt(0)
	s_barrier
	s_add_u32 s56, s56, 0x80
	s_addc_u32 s57, s57, 0
	s_add_u32 s58, s58, 0x800
	s_addc_u32 s59, s59, 0
	s_add_u32 s4, s56, 0x0
	s_addc_u32 s5, s57, 0
	s_add_u32 m0, s62, 0x8800
	s_nop 0
	global_load_lds_dwordx4 v162, s[4:5]
	s_add_u32 s4, s56, 0x40000
	s_addc_u32 s5, s57, 0
	s_add_u32 m0, s62, 0x9800
	s_nop 0
	global_load_lds_dwordx4 v162, s[4:5]
	s_add_u32 s4, s56, 0x80000
	s_addc_u32 s5, s57, 0
	s_add_u32 m0, s62, 0xa800
	s_nop 0
	global_load_lds_dwordx4 v162, s[4:5]
	s_add_u32 s4, s56, 0xc0000
	s_addc_u32 s5, s57, 0
	s_add_u32 m0, s62, 0xb800
	s_nop 0
	global_load_lds_dwordx4 v162, s[4:5]
	s_add_u32 s4, s56, 0x100000
	s_addc_u32 s5, s57, 0
	s_add_u32 m0, s62, 0xc800
	s_nop 0
	global_load_lds_dwordx4 v162, s[4:5]
	s_add_u32 s4, s56, 0x140000
	s_addc_u32 s5, s57, 0
	s_add_u32 m0, s62, 0xd800
	s_nop 0
	global_load_lds_dwordx4 v162, s[4:5]
	s_add_u32 s4, s56, 0x180000
	s_addc_u32 s5, s57, 0
	s_add_u32 m0, s62, 0xe800
	s_nop 0
	global_load_lds_dwordx4 v162, s[4:5]
	s_add_u32 s4, s56, 0x1c0000
	s_addc_u32 s5, s57, 0
	s_add_u32 m0, s62, 0xf800
	s_nop 0
	global_load_lds_dwordx4 v162, s[4:5]
	s_cmp_gt_u32 s70, 1
	s_cbranch_scc1 .Lg2_ff2_nodma_1
	s_add_u32 s4, s56, 0x200000
	s_addc_u32 s5, s57, 0
	s_add_u32 m0, s62, 0x10800
	s_nop 0
	global_load_lds_dwordx4 v162, s[4:5]
.Lg2_ff2_nodma_1:
	global_load_dwordx4 v[200:203], v160, s[58:59] offset:0
	global_load_dwordx4 v[204:207], v160, s[58:59] offset:1024
	global_load_dwordx4 v[208:211], v161, s[58:59] offset:0
	global_load_dwordx4 v[240:243], v161, s[58:59] offset:1024
	ds_read_b128 v[136:139], v156 offset:0
	ds_read_b128 v[140:143], v156 offset:2048
	ds_read_b128 v[144:147], v156 offset:4096
	ds_read_b128 v[148:151], v156 offset:6144
	ds_read_b128 v[164:167], v156 offset:8192
	ds_read_b128 v[168:171], v156 offset:10240
	ds_read_b128 v[172:175], v156 offset:12288
	ds_read_b128 v[176:179], v156 offset:14336
	s_waitcnt lgkmcnt(4)
	v_mfma_f32_16x16x32_bf16 v[0:3], v[184:187], v[136:139], v[0:3]
	v_mfma_f32_16x16x32_bf16 v[4:7], v[192:195], v[136:139], v[4:7]
	v_mfma_f32_16x16x32_bf16 v[8:11], v[184:187], v[140:143], v[8:11]
	v_mfma_f32_16x16x32_bf16 v[12:15], v[192:195], v[140:143], v[12:15]
	v_mfma_f32_16x16x32_bf16 v[16:19], v[184:187], v[144:147], v[16:19]
	v_mfma_f32_16x16x32_bf16 v[20:23], v[192:195], v[144:147], v[20:23]
	v_mfma_f32_16x16x32_bf16 v[24:27], v[184:187], v[148:151], v[24:27]
	v_mfma_f32_16x16x32_bf16 v[28:31], v[192:195], v[148:151], v[28:31]
	ds_read_b128 v[136:139], v156 offset:16384
	ds_read_b128 v[140:143], v156 offset:18432
	ds_read_b128 v[144:147], v156 offset:20480
	ds_read_b128 v[148:151], v156 offset:22528
	s_waitcnt lgkmcnt(4)
	v_mfma_f32_16x16x32_bf16 v[32:35], v[184:187], v[164:167], v[32:35]
	v_mfma_f32_16x16x32_bf16 v[36:39], v[192:195], v[164:167], v[36:39]
	v_mfma_f32_16x16x32_bf16 v[40:43], v[184:187], v[168:171], v[40:43]
	v_mfma_f32_16x16x32_bf16 v[44:47], v[192:195], v[168:171], v[44:47]
	v_mfma_f32_16x16x32_bf16 v[48:51], v[184:187], v[172:175], v[48:51]
	v_mfma_f32_16x16x32_bf16 v[52:55], v[192:195], v[172:175], v[52:55]
	v_mfma_f32_16x16x32_bf16 v[56:59], v[184:187], v[176:179], v[56:59]
	v_mfma_f32_16x16x32_bf16 v[60:63], v[192:195], v[176:179], v[60:63]
	ds_read_b128 v[164:167], v156 offset:24576
	ds_read_b128 v[168:171], v156 offset:26624
	ds_read_b128 v[172:175], v156 offset:28672
	ds_read_b128 v[176:179], v156 offset:30720
	ds_read_b128 v[180:183], v156 offset:32768
	s_waitcnt lgkmcnt(5)
	v_mfma_f32_16x16x32_bf16 v[64:67], v[184:187], v[136:139], v[64:67]
	v_mfma_f32_16x16x32_bf16 v[68:71], v[192:195], v[136:139], v[68:71]
	v_mfma_f32_16x16x32_bf16 v[72:75], v[184:187], v[140:143], v[72:75]
	v_mfma_f32_16x16x32_bf16 v[76:79], v[192:195], v[140:143], v[76:79]
	v_mfma_f32_16x16x32_bf16 v[80:83], v[184:187], v[144:147], v[80:83]
	v_mfma_f32_16x16x32_bf16 v[84:87], v[192:195], v[144:147], v[84:87]
	v_mfma_f32_16x16x32_bf16 v[88:91], v[184:187], v[148:151], v[88:91]
	v_mfma_f32_16x16x32_bf16 v[92:95], v[192:195], v[148:151], v[92:95]
	ds_read_b128 v[136:139], v157 offset:0
	ds_read_b128 v[140:143], v157 offset:2048
	ds_read_b128 v[144:147], v157 offset:4096
	ds_read_b128 v[148:151], v157 offset:6144
	s_waitcnt lgkmcnt(4)
	v_mfma_f32_16x16x32_bf16 v[96:99], v[184:187], v[164:167], v[96:99]
	v_mfma_f32_16x16x32_bf16 v[100:103], v[192:195], v[164:167], v[100:103]
	v_mfma_f32_16x16x32_bf16 v[104:107], v[184:187], v[168:171], v[104:107]
	v_mfma_f32_16x16x32_bf16 v[108:111], v[192:195], v[168:171], v[108:111]
	v_mfma_f32_16x16x32_bf16 v[112:115], v[184:187], v[172:175], v[112:115]
	v_mfma_f32_16x16x32_bf16 v[116:119], v[192:195], v[172:175], v[116:119]
	v_mfma_f32_16x16x32_bf16 v[120:123], v[184:187], v[176:179], v[120:123]
	v_mfma_f32_16x16x32_bf16 v[124:127], v[192:195], v[176:179], v[124:127]
	v_mfma_f32_16x16x32_bf16 v[128:131], v[184:187], v[180:183], v[128:131]
	v_mfma_f32_16x16x32_bf16 v[132:135], v[192:195], v[180:183], v[132:135]
	ds_read_b128 v[164:167], v157 offset:8192
	ds_read_b128 v[168:171], v157 offset:10240
	ds_read_b128 v[172:175], v157 offset:12288
	ds_read_b128 v[176:179], v157 offset:14336
	s_waitcnt lgkmcnt(4)
	v_mfma_f32_16x16x32_bf16 v[0:3], v[188:191], v[136:139], v[0:3]
	v_mfma_f32_16x16x32_bf16 v[4:7], v[196:199], v[136:139], v[4:7]
	v_mfma_f32_16x16x32_bf16 v[8:11], v[188:191], v[140:143], v[8:11]
	v_mfma_f32_16x16x32_bf16 v[12:15], v[196:199], v[140:143], v[12:15]
	v_mfma_f32_16x16x32_bf16 v[16:19], v[188:191], v[144:147], v[16:19]
	v_mfma_f32_16x16x32_bf16 v[20:23], v[196:199], v[144:147], v[20:23]
	v_mfma_f32_16x16x32_bf16 v[24:27], v[188:191], v[148:151], v[24:27]
	v_mfma_f32_16x16x32_bf16 v[28:31], v[196:199], v[148:151], v[28:31]
	ds_read_b128 v[136:139], v157 offset:16384
	ds_read_b128 v[140:143], v157 offset:18432
	ds_read_b128 v[144:147], v157 offset:20480
	ds_read_b128 v[148:151], v157 offset:22528
	s_waitcnt lgkmcnt(4)
	v_mfma_f32_16x16x32_bf16 v[32:35], v[188:191], v[164:167], v[32:35]
	v_mfma_f32_16x16x32_bf16 v[36:39], v[196:199], v[164:167], v[36:39]
	v_mfma_f32_16x16x32_bf16 v[40:43], v[188:191], v[168:171], v[40:43]
	v_mfma_f32_16x16x32_bf16 v[44:47], v[196:199], v[168:171], v[44:47]
	v_mfma_f32_16x16x32_bf16 v[48:51], v[188:191], v[172:175], v[48:51]
	v_mfma_f32_16x16x32_bf16 v[52:55], v[196:199], v[172:175], v[52:55]
	v_mfma_f32_16x16x32_bf16 v[56:59], v[188:191], v[176:179], v[56:59]
	v_mfma_f32_16x16x32_bf16 v[60:63], v[196:199], v[176:179], v[60:63]
	ds_read_b128 v[164:167], v157 offset:24576
	ds_read_b128 v[168:171], v157 offset:26624
	ds_read_b128 v[172:175], v157 offset:28672
	ds_read_b128 v[176:179], v157 offset:30720
	ds_read_b128 v[180:183], v157 offset:32768
	s_waitcnt lgkmcnt(5)
	v_mfma_f32_16x16x32_bf16 v[64:67], v[188:191], v[136:139], v[64:67]
	v_mfma_f32_16x16x32_bf16 v[68:71], v[196:199], v[136:139], v[68:71]
	v_mfma_f32_16x16x32_bf16 v[72:75], v[188:191], v[140:143], v[72:75]
	v_mfma_f32_16x16x32_bf16 v[76:79], v[196:199], v[140:143], v[76:79]
	v_mfma_f32_16x16x32_bf16 v[80:83], v[188:191], v[144:147], v[80:83]
	v_mfma_f32_16x16x32_bf16 v[84:87], v[196:199], v[144:147], v[84:87]
	v_mfma_f32_16x16x32_bf16 v[88:91], v[188:191], v[148:151], v[88:91]
	v_mfma_f32_16x16x32_bf16 v[92:95], v[196:199], v[148:151], v[92:95]
	s_waitcnt lgkmcnt(0)
	v_mfma_f32_16x16x32_bf16 v[96:99], v[188:191], v[164:167], v[96:99]
	v_mfma_f32_16x16x32_bf16 v[100:103], v[196:199], v[164:167], v[100:103]
	v_mfma_f32_16x16x32_bf16 v[104:107], v[188:191], v[168:171], v[104:107]
	v_mfma_f32_16x16x32_bf16 v[108:111], v[196:199], v[168:171], v[108:111]
	v_mfma_f32_16x16x32_bf16 v[112:115], v[188:191], v[172:175], v[112:115]
	v_mfma_f32_16x16x32_bf16 v[116:119], v[196:199], v[172:175], v[116:119]
	v_mfma_f32_16x16x32_bf16 v[120:123], v[188:191], v[176:179], v[120:123]
	v_mfma_f32_16x16x32_bf16 v[124:127], v[196:199], v[176:179], v[124:127]
	v_mfma_f32_16x16x32_bf16 v[128:131], v[188:191], v[180:183], v[128:131]
	v_mfma_f32_16x16x32_bf16 v[132:135], v[196:199], v[180:183], v[132:135]
	s_waitcnt vmcnt(0)
	s_barrier
	s_cmp_ge_u32 s63, 62
	s_cbranch_scc1 .Lg2_ff2_noissue17
	s_add_u32 s56, s56, 0x80
	s_addc_u32 s57, s57, 0
	s_add_u32 s58, s58, 0x800
	s_addc_u32 s59, s59, 0
	s_add_u32 s4, s56, 0x0
	s_addc_u32 s5, s57, 0
	s_add_u32 m0, s62, 0x0
	s_nop 0
	global_load_lds_dwordx4 v162, s[4:5]
	s_add_u32 s4, s56, 0x40000
	s_addc_u32 s5, s57, 0
	s_add_u32 m0, s62, 0x1000
	s_nop 0
	global_load_lds_dwordx4 v162, s[4:5]
	s_add_u32 s4, s56, 0x80000
	s_addc_u32 s5, s57, 0
	s_add_u32 m0, s62, 0x2000
	s_nop 0
	global_load_lds_dwordx4 v162, s[4:5]
	s_add_u32 s4, s56, 0xc0000
	s_addc_u32 s5, s57, 0
	s_add_u32 m0, s62, 0x3000
	s_nop 0
	global_load_lds_dwordx4 v162, s[4:5]
	s_add_u32 s4, s56, 0x100000
	s_addc_u32 s5, s57, 0
	s_add_u32 m0, s62, 0x4000
	s_nop 0
	global_load_lds_dwordx4 v162, s[4:5]
	s_add_u32 s4, s56, 0x140000
	s_addc_u32 s5, s57, 0
	s_add_u32 m0, s62, 0x5000
	s_nop 0
	global_load_lds_dwordx4 v162, s[4:5]
	s_add_u32 s4, s56, 0x180000
	s_addc_u32 s5, s57, 0
	s_add_u32 m0, s62, 0x6000
	s_nop 0
	global_load_lds_dwordx4 v162, s[4:5]
	s_add_u32 s4, s56, 0x1c0000
	s_addc_u32 s5, s57, 0
	s_add_u32 m0, s62, 0x7000
	s_nop 0
	global_load_lds_dwordx4 v162, s[4:5]
	s_cmp_gt_u32 s70, 1
	s_cbranch_scc1 .Lg2_ff2_nodma_2
	s_add_u32 s4, s56, 0x200000
	s_addc_u32 s5, s57, 0
	s_add_u32 m0, s62, 0x8000
	s_nop 0
	global_load_lds_dwordx4 v162, s[4:5]
.Lg2_ff2_nodma_2:
	global_load_dwordx4 v[184:187], v160, s[58:59] offset:0
	global_load_dwordx4 v[188:191], v160, s[58:59] offset:1024
	global_load_dwordx4 v[192:195], v161, s[58:59] offset:0
	global_load_dwordx4 v[196:199], v161, s[58:59] offset:1024

.Lg2_ff2_k16:
	v_mov_b32_e32 v0, 0
	v_mov_b32_e32 v1, 0
	v_mov_b32_e32 v2, 0
	v_mov_b32_e32 v3, 0
	v_mov_b32_e32 v4, 0
	v_mov_b32_e32 v5, 0
	v_mov_b32_e32 v6, 0
	v_mov_b32_e32 v7, 0
	v_mov_b32_e32 v8, 0
	v_mov_b32_e32 v9, 0
	v_mov_b32_e32 v10, 0
	v_mov_b32_e32 v11, 0
	v_mov_b32_e32 v12, 0
	v_mov_b32_e32 v13, 0
	v_mov_b32_e32 v14, 0
	v_mov_b32_e32 v15, 0
	v_mov_b32_e32 v16, 0
	v_mov_b32_e32 v17, 0
	v_mov_b32_e32 v18, 0
	v_mov_b32_e32 v19, 0
	v_mov_b32_e32 v20, 0
	v_mov_b32_e32 v21, 0
	v_mov_b32_e32 v22, 0
	v_mov_b32_e32 v23, 0
	v_mov_b32_e32 v24, 0
	v_mov_b32_e32 v25, 0
	v_mov_b32_e32 v26, 0
	v_mov_b32_e32 v27, 0
	v_mov_b32_e32 v28, 0
	v_mov_b32_e32 v29, 0
	v_mov_b32_e32 v30, 0
	v_mov_b32_e32 v31, 0
	v_mov_b32_e32 v32, 0
	v_mov_b32_e32 v33, 0
	v_mov_b32_e32 v34, 0
	v_mov_b32_e32 v35, 0
	v_mov_b32_e32 v36, 0
	v_mov_b32_e32 v37, 0
	v_mov_b32_e32 v38, 0
	v_mov_b32_e32 v39, 0
	v_mov_b32_e32 v40, 0
	v_mov_b32_e32 v41, 0
	v_mov_b32_e32 v42, 0
	v_mov_b32_e32 v43, 0
	v_mov_b32_e32 v44, 0
	v_mov_b32_e32 v45, 0
	v_mov_b32_e32 v46, 0
	v_mov_b32_e32 v47, 0
	v_mov_b32_e32 v48, 0
	v_mov_b32_e32 v49, 0
	v_mov_b32_e32 v50, 0
	v_mov_b32_e32 v51, 0
	v_mov_b32_e32 v52, 0
	v_mov_b32_e32 v53, 0
	v_mov_b32_e32 v54, 0
	v_mov_b32_e32 v55, 0
	v_mov_b32_e32 v56, 0
	v_mov_b32_e32 v57, 0
	v_mov_b32_e32 v58, 0
	v_mov_b32_e32 v59, 0
	v_mov_b32_e32 v60, 0
	v_mov_b32_e32 v61, 0
	v_mov_b32_e32 v62, 0
	v_mov_b32_e32 v63, 0
	v_mov_b32_e32 v64, 0
	v_mov_b32_e32 v65, 0
	v_mov_b32_e32 v66, 0
	v_mov_b32_e32 v67, 0
	v_mov_b32_e32 v68, 0
	v_mov_b32_e32 v69, 0
	v_mov_b32_e32 v70, 0
	v_mov_b32_e32 v71, 0
	v_mov_b32_e32 v72, 0
	v_mov_b32_e32 v73, 0
	v_mov_b32_e32 v74, 0
	v_mov_b32_e32 v75, 0
	v_mov_b32_e32 v76, 0
	v_mov_b32_e32 v77, 0
	v_mov_b32_e32 v78, 0
	v_mov_b32_e32 v79, 0
	v_mov_b32_e32 v80, 0
	v_mov_b32_e32 v81, 0
	v_mov_b32_e32 v82, 0
	v_mov_b32_e32 v83, 0
	v_mov_b32_e32 v84, 0
	v_mov_b32_e32 v85, 0
	v_mov_b32_e32 v86, 0
	v_mov_b32_e32 v87, 0
	v_mov_b32_e32 v88, 0
	v_mov_b32_e32 v89, 0
	v_mov_b32_e32 v90, 0
	v_mov_b32_e32 v91, 0
	v_mov_b32_e32 v92, 0
	v_mov_b32_e32 v93, 0
	v_mov_b32_e32 v94, 0
	v_mov_b32_e32 v95, 0
	v_mov_b32_e32 v96, 0
	v_mov_b32_e32 v97, 0
	v_mov_b32_e32 v98, 0
	v_mov_b32_e32 v99, 0
	v_mov_b32_e32 v100, 0
	v_mov_b32_e32 v101, 0
	v_mov_b32_e32 v102, 0
	v_mov_b32_e32 v103, 0
	v_mov_b32_e32 v104, 0
	v_mov_b32_e32 v105, 0
	v_mov_b32_e32 v106, 0
	v_mov_b32_e32 v107, 0
	v_mov_b32_e32 v108, 0
	v_mov_b32_e32 v109, 0
	v_mov_b32_e32 v110, 0
	v_mov_b32_e32 v111, 0
	v_mov_b32_e32 v112, 0
	v_mov_b32_e32 v113, 0
	v_mov_b32_e32 v114, 0
	v_mov_b32_e32 v115, 0
	v_mov_b32_e32 v116, 0
	v_mov_b32_e32 v117, 0
	v_mov_b32_e32 v118, 0
	v_mov_b32_e32 v119, 0
	v_mov_b32_e32 v120, 0
	v_mov_b32_e32 v121, 0
	v_mov_b32_e32 v122, 0
	v_mov_b32_e32 v123, 0
	v_mov_b32_e32 v124, 0
	v_mov_b32_e32 v125, 0
	v_mov_b32_e32 v126, 0
	v_mov_b32_e32 v127, 0
	s_add_u32 s4, s56, 0x0
	s_addc_u32 s5, s57, 0
	s_add_u32 m0, s62, 0x0
	s_nop 0
	global_load_lds_dwordx4 v162, s[4:5]
	s_add_u32 s4, s56, 0x40000
	s_addc_u32 s5, s57, 0
	s_add_u32 m0, s62, 0x1000
	s_nop 0
	global_load_lds_dwordx4 v162, s[4:5]
	s_add_u32 s4, s56, 0x80000
	s_addc_u32 s5, s57, 0
	s_add_u32 m0, s62, 0x2000
	s_nop 0
	global_load_lds_dwordx4 v162, s[4:5]
	s_add_u32 s4, s56, 0xc0000
	s_addc_u32 s5, s57, 0
	s_add_u32 m0, s62, 0x3000
	s_nop 0
	global_load_lds_dwordx4 v162, s[4:5]
	s_add_u32 s4, s56, 0x100000
	s_addc_u32 s5, s57, 0
	s_add_u32 m0, s62, 0x4000
	s_nop 0
	global_load_lds_dwordx4 v162, s[4:5]
	s_add_u32 s4, s56, 0x140000
	s_addc_u32 s5, s57, 0
	s_add_u32 m0, s62, 0x5000
	s_nop 0
	global_load_lds_dwordx4 v162, s[4:5]
	s_add_u32 s4, s56, 0x180000
	s_addc_u32 s5, s57, 0
	s_add_u32 m0, s62, 0x6000
	s_nop 0
	global_load_lds_dwordx4 v162, s[4:5]
	s_add_u32 s4, s56, 0x1c0000
	s_addc_u32 s5, s57, 0
	s_add_u32 m0, s62, 0x7000
	s_nop 0
	global_load_lds_dwordx4 v162, s[4:5]
	global_load_dwordx4 v[184:187], v160, s[58:59] offset:0
	global_load_dwordx4 v[188:191], v160, s[58:59] offset:1024
	global_load_dwordx4 v[192:195], v161, s[58:59] offset:0
	global_load_dwordx4 v[196:199], v161, s[58:59] offset:1024
	s_mov_b32 s63, 0
.Lg2_ff2_loop16:
	s_waitcnt vmcnt(0)
	s_barrier
	s_add_u32 s56, s56, 0x80
	s_addc_u32 s57, s57, 0
	s_add_u32 s58, s58, 0x800
	s_addc_u32 s59, s59, 0
	s_add_u32 s4, s56, 0x0
	s_addc_u32 s5, s57, 0
	s_add_u32 m0, s62, 0x8800
	s_nop 0
	global_load_lds_dwordx4 v162, s[4:5]
	s_add_u32 s4, s56, 0x40000
	s_addc_u32 s5, s57, 0
	s_add_u32 m0, s62, 0x9800
	s_nop 0
	global_load_lds_dwordx4 v162, s[4:5]
	s_add_u32 s4, s56, 0x80000
	s_addc_u32 s5, s57, 0
	s_add_u32 m0, s62, 0xa800
	s_nop 0
	global_load_lds_dwordx4 v162, s[4:5]
	s_add_u32 s4, s56, 0xc0000
	s_addc_u32 s5, s57, 0
	s_add_u32 m0, s62, 0xb800
	s_nop 0
	global_load_lds_dwordx4 v162, s[4:5]
	s_add_u32 s4, s56, 0x100000
	s_addc_u32 s5, s57, 0
	s_add_u32 m0, s62, 0xc800
	s_nop 0
	global_load_lds_dwordx4 v162, s[4:5]
	s_add_u32 s4, s56, 0x140000
	s_addc_u32 s5, s57, 0
	s_add_u32 m0, s62, 0xd800
	s_nop 0
	global_load_lds_dwordx4 v162, s[4:5]
	s_add_u32 s4, s56, 0x180000
	s_addc_u32 s5, s57, 0
	s_add_u32 m0, s62, 0xe800
	s_nop 0
	global_load_lds_dwordx4 v162, s[4:5]
	s_add_u32 s4, s56, 0x1c0000
	s_addc_u32 s5, s57, 0
	s_add_u32 m0, s62, 0xf800
	s_nop 0
	global_load_lds_dwordx4 v162, s[4:5]
	global_load_dwordx4 v[200:203], v160, s[58:59] offset:0
	global_load_dwordx4 v[204:207], v160, s[58:59] offset:1024
	global_load_dwordx4 v[208:211], v161, s[58:59] offset:0
	global_load_dwordx4 v[240:243], v161, s[58:59] offset:1024
	ds_read_b128 v[136:139], v156 offset:0
	ds_read_b128 v[140:143], v156 offset:2048
	ds_read_b128 v[144:147], v156 offset:4096
	ds_read_b128 v[148:151], v156 offset:6144
	ds_read_b128 v[164:167], v156 offset:8192
	ds_read_b128 v[168:171], v156 offset:10240
	ds_read_b128 v[172:175], v156 offset:12288
	ds_read_b128 v[176:179], v156 offset:14336
	s_waitcnt lgkmcnt(4)
	v_mfma_f32_16x16x32_bf16 v[0:3], v[184:187], v[136:139], v[0:3]
	v_mfma_f32_16x16x32_bf16 v[4:7], v[192:195], v[136:139], v[4:7]
	v_mfma_f32_16x16x32_bf16 v[8:11], v[184:187], v[140:143], v[8:11]
	v_mfma_f32_16x16x32_bf16 v[12:15], v[192:195], v[140:143], v[12:15]
	v_mfma_f32_16x16x32_bf16 v[16:19], v[184:187], v[144:147], v[16:19]
	v_mfma_f32_16x16x32_bf16 v[20:23], v[192:195], v[144:147], v[20:23]
	v_mfma_f32_16x16x32_bf16 v[24:27], v[184:187], v[148:151], v[24:27]
	v_mfma_f32_16x16x32_bf16 v[28:31], v[192:195], v[148:151], v[28:31]
	ds_read_b128 v[136:139], v156 offset:16384
	ds_read_b128 v[140:143], v156 offset:18432
	ds_read_b128 v[144:147], v156 offset:20480
	ds_read_b128 v[148:151], v156 offset:22528
	s_waitcnt lgkmcnt(4)
	v_mfma_f32_16x16x32_bf16 v[32:35], v[184:187], v[164:167], v[32:35]
	v_mfma_f32_16x16x32_bf16 v[36:39], v[192:195], v[164:167], v[36:39]
	v_mfma_f32_16x16x32_bf16 v[40:43], v[184:187], v[168:171], v[40:43]
	v_mfma_f32_16x16x32_bf16 v[44:47], v[192:195], v[168:171], v[44:47]
	v_mfma_f32_16x16x32_bf16 v[48:51], v[184:187], v[172:175], v[48:51]
	v_mfma_f32_16x16x32_bf16 v[52:55], v[192:195], v[172:175], v[52:55]
	v_mfma_f32_16x16x32_bf16 v[56:59], v[184:187], v[176:179], v[56:59]
	v_mfma_f32_16x16x32_bf16 v[60:63], v[192:195], v[176:179], v[60:63]
	ds_read_b128 v[164:167], v156 offset:24576
	ds_read_b128 v[168:171], v156 offset:26624
	ds_read_b128 v[172:175], v156 offset:28672
	ds_read_b128 v[176:179], v156 offset:30720
	s_waitcnt lgkmcnt(4)
	v_mfma_f32_16x16x32_bf16 v[64:67], v[184:187], v[136:139], v[64:67]
	v_mfma_f32_16x16x32_bf16 v[68:71], v[192:195], v[136:139], v[68:71]
	v_mfma_f32_16x16x32_bf16 v[72:75], v[184:187], v[140:143], v[72:75]
	v_mfma_f32_16x16x32_bf16 v[76:79], v[192:195], v[140:143], v[76:79]
	v_mfma_f32_16x16x32_bf16 v[80:83], v[184:187], v[144:147], v[80:83]
	v_mfma_f32_16x16x32_bf16 v[84:87], v[192:195], v[144:147], v[84:87]
	v_mfma_f32_16x16x32_bf16 v[88:91], v[184:187], v[148:151], v[88:91]
	v_mfma_f32_16x16x32_bf16 v[92:95], v[192:195], v[148:151], v[92:95]
	ds_read_b128 v[136:139], v157 offset:0
	ds_read_b128 v[140:143], v157 offset:2048
	ds_read_b128 v[144:147], v157 offset:4096
	ds_read_b128 v[148:151], v157 offset:6144
	s_waitcnt lgkmcnt(4)
	v_mfma_f32_16x16x32_bf16 v[96:99], v[184:187], v[164:167], v[96:99]
	v_mfma_f32_16x16x32_bf16 v[100:103], v[192:195], v[164:167], v[100:103]
	v_mfma_f32_16x16x32_bf16 v[104:107], v[184:187], v[168:171], v[104:107]
	v_mfma_f32_16x16x32_bf16 v[108:111], v[192:195], v[168:171], v[108:111]
	v_mfma_f32_16x16x32_bf16 v[112:115], v[184:187], v[172:175], v[112:115]
	v_mfma_f32_16x16x32_bf16 v[116:119], v[192:195], v[172:175], v[116:119]
	v_mfma_f32_16x16x32_bf16 v[120:123], v[184:187], v[176:179], v[120:123]
	v_mfma_f32_16x16x32_bf16 v[124:127], v[192:195], v[176:179], v[124:127]
	ds_read_b128 v[164:167], v157 offset:8192
	ds_read_b128 v[168:171], v157 offset:10240
	ds_read_b128 v[172:175], v157 offset:12288
	ds_read_b128 v[176:179], v157 offset:14336
	s_waitcnt lgkmcnt(4)
	v_mfma_f32_16x16x32_bf16 v[0:3], v[188:191], v[136:139], v[0:3]
	v_mfma_f32_16x16x32_bf16 v[4:7], v[196:199], v[136:139], v[4:7]
	v_mfma_f32_16x16x32_bf16 v[8:11], v[188:191], v[140:143], v[8:11]
	v_mfma_f32_16x16x32_bf16 v[12:15], v[196:199], v[140:143], v[12:15]
	v_mfma_f32_16x16x32_bf16 v[16:19], v[188:191], v[144:147], v[16:19]
	v_mfma_f32_16x16x32_bf16 v[20:23], v[196:199], v[144:147], v[20:23]
	v_mfma_f32_16x16x32_bf16 v[24:27], v[188:191], v[148:151], v[24:27]
	v_mfma_f32_16x16x32_bf16 v[28:31], v[196:199], v[148:151], v[28:31]
	ds_read_b128 v[136:139], v157 offset:16384
	ds_read_b128 v[140:143], v157 offset:18432
	ds_read_b128 v[144:147], v157 offset:20480
	ds_read_b128 v[148:151], v157 offset:22528
	s_waitcnt lgkmcnt(4)
	v_mfma_f32_16x16x32_bf16 v[32:35], v[188:191], v[164:167], v[32:35]
	v_mfma_f32_16x16x32_bf16 v[36:39], v[196:199], v[164:167], v[36:39]
	v_mfma_f32_16x16x32_bf16 v[40:43], v[188:191], v[168:171], v[40:43]
	v_mfma_f32_16x16x32_bf16 v[44:47], v[196:199], v[168:171], v[44:47]
	v_mfma_f32_16x16x32_bf16 v[48:51], v[188:191], v[172:175], v[48:51]
	v_mfma_f32_16x16x32_bf16 v[52:55], v[196:199], v[172:175], v[52:55]
	v_mfma_f32_16x16x32_bf16 v[56:59], v[188:191], v[176:179], v[56:59]
	v_mfma_f32_16x16x32_bf16 v[60:63], v[196:199], v[176:179], v[60:63]
	ds_read_b128 v[164:167], v157 offset:24576
	ds_read_b128 v[168:171], v157 offset:26624
	ds_read_b128 v[172:175], v157 offset:28672
	ds_read_b128 v[176:179], v157 offset:30720
	s_waitcnt lgkmcnt(4)
	v_mfma_f32_16x16x32_bf16 v[64:67], v[188:191], v[136:139], v[64:67]
	v_mfma_f32_16x16x32_bf16 v[68:71], v[196:199], v[136:139], v[68:71]
	v_mfma_f32_16x16x32_bf16 v[72:75], v[188:191], v[140:143], v[72:75]
	v_mfma_f32_16x16x32_bf16 v[76:79], v[196:199], v[140:143], v[76:79]
	v_mfma_f32_16x16x32_bf16 v[80:83], v[188:191], v[144:147], v[80:83]
	v_mfma_f32_16x16x32_bf16 v[84:87], v[196:199], v[144:147], v[84:87]
	v_mfma_f32_16x16x32_bf16 v[88:91], v[188:191], v[148:151], v[88:91]
	v_mfma_f32_16x16x32_bf16 v[92:95], v[196:199], v[148:151], v[92:95]
	s_waitcnt lgkmcnt(0)
	v_mfma_f32_16x16x32_bf16 v[96:99], v[188:191], v[164:167], v[96:99]
	v_mfma_f32_16x16x32_bf16 v[100:103], v[196:199], v[164:167], v[100:103]
	v_mfma_f32_16x16x32_bf16 v[104:107], v[188:191], v[168:171], v[104:107]
	v_mfma_f32_16x16x32_bf16 v[108:111], v[196:199], v[168:171], v[108:111]
	v_mfma_f32_16x16x32_bf16 v[112:115], v[188:191], v[172:175], v[112:115]
	v_mfma_f32_16x16x32_bf16 v[116:119], v[196:199], v[172:175], v[116:119]
	v_mfma_f32_16x16x32_bf16 v[120:123], v[188:191], v[176:179], v[120:123]
	v_mfma_f32_16x16x32_bf16 v[124:127], v[196:199], v[176:179], v[124:127]
	s_waitcnt vmcnt(0)
	s_barrier
	s_cmp_ge_u32 s63, 62
	s_cbranch_scc1 .Lg2_ff2_noissue16
	s_add_u32 s56, s56, 0x80
	s_addc_u32 s57, s57, 0
	s_add_u32 s58, s58, 0x800
	s_addc_u32 s59, s59, 0
	s_add_u32 s4, s56, 0x0
	s_addc_u32 s5, s57, 0
	s_add_u32 m0, s62, 0x0
	s_nop 0
	global_load_lds_dwordx4 v162, s[4:5]
	s_add_u32 s4, s56, 0x40000
	s_addc_u32 s5, s57, 0
	s_add_u32 m0, s62, 0x1000
	s_nop 0
	global_load_lds_dwordx4 v162, s[4:5]
	s_add_u32 s4, s56, 0x80000
	s_addc_u32 s5, s57, 0
	s_add_u32 m0, s62, 0x2000
	s_nop 0
	global_load_lds_dwordx4 v162, s[4:5]
	s_add_u32 s4, s56, 0xc0000
	s_addc_u32 s5, s57, 0
	s_add_u32 m0, s62, 0x3000
	s_nop 0
	global_load_lds_dwordx4 v162, s[4:5]
	s_add_u32 s4, s56, 0x100000
	s_addc_u32 s5, s57, 0
	s_add_u32 m0, s62, 0x4000
	s_nop 0
	global_load_lds_dwordx4 v162, s[4:5]
	s_add_u32 s4, s56, 0x140000
	s_addc_u32 s5, s57, 0
	s_add_u32 m0, s62, 0x5000
	s_nop 0
	global_load_lds_dwordx4 v162, s[4:5]
	s_add_u32 s4, s56, 0x180000
	s_addc_u32 s5, s57, 0
	s_add_u32 m0, s62, 0x6000
	s_nop 0
	global_load_lds_dwordx4 v162, s[4:5]
	s_add_u32 s4, s56, 0x1c0000
	s_addc_u32 s5, s57, 0
	s_add_u32 m0, s62, 0x7000
	s_nop 0
	global_load_lds_dwordx4 v162, s[4:5]
	global_load_dwordx4 v[184:187], v160, s[58:59] offset:0
	global_load_dwordx4 v[188:191], v160, s[58:59] offset:1024
	global_load_dwordx4 v[192:195], v161, s[58:59] offset:0
	global_load_dwordx4 v[196:199], v161, s[58:59] offset:1024
.Lg2_ff2_noissue16:
	ds_read_b128 v[136:139], v158 offset:0
	ds_read_b128 v[140:143], v158 offset:2048
	ds_read_b128 v[144:147], v158 offset:4096
	ds_read_b128 v[148:151], v158 offset:6144
	ds_read_b128 v[164:167], v158 offset:8192
	ds_read_b128 v[168:171], v158 offset:10240
	ds_read_b128 v[172:175], v158 offset:12288
	ds_read_b128 v[176:179], v158 offset:14336
	s_waitcnt lgkmcnt(4)
	v_mfma_f32_16x16x32_bf16 v[0:3], v[200:203], v[136:139], v[0:3]
	v_mfma_f32_16x16x32_bf16 v[4:7], v[208:211], v[136:139], v[4:7]
	v_mfma_f32_16x16x32_bf16 v[8:11], v[200:203], v[140:143], v[8:11]
	v_mfma_f32_16x16x32_bf16 v[12:15], v[208:211], v[140:143], v[12:15]
	v_mfma_f32_16x16x32_bf16 v[16:19], v[200:203], v[144:147], v[16:19]
	v_mfma_f32_16x16x32_bf16 v[20:23], v[208:211], v[144:147], v[20:23]
	v_mfma_f32_16x16x32_bf16 v[24:27], v[200:203], v[148:151], v[24:27]
	v_mfma_f32_16x16x32_bf16 v[28:31], v[208:211], v[148:151], v[28:31]
	ds_read_b128 v[136:139], v158 offset:16384
	ds_read_b128 v[140:143], v158 offset:18432
	ds_read_b128 v[144:147], v158 offset:20480
	ds_read_b128 v[148:151], v158 offset:22528
	s_waitcnt lgkmcnt(4)
	v_mfma_f32_16x16x32_bf16 v[32:35], v[200:203], v[164:167], v[32:35]
	v_mfma_f32_16x16x32_bf16 v[36:39], v[208:211], v[164:167], v[36:39]
	v_mfma_f32_16x16x32_bf16 v[40:43], v[200:203], v[168:171], v[40:43]
	v_mfma_f32_16x16x32_bf16 v[44:47], v[208:211], v[168:171], v[44:47]
	v_mfma_f32_16x16x32_bf16 v[48:51], v[200:203], v[172:175], v[48:51]
	v_mfma_f32_16x16x32_bf16 v[52:55], v[208:211], v[172:175], v[52:55]
	v_mfma_f32_16x16x32_bf16 v[56:59], v[200:203], v[176:179], v[56:59]
	v_mfma_f32_16x16x32_bf16 v[60:63], v[208:211], v[176:179], v[60:63]
	ds_read_b128 v[164:167], v158 offset:24576
	ds_read_b128 v[168:171], v158 offset:26624
	ds_read_b128 v[172:175], v158 offset:28672
	ds_read_b128 v[176:179], v158 offset:30720
	s_waitcnt lgkmcnt(4)
	v_mfma_f32_16x16x32_bf16 v[64:67], v[200:203], v[136:139], v[64:67]
	v_mfma_f32_16x16x32_bf16 v[68:71], v[208:211], v[136:139], v[68:71]
	v_mfma_f32_16x16x32_bf16 v[72:75], v[200:203], v[140:143], v[72:75]
	v_mfma_f32_16x16x32_bf16 v[76:79], v[208:211], v[140:143], v[76:79]
	v_mfma_f32_16x16x32_bf16 v[80:83], v[200:203], v[144:147], v[80:83]
	v_mfma_f32_16x16x32_bf16 v[84:87], v[208:211], v[144:147], v[84:87]
	v_mfma_f32_16x16x32_bf16 v[88:91], v[200:203], v[148:151], v[88:91]
	v_mfma_f32_16x16x32_bf16 v[92:95], v[208:211], v[148:151], v[92:95]
	ds_read_b128 v[136:139], v159 offset:0
	ds_read_b128 v[140:143], v159 offset:2048
	ds_read_b128 v[144:147], v159 offset:4096
	ds_read_b128 v[148:151], v159 offset:6144
	s_waitcnt lgkmcnt(4)
	v_mfma_f32_16x16x32_bf16 v[96:99], v[200:203], v[164:167], v[96:99]
	v_mfma_f32_16x16x32_bf16 v[100:103], v[208:211], v[164:167], v[100:103]
	v_mfma_f32_16x16x32_bf16 v[104:107], v[200:203], v[168:171], v[104:107]
	v_mfma_f32_16x16x32_bf16 v[108:111], v[208:211], v[168:171], v[108:111]
	v_mfma_f32_16x16x32_bf16 v[112:115], v[200:203], v[172:175], v[112:115]
	v_mfma_f32_16x16x32_bf16 v[116:119], v[208:211], v[172:175], v[116:119]
	v_mfma_f32_16x16x32_bf16 v[120:123], v[200:203], v[176:179], v[120:123]
	v_mfma_f32_16x16x32_bf16 v[124:127], v[208:211], v[176:179], v[124:127]
	ds_read_b128 v[164:167], v159 offset:8192
	ds_read_b128 v[168:171], v159 offset:10240
	ds_read_b128 v[172:175], v159 offset:12288
	ds_read_b128 v[176:179], v159 offset:14336
	s_waitcnt lgkmcnt(4)
	v_mfma_f32_16x16x32_bf16 v[0:3], v[204:207], v[136:139], v[0:3]
	v_mfma_f32_16x16x32_bf16 v[4:7], v[240:243], v[136:139], v[4:7]
	v_mfma_f32_16x16x32_bf16 v[8:11], v[204:207], v[140:143], v[8:11]
	v_mfma_f32_16x16x32_bf16 v[12:15], v[240:243], v[140:143], v[12:15]
	v_mfma_f32_16x16x32_bf16 v[16:19], v[204:207], v[144:147], v[16:19]
	v_mfma_f32_16x16x32_bf16 v[20:23], v[240:243], v[144:147], v[20:23]
	v_mfma_f32_16x16x32_bf16 v[24:27], v[204:207], v[148:151], v[24:27]
	v_mfma_f32_16x16x32_bf16 v[28:31], v[240:243], v[148:151], v[28:31]
	ds_read_b128 v[136:139], v159 offset:16384
	ds_read_b128 v[140:143], v159 offset:18432
	ds_read_b128 v[144:147], v159 offset:20480
	ds_read_b128 v[148:151], v159 offset:22528
	s_waitcnt lgkmcnt(4)
	v_mfma_f32_16x16x32_bf16 v[32:35], v[204:207], v[164:167], v[32:35]
	v_mfma_f32_16x16x32_bf16 v[36:39], v[240:243], v[164:167], v[36:39]
	v_mfma_f32_16x16x32_bf16 v[40:43], v[204:207], v[168:171], v[40:43]
	v_mfma_f32_16x16x32_bf16 v[44:47], v[240:243], v[168:171], v[44:47]
	v_mfma_f32_16x16x32_bf16 v[48:51], v[204:207], v[172:175], v[48:51]
	v_mfma_f32_16x16x32_bf16 v[52:55], v[240:243], v[172:175], v[52:55]
	v_mfma_f32_16x16x32_bf16 v[56:59], v[204:207], v[176:179], v[56:59]
	v_mfma_f32_16x16x32_bf16 v[60:63], v[240:243], v[176:179], v[60:63]
	ds_read_b128 v[164:167], v159 offset:24576
	ds_read_b128 v[168:171], v159 offset:26624
	ds_read_b128 v[172:175], v159 offset:28672
	ds_read_b128 v[176:179], v159 offset:30720
	s_waitcnt lgkmcnt(4)
	v_mfma_f32_16x16x32_bf16 v[64:67], v[204:207], v[136:139], v[64:67]
	v_mfma_f32_16x16x32_bf16 v[68:71], v[240:243], v[136:139], v[68:71]
	v_mfma_f32_16x16x32_bf16 v[72:75], v[204:207], v[140:143], v[72:75]
	v_mfma_f32_16x16x32_bf16 v[76:79], v[240:243], v[140:143], v[76:79]
	v_mfma_f32_16x16x32_bf16 v[80:83], v[204:207], v[144:147], v[80:83]
	v_mfma_f32_16x16x32_bf16 v[84:87], v[240:243], v[144:147], v[84:87]
	v_mfma_f32_16x16x32_bf16 v[88:91], v[204:207], v[148:151], v[88:91]
	v_mfma_f32_16x16x32_bf16 v[92:95], v[240:243], v[148:151], v[92:95]
	s_waitcnt lgkmcnt(0)
	v_mfma_f32_16x16x32_bf16 v[96:99], v[204:207], v[164:167], v[96:99]
	v_mfma_f32_16x16x32_bf16 v[100:103], v[240:243], v[164:167], v[100:103]
	v_mfma_f32_16x16x32_bf16 v[104:107], v[204:207], v[168:171], v[104:107]
	v_mfma_f32_16x16x32_bf16 v[108:111], v[240:243], v[168:171], v[108:111]
	v_mfma_f32_16x16x32_bf16 v[112:115], v[204:207], v[172:175], v[112:115]
	v_mfma_f32_16x16x32_bf16 v[116:119], v[240:243], v[172:175], v[116:119]
	v_mfma_f32_16x16x32_bf16 v[120:123], v[204:207], v[176:179], v[120:123]
	v_mfma_f32_16x16x32_bf16 v[124:127], v[240:243], v[176:179], v[124:127]
	s_add_i32 s63, s63, 2
	s_cmp_lt_u32 s63, 64
	s_cbranch_scc1 .Lg2_ff2_loop16
	s_branch .Lg2_ff2_episel
.Lg2_ff2_episel:
.Lg2_ff2_epiP:
	s_nop 7
	s_nop 7
	s_barrier
	v_cvt_pk_bf16_f32 v0, v0, v1
	v_cvt_pk_bf16_f32 v1, v2, v3
	ds_write_b64 v212, v[0:1] offset:0
	v_cvt_pk_bf16_f32 v4, v4, v5
	v_cvt_pk_bf16_f32 v5, v6, v7
	ds_write_b64 v213, v[4:5] offset:0
	v_cvt_pk_bf16_f32 v8, v8, v9
	v_cvt_pk_bf16_f32 v9, v10, v11
	ds_write_b64 v212, v[8:9] offset:4096
	v_cvt_pk_bf16_f32 v12, v12, v13
	v_cvt_pk_bf16_f32 v13, v14, v15
	ds_write_b64 v213, v[12:13] offset:4096
	v_cvt_pk_bf16_f32 v16, v16, v17
	v_cvt_pk_bf16_f32 v17, v18, v19
	ds_write_b64 v212, v[16:17] offset:8192
	v_cvt_pk_bf16_f32 v20, v20, v21
	v_cvt_pk_bf16_f32 v21, v22, v23
	ds_write_b64 v213, v[20:21] offset:8192
	v_cvt_pk_bf16_f32 v24, v24, v25
	v_cvt_pk_bf16_f32 v25, v26, v27
	ds_write_b64 v212, v[24:25] offset:12288
	v_cvt_pk_bf16_f32 v28, v28, v29
	v_cvt_pk_bf16_f32 v29, v30, v31
	ds_write_b64 v213, v[28:29] offset:12288
	v_cvt_pk_bf16_f32 v32, v32, v33
	v_cvt_pk_bf16_f32 v33, v34, v35
	ds_write_b64 v212, v[32:33] offset:16384
	v_cvt_pk_bf16_f32 v36, v36, v37
	v_cvt_pk_bf16_f32 v37, v38, v39
	ds_write_b64 v213, v[36:37] offset:16384
	v_cvt_pk_bf16_f32 v40, v40, v41
	v_cvt_pk_bf16_f32 v41, v42, v43
	ds_write_b64 v212, v[40:41] offset:20480
	v_cvt_pk_bf16_f32 v44, v44, v45
	v_cvt_pk_bf16_f32 v45, v46, v47
	ds_write_b64 v213, v[44:45] offset:20480
	v_cvt_pk_bf16_f32 v48, v48, v49
	v_cvt_pk_bf16_f32 v49, v50, v51
	ds_write_b64 v212, v[48:49] offset:24576
	v_cvt_pk_bf16_f32 v52, v52, v53
	v_cvt_pk_bf16_f32 v53, v54, v55
	ds_write_b64 v213, v[52:53] offset:24576
	v_cvt_pk_bf16_f32 v56, v56, v57
	v_cvt_pk_bf16_f32 v57, v58, v59
	ds_write_b64 v212, v[56:57] offset:28672
	v_cvt_pk_bf16_f32 v60, v60, v61
	v_cvt_pk_bf16_f32 v61, v62, v63
	ds_write_b64 v213, v[60:61] offset:28672
	v_cvt_pk_bf16_f32 v64, v64, v65
	v_cvt_pk_bf16_f32 v65, v66, v67
	ds_write_b64 v253, v[64:65] offset:0
	v_cvt_pk_bf16_f32 v68, v68, v69
	v_cvt_pk_bf16_f32 v69, v70, v71
	ds_write_b64 v254, v[68:69] offset:0
	v_cvt_pk_bf16_f32 v72, v72, v73
	v_cvt_pk_bf16_f32 v73, v74, v75
	ds_write_b64 v253, v[72:73] offset:4096
	v_cvt_pk_bf16_f32 v76, v76, v77
	v_cvt_pk_bf16_f32 v77, v78, v79
	ds_write_b64 v254, v[76:77] offset:4096
	v_cvt_pk_bf16_f32 v80, v80, v81
	v_cvt_pk_bf16_f32 v81, v82, v83
	ds_write_b64 v253, v[80:81] offset:8192
	v_cvt_pk_bf16_f32 v84, v84, v85
	v_cvt_pk_bf16_f32 v85, v86, v87
	ds_write_b64 v254, v[84:85] offset:8192
	v_cvt_pk_bf16_f32 v88, v88, v89
	v_cvt_pk_bf16_f32 v89, v90, v91
	ds_write_b64 v253, v[88:89] offset:12288
	v_cvt_pk_bf16_f32 v92, v92, v93
	v_cvt_pk_bf16_f32 v93, v94, v95
	ds_write_b64 v254, v[92:93] offset:12288
	v_cvt_pk_bf16_f32 v96, v96, v97
	v_cvt_pk_bf16_f32 v97, v98, v99
	ds_write_b64 v253, v[96:97] offset:16384
	v_cvt_pk_bf16_f32 v100, v100, v101
	v_cvt_pk_bf16_f32 v101, v102, v103
	ds_write_b64 v254, v[100:101] offset:16384
	v_cvt_pk_bf16_f32 v104, v104, v105
	v_cvt_pk_bf16_f32 v105, v106, v107
	ds_write_b64 v253, v[104:105] offset:20480
	v_cvt_pk_bf16_f32 v108, v108, v109
	v_cvt_pk_bf16_f32 v109, v110, v111
	ds_write_b64 v254, v[108:109] offset:20480
	v_cvt_pk_bf16_f32 v112, v112, v113
	v_cvt_pk_bf16_f32 v113, v114, v115
	ds_write_b64 v253, v[112:113] offset:24576
	v_cvt_pk_bf16_f32 v116, v116, v117
	v_cvt_pk_bf16_f32 v117, v118, v119
	ds_write_b64 v254, v[116:117] offset:24576
	v_cvt_pk_bf16_f32 v120, v120, v121
	v_cvt_pk_bf16_f32 v121, v122, v123
	ds_write_b64 v253, v[120:121] offset:28672
	v_cvt_pk_bf16_f32 v124, v124, v125
	v_cvt_pk_bf16_f32 v125, v126, v127
	ds_write_b64 v254, v[124:125] offset:28672
	s_cmp_eq_u32 s65, 0
	s_cbranch_scc1 .Lg2_ff2_st_lastP
	v_cvt_pk_bf16_f32 v128, v128, v129
	v_cvt_pk_bf16_f32 v129, v130, v131
	ds_write_b64 v253, v[128:129] offset:32768
	v_cvt_pk_bf16_f32 v132, v132, v133
	v_cvt_pk_bf16_f32 v133, v134, v135
	ds_write_b64 v254, v[132:133] offset:32768
.Lg2_ff2_st_lastP:
	s_waitcnt vmcnt(0) lgkmcnt(0)
	s_barrier
	ds_read_b128 v[0:3], v247 offset:0
	ds_read_b128 v[4:7], v247 offset:4096
	ds_read_b128 v[8:11], v247 offset:8192
	ds_read_b128 v[12:15], v247 offset:12288
	ds_read_b128 v[16:19], v247 offset:16384
	ds_read_b128 v[20:23], v247 offset:20480
	ds_read_b128 v[24:27], v247 offset:24576
	ds_read_b128 v[28:31], v247 offset:28672
	ds_read_b128 v[32:35], v255 offset:0
	ds_read_b128 v[36:39], v255 offset:4096
	ds_read_b128 v[40:43], v255 offset:8192
	ds_read_b128 v[44:47], v255 offset:12288
	ds_read_b128 v[48:51], v255 offset:16384
	ds_read_b128 v[52:55], v255 offset:20480
	ds_read_b128 v[56:59], v255 offset:24576
	ds_read_b128 v[60:63], v255 offset:28672
	s_cmp_eq_u32 s65, 0
	s_cbranch_scc1 .Lg2_ff2_rd_lastaP
	ds_read_b128 v[64:67], v255 offset:32768

.Lg2_ff2_rd_lastP:
	s_waitcnt lgkmcnt(0)
	s_barrier
	s_branch .Lg2_ff2_next
.Lg2_ff2_next:
	s_add_i32 s64, s64, 1
	s_cmp_lt_u32 s64, 1
	s_cbranch_scc1 .Lg2_ff2_tile
.Lg2_ff2_exit:
	v_mov_b32_e32 v2, 0x10200
	v_mov_b32_e32 v4, s66
	v_mov_b32_e32 v5, s67
	ds_write_b64 v2, v[4:5]
	v_mov_b32_e32 v1, 0
	s_waitcnt vmcnt(0) lgkmcnt(0)

.Lg2_ff1_entry:
	s_waitcnt vmcnt(0) lgkmcnt(0)
	s_barrier
	v_mov_b32_e32 v2, 0x10200
	ds_read_b64 v[2:3], v2
	v_readlane_b32 s0, v246, 0
	v_lshrrev_b32_e32 v4, 6, v163
	v_and_b32_e32 v5, 63, v163
	s_and_b32 s1, s0, 7
	s_lshr_b32 s0, s0, 3
	s_lshr_b32 s68, s0, 3
	s_and_b32 s0, s0, 7
	s_lshl_b32 s0, s0, 3
	s_add_i32 s0, s0, s1
	s_cmp_lt_u32 s0, 32
	s_cselect_b32 s43, 1, 0
	s_min_u32 s1, s0, 32
	s_lshl_b32 s0, s0, 4
	s_add_i32 s0, s0, s1
	s_lshl_b32 s42, s0, 4
	v_readfirstlane_b32 s70, v4
	v_and_b32_e32 v6, 15, v5
	v_lshrrev_b32_e32 v7, 4, v5
	s_waitcnt lgkmcnt(0)
	v_readfirstlane_b32 s66, v2
	v_readfirstlane_b32 s67, v3
	s_lshl_b32 s62, s70, 10
	v_and_b32_e32 v8, 7, v6
	v_xor_b32_e32 v9, v7, v8
	v_lshlrev_b32_e32 v9, 4, v9
	v_lshl_add_u32 v156, v6, 7, v9
	v_add_u32_e32 v10, 4, v7
	v_xor_b32_e32 v10, v10, v8
	v_lshlrev_b32_e32 v10, 4, v10
	v_lshl_add_u32 v157, v6, 7, v10
	v_add_u32_e32 v158, 0x8800, v156
	v_add_u32_e32 v159, 0x8800, v157
	v_lshrrev_b32_e32 v11, 3, v163
	v_and_b32_e32 v12, 7, v163
	v_and_b32_e32 v13, 7, v11
	v_xor_b32_e32 v12, v12, v13
	v_lshlrev_b32_e32 v12, 4, v12
	s_mov_b32 s2, 0x800
	v_mul_lo_u32 v11, v11, s2
	v_add_u32_e32 v162, v11, v12
	v_lshrrev_b32_e32 v11, 4, v163
	v_and_b32_e32 v12, 15, v163
	v_xor_b32_e32 v13, v12, v11
	v_lshlrev_b32_e32 v13, 4, v13
	v_lshl_add_u32 v247, v11, 8, v13
	s_mov_b32 s2, 0x2000
	v_mul_lo_u32 v11, v11, s2
	v_lshl_add_u32 v252, v12, 4, v11
	v_add_u32_e32 v255, 0x8000, v247
	v_lshlrev_b32_e32 v11, 1, v4
	s_mov_b32 s2, 0x8000
	v_mul_lo_u32 v12, v11, s2
	v_lshl_add_u32 v160, v5, 4, v12
	v_add_u32_e32 v161, 0x8000, v160
	v_lshrrev_b32_e32 v12, 1, v7
	v_lshl_add_u32 v12, v11, 1, v12
	v_and_b32_e32 v13, 1, v7
	v_lshlrev_b32_e32 v13, 3, v13
	v_lshl_add_u32 v14, v6, 8, v13
	v_xor_b32_e32 v15, v12, v6
	v_lshlrev_b32_e32 v15, 4, v15
	v_add_u32_e32 v212, v14, v15
	v_add_u32_e32 v12, 2, v12
	v_xor_b32_e32 v15, v12, v6
	v_lshlrev_b32_e32 v15, 4, v15
	v_add_u32_e32 v213, v14, v15
	v_add_u32_e32 v253, 0x8000, v212
	v_add_u32_e32 v254, 0x8000, v213
	s_mov_b32 s64, 0
.Lg2_ff1_tile:
	s_lshl_b32 s0, s64, 3
	s_add_i32 s38, s0, s68
	s_mov_b32 s69, s42
	s_mov_b32 s65, s43
	s_lshl_b32 s0, s38, 7
	s_mul_i32 s2, s69, 0x800
	s_mul_hi_u32 s3, s69, 0x800
	s_add_u32 s56, s26, s2
	s_addc_u32 s57, s27, s3
	s_add_u32 s56, s56, 0x13240000
	s_addc_u32 s57, s57, 0
	s_mul_i32 s2, s0, 0x800
	s_mul_hi_u32 s3, s0, 0x800
	s_add_u32 s58, s26, s2
	s_addc_u32 s59, s27, s3
	s_add_u32 s58, s58, 0xff40000
	s_addc_u32 s59, s59, 0
	s_mul_i32 s2, s69, 0x2000
	s_mul_hi_u32 s3, s69, 0x2000
	s_lshl_b32 s0, s0, 1
	s_add_u32 s2, s2, s0
	s_addc_u32 s3, s3, 0
	s_add_u32 s60, s26, s2
	s_addc_u32 s61, s27, s3
	s_add_u32 s60, s60, 0x0
	s_addc_u32 s61, s61, 0
	s_cmp_eq_u32 s65, 0
	s_cbranch_scc1 .Lg2_ff1_k16
	v_mov_b32_e32 v0, 0
	v_mov_b32_e32 v1, 0
	v_mov_b32_e32 v2, 0
	v_mov_b32_e32 v3, 0
	v_mov_b32_e32 v4, 0
	v_mov_b32_e32 v5, 0
	v_mov_b32_e32 v6, 0
	v_mov_b32_e32 v7, 0
	v_mov_b32_e32 v8, 0
	v_mov_b32_e32 v9, 0
	v_mov_b32_e32 v10, 0
	v_mov_b32_e32 v11, 0
	v_mov_b32_e32 v12, 0
	v_mov_b32_e32 v13, 0
	v_mov_b32_e32 v14, 0
	v_mov_b32_e32 v15, 0
	v_mov_b32_e32 v16, 0
	v_mov_b32_e32 v17, 0
	v_mov_b32_e32 v18, 0
	v_mov_b32_e32 v19, 0
	v_mov_b32_e32 v20, 0
	v_mov_b32_e32 v21, 0
	v_mov_b32_e32 v22, 0
	v_mov_b32_e32 v23, 0
	v_mov_b32_e32 v24, 0
	v_mov_b32_e32 v25, 0
	v_mov_b32_e32 v26, 0
	v_mov_b32_e32 v27, 0
	v_mov_b32_e32 v28, 0
	v_mov_b32_e32 v29, 0
	v_mov_b32_e32 v30, 0
	v_mov_b32_e32 v31, 0
	v_mov_b32_e32 v32, 0
	v_mov_b32_e32 v33, 0
	v_mov_b32_e32 v34, 0
	v_mov_b32_e32 v35, 0
	v_mov_b32_e32 v36, 0
	v_mov_b32_e32 v37, 0
	v_mov_b32_e32 v38, 0
	v_mov_b32_e32 v39, 0
	v_mov_b32_e32 v40, 0
	v_mov_b32_e32 v41, 0
	v_mov_b32_e32 v42, 0
	v_mov_b32_e32 v43, 0
	v_mov_b32_e32 v44, 0
	v_mov_b32_e32 v45, 0
	v_mov_b32_e32 v46, 0
	v_mov_b32_e32 v47, 0
	v_mov_b32_e32 v48, 0
	v_mov_b32_e32 v49, 0
	v_mov_b32_e32 v50, 0
	v_mov_b32_e32 v51, 0
	v_mov_b32_e32 v52, 0
	v_mov_b32_e32 v53, 0
	v_mov_b32_e32 v54, 0
	v_mov_b32_e32 v55, 0
	v_mov_b32_e32 v56, 0
	v_mov_b32_e32 v57, 0
	v_mov_b32_e32 v58, 0
	v_mov_b32_e32 v59, 0
	v_mov_b32_e32 v60, 0
	v_mov_b32_e32 v61, 0
	v_mov_b32_e32 v62, 0
	v_mov_b32_e32 v63, 0
	v_mov_b32_e32 v64, 0
	v_mov_b32_e32 v65, 0
	v_mov_b32_e32 v66, 0
	v_mov_b32_e32 v67, 0
	v_mov_b32_e32 v68, 0
	v_mov_b32_e32 v69, 0
	v_mov_b32_e32 v70, 0
	v_mov_b32_e32 v71, 0
	v_mov_b32_e32 v72, 0
	v_mov_b32_e32 v73, 0
	v_mov_b32_e32 v74, 0
	v_mov_b32_e32 v75, 0
	v_mov_b32_e32 v76, 0
	v_mov_b32_e32 v77, 0
	v_mov_b32_e32 v78, 0
	v_mov_b32_e32 v79, 0
	v_mov_b32_e32 v80, 0
	v_mov_b32_e32 v81, 0
	v_mov_b32_e32 v82, 0
	v_mov_b32_e32 v83, 0
	v_mov_b32_e32 v84, 0
	v_mov_b32_e32 v85, 0
	v_mov_b32_e32 v86, 0
	v_mov_b32_e32 v87, 0
	v_mov_b32_e32 v88, 0
	v_mov_b32_e32 v89, 0
	v_mov_b32_e32 v90, 0
	v_mov_b32_e32 v91, 0
	v_mov_b32_e32 v92, 0
	v_mov_b32_e32 v93, 0
	v_mov_b32_e32 v94, 0
	v_mov_b32_e32 v95, 0
	v_mov_b32_e32 v96, 0
	v_mov_b32_e32 v97, 0
	v_mov_b32_e32 v98, 0
	v_mov_b32_e32 v99, 0
	v_mov_b32_e32 v100, 0
	v_mov_b32_e32 v101, 0
	v_mov_b32_e32 v102, 0
	v_mov_b32_e32 v103, 0
	v_mov_b32_e32 v104, 0
	v_mov_b32_e32 v105, 0
	v_mov_b32_e32 v106, 0
	v_mov_b32_e32 v107, 0
	v_mov_b32_e32 v108, 0
	v_mov_b32_e32 v109, 0
	v_mov_b32_e32 v110, 0
	v_mov_b32_e32 v111, 0
	v_mov_b32_e32 v112, 0
	v_mov_b32_e32 v113, 0
	v_mov_b32_e32 v114, 0
	v_mov_b32_e32 v115, 0
	v_mov_b32_e32 v116, 0
	v_mov_b32_e32 v117, 0
	v_mov_b32_e32 v118, 0
	v_mov_b32_e32 v119, 0
	v_mov_b32_e32 v120, 0
	v_mov_b32_e32 v121, 0
	v_mov_b32_e32 v122, 0
	v_mov_b32_e32 v123, 0
	v_mov_b32_e32 v124, 0
	v_mov_b32_e32 v125, 0
	v_mov_b32_e32 v126, 0
	v_mov_b32_e32 v127, 0
	v_mov_b32_e32 v128, 0
	v_mov_b32_e32 v129, 0
	v_mov_b32_e32 v130, 0
	v_mov_b32_e32 v131, 0
	v_mov_b32_e32 v132, 0
	v_mov_b32_e32 v133, 0
	v_mov_b32_e32 v134, 0
	v_mov_b32_e32 v135, 0
	s_add_u32 s4, s56, 0x0
	s_addc_u32 s5, s57, 0
	s_add_u32 m0, s62, 0x0
	s_nop 0
	global_load_lds_dwordx4 v162, s[4:5]
	s_add_u32 s4, s56, 0x10000
	s_addc_u32 s5, s57, 0
	s_add_u32 m0, s62, 0x1000
	s_nop 0
	global_load_lds_dwordx4 v162, s[4:5]
	s_add_u32 s4, s56, 0x20000
	s_addc_u32 s5, s57, 0
	s_add_u32 m0, s62, 0x2000
	s_nop 0
	global_load_lds_dwordx4 v162, s[4:5]
	s_add_u32 s4, s56, 0x30000
	s_addc_u32 s5, s57, 0
	s_add_u32 m0, s62, 0x3000
	s_nop 0
	global_load_lds_dwordx4 v162, s[4:5]
	s_add_u32 s4, s56, 0x40000
	s_addc_u32 s5, s57, 0
	s_add_u32 m0, s62, 0x4000
	s_nop 0
	global_load_lds_dwordx4 v162, s[4:5]
	s_add_u32 s4, s56, 0x50000
	s_addc_u32 s5, s57, 0
	s_add_u32 m0, s62, 0x5000
	s_nop 0
	global_load_lds_dwordx4 v162, s[4:5]
	s_add_u32 s4, s56, 0x60000
	s_addc_u32 s5, s57, 0
	s_add_u32 m0, s62, 0x6000
	s_nop 0
	global_load_lds_dwordx4 v162, s[4:5]
	s_add_u32 s4, s56, 0x70000
	s_addc_u32 s5, s57, 0
	s_add_u32 m0, s62, 0x7000
	s_nop 0
	global_load_lds_dwordx4 v162, s[4:5]
	s_cmp_gt_u32 s70, 1
	s_cbranch_scc1 .Lg2_ff1_nodma_0
	s_add_u32 s4, s56, 0x80000
	s_addc_u32 s5, s57, 0
	s_add_u32 m0, s62, 0x8000
	s_nop 0
	global_load_lds_dwordx4 v162, s[4:5]

.Lg2_ff1_loop17:
	s_waitcnt vmcnt(0)
	s_barrier
	s_add_u32 s56, s56, 0x80
	s_addc_u32 s57, s57, 0
	s_add_u32 s58, s58, 0x800
	s_addc_u32 s59, s59, 0
	s_add_u32 s4, s56, 0x0
	s_addc_u32 s5, s57, 0
	s_add_u32 m0, s62, 0x8800
	s_nop 0
	global_load_lds_dwordx4 v162, s[4:5]
	s_add_u32 s4, s56, 0x10000
	s_addc_u32 s5, s57, 0
	s_add_u32 m0, s62, 0x9800
	s_nop 0
	global_load_lds_dwordx4 v162, s[4:5]
	s_add_u32 s4, s56, 0x20000
	s_addc_u32 s5, s57, 0
	s_add_u32 m0, s62, 0xa800
	s_nop 0
	global_load_lds_dwordx4 v162, s[4:5]
	s_add_u32 s4, s56, 0x30000
	s_addc_u32 s5, s57, 0
	s_add_u32 m0, s62, 0xb800
	s_nop 0
	global_load_lds_dwordx4 v162, s[4:5]
	s_add_u32 s4, s56, 0x40000
	s_addc_u32 s5, s57, 0
	s_add_u32 m0, s62, 0xc800
	s_nop 0
	global_load_lds_dwordx4 v162, s[4:5]
	s_add_u32 s4, s56, 0x50000
	s_addc_u32 s5, s57, 0
	s_add_u32 m0, s62, 0xd800
	s_nop 0
	global_load_lds_dwordx4 v162, s[4:5]
	s_add_u32 s4, s56, 0x60000
	s_addc_u32 s5, s57, 0
	s_add_u32 m0, s62, 0xe800
	s_nop 0
	global_load_lds_dwordx4 v162, s[4:5]
	s_add_u32 s4, s56, 0x70000
	s_addc_u32 s5, s57, 0
	s_add_u32 m0, s62, 0xf800
	s_nop 0
	global_load_lds_dwordx4 v162, s[4:5]
	s_cmp_gt_u32 s70, 1
	s_cbranch_scc1 .Lg2_ff1_nodma_1
	s_add_u32 s4, s56, 0x80000
	s_addc_u32 s5, s57, 0
	s_add_u32 m0, s62, 0x10800
	s_nop 0
	global_load_lds_dwordx4 v162, s[4:5]
.Lg2_ff1_nodma_1:
	global_load_dwordx4 v[200:203], v160, s[58:59] offset:0
	global_load_dwordx4 v[204:207], v160, s[58:59] offset:1024
	global_load_dwordx4 v[208:211], v161, s[58:59] offset:0
	global_load_dwordx4 v[240:243], v161, s[58:59] offset:1024
	ds_read_b128 v[136:139], v156 offset:0
	ds_read_b128 v[140:143], v156 offset:2048
	ds_read_b128 v[144:147], v156 offset:4096
	ds_read_b128 v[148:151], v156 offset:6144
	ds_read_b128 v[164:167], v156 offset:8192
	ds_read_b128 v[168:171], v156 offset:10240
	ds_read_b128 v[172:175], v156 offset:12288
	ds_read_b128 v[176:179], v156 offset:14336
	s_waitcnt lgkmcnt(4)
	v_mfma_f32_16x16x32_bf16 v[0:3], v[184:187], v[136:139], v[0:3]
	v_mfma_f32_16x16x32_bf16 v[4:7], v[192:195], v[136:139], v[4:7]
	v_mfma_f32_16x16x32_bf16 v[8:11], v[184:187], v[140:143], v[8:11]
	v_mfma_f32_16x16x32_bf16 v[12:15], v[192:195], v[140:143], v[12:15]
	v_mfma_f32_16x16x32_bf16 v[16:19], v[184:187], v[144:147], v[16:19]
	v_mfma_f32_16x16x32_bf16 v[20:23], v[192:195], v[144:147], v[20:23]
	v_mfma_f32_16x16x32_bf16 v[24:27], v[184:187], v[148:151], v[24:27]
	v_mfma_f32_16x16x32_bf16 v[28:31], v[192:195], v[148:151], v[28:31]
	ds_read_b128 v[136:139], v156 offset:16384
	ds_read_b128 v[140:143], v156 offset:18432
	ds_read_b128 v[144:147], v156 offset:20480
	ds_read_b128 v[148:151], v156 offset:22528
	s_waitcnt lgkmcnt(4)
	v_mfma_f32_16x16x32_bf16 v[32:35], v[184:187], v[164:167], v[32:35]
	v_mfma_f32_16x16x32_bf16 v[36:39], v[192:195], v[164:167], v[36:39]
	v_mfma_f32_16x16x32_bf16 v[40:43], v[184:187], v[168:171], v[40:43]
	v_mfma_f32_16x16x32_bf16 v[44:47], v[192:195], v[168:171], v[44:47]
	v_mfma_f32_16x16x32_bf16 v[48:51], v[184:187], v[172:175], v[48:51]
	v_mfma_f32_16x16x32_bf16 v[52:55], v[192:195], v[172:175], v[52:55]
	v_mfma_f32_16x16x32_bf16 v[56:59], v[184:187], v[176:179], v[56:59]
	v_mfma_f32_16x16x32_bf16 v[60:63], v[192:195], v[176:179], v[60:63]
	ds_read_b128 v[164:167], v156 offset:24576
	ds_read_b128 v[168:171], v156 offset:26624
	ds_read_b128 v[172:175], v156 offset:28672
	ds_read_b128 v[176:179], v156 offset:30720
	ds_read_b128 v[180:183], v156 offset:32768
	s_waitcnt lgkmcnt(5)
	v_mfma_f32_16x16x32_bf16 v[64:67], v[184:187], v[136:139], v[64:67]
	v_mfma_f32_16x16x32_bf16 v[68:71], v[192:195], v[136:139], v[68:71]
	v_mfma_f32_16x16x32_bf16 v[72:75], v[184:187], v[140:143], v[72:75]
	v_mfma_f32_16x16x32_bf16 v[76:79], v[192:195], v[140:143], v[76:79]
	v_mfma_f32_16x16x32_bf16 v[80:83], v[184:187], v[144:147], v[80:83]
	v_mfma_f32_16x16x32_bf16 v[84:87], v[192:195], v[144:147], v[84:87]
	v_mfma_f32_16x16x32_bf16 v[88:91], v[184:187], v[148:151], v[88:91]
	v_mfma_f32_16x16x32_bf16 v[92:95], v[192:195], v[148:151], v[92:95]
	ds_read_b128 v[136:139], v157 offset:0
	ds_read_b128 v[140:143], v157 offset:2048
	ds_read_b128 v[144:147], v157 offset:4096
	ds_read_b128 v[148:151], v157 offset:6144
	s_waitcnt lgkmcnt(4)
	v_mfma_f32_16x16x32_bf16 v[96:99], v[184:187], v[164:167], v[96:99]
	v_mfma_f32_16x16x32_bf16 v[100:103], v[192:195], v[164:167], v[100:103]
	v_mfma_f32_16x16x32_bf16 v[104:107], v[184:187], v[168:171], v[104:107]
	v_mfma_f32_16x16x32_bf16 v[108:111], v[192:195], v[168:171], v[108:111]
	v_mfma_f32_16x16x32_bf16 v[112:115], v[184:187], v[172:175], v[112:115]
	v_mfma_f32_16x16x32_bf16 v[116:119], v[192:195], v[172:175], v[116:119]
	v_mfma_f32_16x16x32_bf16 v[120:123], v[184:187], v[176:179], v[120:123]
	v_mfma_f32_16x16x32_bf16 v[124:127], v[192:195], v[176:179], v[124:127]
	v_mfma_f32_16x16x32_bf16 v[128:131], v[184:187], v[180:183], v[128:131]
	v_mfma_f32_16x16x32_bf16 v[132:135], v[192:195], v[180:183], v[132:135]
	ds_read_b128 v[164:167], v157 offset:8192
	ds_read_b128 v[168:171], v157 offset:10240
	ds_read_b128 v[172:175], v157 offset:12288
	ds_read_b128 v[176:179], v157 offset:14336
	s_waitcnt lgkmcnt(4)
	v_mfma_f32_16x16x32_bf16 v[0:3], v[188:191], v[136:139], v[0:3]
	v_mfma_f32_16x16x32_bf16 v[4:7], v[196:199], v[136:139], v[4:7]
	v_mfma_f32_16x16x32_bf16 v[8:11], v[188:191], v[140:143], v[8:11]
	v_mfma_f32_16x16x32_bf16 v[12:15], v[196:199], v[140:143], v[12:15]
	v_mfma_f32_16x16x32_bf16 v[16:19], v[188:191], v[144:147], v[16:19]
	v_mfma_f32_16x16x32_bf16 v[20:23], v[196:199], v[144:147], v[20:23]
	v_mfma_f32_16x16x32_bf16 v[24:27], v[188:191], v[148:151], v[24:27]
	v_mfma_f32_16x16x32_bf16 v[28:31], v[196:199], v[148:151], v[28:31]
	ds_read_b128 v[136:139], v157 offset:16384
	ds_read_b128 v[140:143], v157 offset:18432
	ds_read_b128 v[144:147], v157 offset:20480
	ds_read_b128 v[148:151], v157 offset:22528
	s_waitcnt lgkmcnt(4)
	v_mfma_f32_16x16x32_bf16 v[32:35], v[188:191], v[164:167], v[32:35]
	v_mfma_f32_16x16x32_bf16 v[36:39], v[196:199], v[164:167], v[36:39]
	v_mfma_f32_16x16x32_bf16 v[40:43], v[188:191], v[168:171], v[40:43]
	v_mfma_f32_16x16x32_bf16 v[44:47], v[196:199], v[168:171], v[44:47]
	v_mfma_f32_16x16x32_bf16 v[48:51], v[188:191], v[172:175], v[48:51]
	v_mfma_f32_16x16x32_bf16 v[52:55], v[196:199], v[172:175], v[52:55]
	v_mfma_f32_16x16x32_bf16 v[56:59], v[188:191], v[176:179], v[56:59]
	v_mfma_f32_16x16x32_bf16 v[60:63], v[196:199], v[176:179], v[60:63]
	ds_read_b128 v[164:167], v157 offset:24576
	ds_read_b128 v[168:171], v157 offset:26624
	ds_read_b128 v[172:175], v157 offset:28672
	ds_read_b128 v[176:179], v157 offset:30720
	ds_read_b128 v[180:183], v157 offset:32768
	s_waitcnt lgkmcnt(5)
	v_mfma_f32_16x16x32_bf16 v[64:67], v[188:191], v[136:139], v[64:67]
	v_mfma_f32_16x16x32_bf16 v[68:71], v[196:199], v[136:139], v[68:71]
	v_mfma_f32_16x16x32_bf16 v[72:75], v[188:191], v[140:143], v[72:75]
	v_mfma_f32_16x16x32_bf16 v[76:79], v[196:199], v[140:143], v[76:79]
	v_mfma_f32_16x16x32_bf16 v[80:83], v[188:191], v[144:147], v[80:83]
	v_mfma_f32_16x16x32_bf16 v[84:87], v[196:199], v[144:147], v[84:87]
	v_mfma_f32_16x16x32_bf16 v[88:91], v[188:191], v[148:151], v[88:91]
	v_mfma_f32_16x16x32_bf16 v[92:95], v[196:199], v[148:151], v[92:95]
	s_waitcnt lgkmcnt(0)
	v_mfma_f32_16x16x32_bf16 v[96:99], v[188:191], v[164:167], v[96:99]
	v_mfma_f32_16x16x32_bf16 v[100:103], v[196:199], v[164:167], v[100:103]
	v_mfma_f32_16x16x32_bf16 v[104:107], v[188:191], v[168:171], v[104:107]
	v_mfma_f32_16x16x32_bf16 v[108:111], v[196:199], v[168:171], v[108:111]
	v_mfma_f32_16x16x32_bf16 v[112:115], v[188:191], v[172:175], v[112:115]
	v_mfma_f32_16x16x32_bf16 v[116:119], v[196:199], v[172:175], v[116:119]
	v_mfma_f32_16x16x32_bf16 v[120:123], v[188:191], v[176:179], v[120:123]
	v_mfma_f32_16x16x32_bf16 v[124:127], v[196:199], v[176:179], v[124:127]
	v_mfma_f32_16x16x32_bf16 v[128:131], v[188:191], v[180:183], v[128:131]
	v_mfma_f32_16x16x32_bf16 v[132:135], v[196:199], v[180:183], v[132:135]
	s_waitcnt vmcnt(0)
	s_barrier
	s_cmp_ge_u32 s63, 14
	s_cbranch_scc1 .Lg2_ff1_noissue17
	s_add_u32 s56, s56, 0x80
	s_addc_u32 s57, s57, 0
	s_add_u32 s58, s58, 0x800
	s_addc_u32 s59, s59, 0
	s_add_u32 s4, s56, 0x0
	s_addc_u32 s5, s57, 0
	s_add_u32 m0, s62, 0x0
	s_nop 0
	global_load_lds_dwordx4 v162, s[4:5]
	s_add_u32 s4, s56, 0x10000
	s_addc_u32 s5, s57, 0
	s_add_u32 m0, s62, 0x1000
	s_nop 0
	global_load_lds_dwordx4 v162, s[4:5]
	s_add_u32 s4, s56, 0x20000
	s_addc_u32 s5, s57, 0
	s_add_u32 m0, s62, 0x2000
	s_nop 0
	global_load_lds_dwordx4 v162, s[4:5]
	s_add_u32 s4, s56, 0x30000
	s_addc_u32 s5, s57, 0
	s_add_u32 m0, s62, 0x3000
	s_nop 0
	global_load_lds_dwordx4 v162, s[4:5]
	s_add_u32 s4, s56, 0x40000
	s_addc_u32 s5, s57, 0
	s_add_u32 m0, s62, 0x4000
	s_nop 0
	global_load_lds_dwordx4 v162, s[4:5]
	s_add_u32 s4, s56, 0x50000
	s_addc_u32 s5, s57, 0
	s_add_u32 m0, s62, 0x5000
	s_nop 0
	global_load_lds_dwordx4 v162, s[4:5]
	s_add_u32 s4, s56, 0x60000
	s_addc_u32 s5, s57, 0
	s_add_u32 m0, s62, 0x6000
	s_nop 0
	global_load_lds_dwordx4 v162, s[4:5]
	s_add_u32 s4, s56, 0x70000
	s_addc_u32 s5, s57, 0
	s_add_u32 m0, s62, 0x7000
	s_nop 0
	global_load_lds_dwordx4 v162, s[4:5]
	s_cmp_gt_u32 s70, 1
	s_cbranch_scc1 .Lg2_ff1_nodma_2
	s_add_u32 s4, s56, 0x80000
	s_addc_u32 s5, s57, 0
	s_add_u32 m0, s62, 0x8000
	s_nop 0
	global_load_lds_dwordx4 v162, s[4:5]

.Lg2_ff1_k16:
	v_mov_b32_e32 v0, 0
	v_mov_b32_e32 v1, 0
	v_mov_b32_e32 v2, 0
	v_mov_b32_e32 v3, 0
	v_mov_b32_e32 v4, 0
	v_mov_b32_e32 v5, 0
	v_mov_b32_e32 v6, 0
	v_mov_b32_e32 v7, 0
	v_mov_b32_e32 v8, 0
	v_mov_b32_e32 v9, 0
	v_mov_b32_e32 v10, 0
	v_mov_b32_e32 v11, 0
	v_mov_b32_e32 v12, 0
	v_mov_b32_e32 v13, 0
	v_mov_b32_e32 v14, 0
	v_mov_b32_e32 v15, 0
	v_mov_b32_e32 v16, 0
	v_mov_b32_e32 v17, 0
	v_mov_b32_e32 v18, 0
	v_mov_b32_e32 v19, 0
	v_mov_b32_e32 v20, 0
	v_mov_b32_e32 v21, 0
	v_mov_b32_e32 v22, 0
	v_mov_b32_e32 v23, 0
	v_mov_b32_e32 v24, 0
	v_mov_b32_e32 v25, 0
	v_mov_b32_e32 v26, 0
	v_mov_b32_e32 v27, 0
	v_mov_b32_e32 v28, 0
	v_mov_b32_e32 v29, 0
	v_mov_b32_e32 v30, 0
	v_mov_b32_e32 v31, 0
	v_mov_b32_e32 v32, 0
	v_mov_b32_e32 v33, 0
	v_mov_b32_e32 v34, 0
	v_mov_b32_e32 v35, 0
	v_mov_b32_e32 v36, 0
	v_mov_b32_e32 v37, 0
	v_mov_b32_e32 v38, 0
	v_mov_b32_e32 v39, 0
	v_mov_b32_e32 v40, 0
	v_mov_b32_e32 v41, 0
	v_mov_b32_e32 v42, 0
	v_mov_b32_e32 v43, 0
	v_mov_b32_e32 v44, 0
	v_mov_b32_e32 v45, 0
	v_mov_b32_e32 v46, 0
	v_mov_b32_e32 v47, 0
	v_mov_b32_e32 v48, 0
	v_mov_b32_e32 v49, 0
	v_mov_b32_e32 v50, 0
	v_mov_b32_e32 v51, 0
	v_mov_b32_e32 v52, 0
	v_mov_b32_e32 v53, 0
	v_mov_b32_e32 v54, 0
	v_mov_b32_e32 v55, 0
	v_mov_b32_e32 v56, 0
	v_mov_b32_e32 v57, 0
	v_mov_b32_e32 v58, 0
	v_mov_b32_e32 v59, 0
	v_mov_b32_e32 v60, 0
	v_mov_b32_e32 v61, 0
	v_mov_b32_e32 v62, 0
	v_mov_b32_e32 v63, 0
	v_mov_b32_e32 v64, 0
	v_mov_b32_e32 v65, 0
	v_mov_b32_e32 v66, 0
	v_mov_b32_e32 v67, 0
	v_mov_b32_e32 v68, 0
	v_mov_b32_e32 v69, 0
	v_mov_b32_e32 v70, 0
	v_mov_b32_e32 v71, 0
	v_mov_b32_e32 v72, 0
	v_mov_b32_e32 v73, 0
	v_mov_b32_e32 v74, 0
	v_mov_b32_e32 v75, 0
	v_mov_b32_e32 v76, 0
	v_mov_b32_e32 v77, 0
	v_mov_b32_e32 v78, 0
	v_mov_b32_e32 v79, 0
	v_mov_b32_e32 v80, 0
	v_mov_b32_e32 v81, 0
	v_mov_b32_e32 v82, 0
	v_mov_b32_e32 v83, 0
	v_mov_b32_e32 v84, 0
	v_mov_b32_e32 v85, 0
	v_mov_b32_e32 v86, 0
	v_mov_b32_e32 v87, 0
	v_mov_b32_e32 v88, 0
	v_mov_b32_e32 v89, 0
	v_mov_b32_e32 v90, 0
	v_mov_b32_e32 v91, 0
	v_mov_b32_e32 v92, 0
	v_mov_b32_e32 v93, 0
	v_mov_b32_e32 v94, 0
	v_mov_b32_e32 v95, 0
	v_mov_b32_e32 v96, 0
	v_mov_b32_e32 v97, 0
	v_mov_b32_e32 v98, 0
	v_mov_b32_e32 v99, 0
	v_mov_b32_e32 v100, 0
	v_mov_b32_e32 v101, 0
	v_mov_b32_e32 v102, 0
	v_mov_b32_e32 v103, 0
	v_mov_b32_e32 v104, 0
	v_mov_b32_e32 v105, 0
	v_mov_b32_e32 v106, 0
	v_mov_b32_e32 v107, 0
	v_mov_b32_e32 v108, 0
	v_mov_b32_e32 v109, 0
	v_mov_b32_e32 v110, 0
	v_mov_b32_e32 v111, 0
	v_mov_b32_e32 v112, 0
	v_mov_b32_e32 v113, 0
	v_mov_b32_e32 v114, 0
	v_mov_b32_e32 v115, 0
	v_mov_b32_e32 v116, 0
	v_mov_b32_e32 v117, 0
	v_mov_b32_e32 v118, 0
	v_mov_b32_e32 v119, 0
	v_mov_b32_e32 v120, 0
	v_mov_b32_e32 v121, 0
	v_mov_b32_e32 v122, 0
	v_mov_b32_e32 v123, 0
	v_mov_b32_e32 v124, 0
	v_mov_b32_e32 v125, 0
	v_mov_b32_e32 v126, 0
	v_mov_b32_e32 v127, 0
	s_add_u32 s4, s56, 0x0
	s_addc_u32 s5, s57, 0
	s_add_u32 m0, s62, 0x0
	s_nop 0
	global_load_lds_dwordx4 v162, s[4:5]
	s_add_u32 s4, s56, 0x10000
	s_addc_u32 s5, s57, 0
	s_add_u32 m0, s62, 0x1000
	s_nop 0
	global_load_lds_dwordx4 v162, s[4:5]
	s_add_u32 s4, s56, 0x20000
	s_addc_u32 s5, s57, 0
	s_add_u32 m0, s62, 0x2000
	s_nop 0
	global_load_lds_dwordx4 v162, s[4:5]
	s_add_u32 s4, s56, 0x30000
	s_addc_u32 s5, s57, 0
	s_add_u32 m0, s62, 0x3000
	s_nop 0
	global_load_lds_dwordx4 v162, s[4:5]
	s_add_u32 s4, s56, 0x40000
	s_addc_u32 s5, s57, 0
	s_add_u32 m0, s62, 0x4000
	s_nop 0
	global_load_lds_dwordx4 v162, s[4:5]
	s_add_u32 s4, s56, 0x50000
	s_addc_u32 s5, s57, 0
	s_add_u32 m0, s62, 0x5000
	s_nop 0
	global_load_lds_dwordx4 v162, s[4:5]
	s_add_u32 s4, s56, 0x60000
	s_addc_u32 s5, s57, 0
	s_add_u32 m0, s62, 0x6000
	s_nop 0
	global_load_lds_dwordx4 v162, s[4:5]
	s_add_u32 s4, s56, 0x70000
	s_addc_u32 s5, s57, 0
	s_add_u32 m0, s62, 0x7000
	s_nop 0
	global_load_lds_dwordx4 v162, s[4:5]
	global_load_dwordx4 v[184:187], v160, s[58:59] offset:0
	global_load_dwordx4 v[188:191], v160, s[58:59] offset:1024
	global_load_dwordx4 v[192:195], v161, s[58:59] offset:0
	global_load_dwordx4 v[196:199], v161, s[58:59] offset:1024
	s_mov_b32 s63, 0
.Lg2_ff1_loop16:
	s_waitcnt vmcnt(0)
	s_barrier
	s_add_u32 s56, s56, 0x80
	s_addc_u32 s57, s57, 0
	s_add_u32 s58, s58, 0x800
	s_addc_u32 s59, s59, 0
	s_add_u32 s4, s56, 0x0
	s_addc_u32 s5, s57, 0
	s_add_u32 m0, s62, 0x8800
	s_nop 0
	global_load_lds_dwordx4 v162, s[4:5]
	s_add_u32 s4, s56, 0x10000
	s_addc_u32 s5, s57, 0
	s_add_u32 m0, s62, 0x9800
	s_nop 0
	global_load_lds_dwordx4 v162, s[4:5]
	s_add_u32 s4, s56, 0x20000
	s_addc_u32 s5, s57, 0
	s_add_u32 m0, s62, 0xa800
	s_nop 0
	global_load_lds_dwordx4 v162, s[4:5]
	s_add_u32 s4, s56, 0x30000
	s_addc_u32 s5, s57, 0
	s_add_u32 m0, s62, 0xb800
	s_nop 0
	global_load_lds_dwordx4 v162, s[4:5]
	s_add_u32 s4, s56, 0x40000
	s_addc_u32 s5, s57, 0
	s_add_u32 m0, s62, 0xc800
	s_nop 0
	global_load_lds_dwordx4 v162, s[4:5]
	s_add_u32 s4, s56, 0x50000
	s_addc_u32 s5, s57, 0
	s_add_u32 m0, s62, 0xd800
	s_nop 0
	global_load_lds_dwordx4 v162, s[4:5]
	s_add_u32 s4, s56, 0x60000
	s_addc_u32 s5, s57, 0
	s_add_u32 m0, s62, 0xe800
	s_nop 0
	global_load_lds_dwordx4 v162, s[4:5]
	s_add_u32 s4, s56, 0x70000
	s_addc_u32 s5, s57, 0
	s_add_u32 m0, s62, 0xf800
	s_nop 0
	global_load_lds_dwordx4 v162, s[4:5]
	global_load_dwordx4 v[200:203], v160, s[58:59] offset:0
	global_load_dwordx4 v[204:207], v160, s[58:59] offset:1024
	global_load_dwordx4 v[208:211], v161, s[58:59] offset:0
	global_load_dwordx4 v[240:243], v161, s[58:59] offset:1024
	ds_read_b128 v[136:139], v156 offset:0
	ds_read_b128 v[140:143], v156 offset:2048
	ds_read_b128 v[144:147], v156 offset:4096
	ds_read_b128 v[148:151], v156 offset:6144
	ds_read_b128 v[164:167], v156 offset:8192
	ds_read_b128 v[168:171], v156 offset:10240
	ds_read_b128 v[172:175], v156 offset:12288
	ds_read_b128 v[176:179], v156 offset:14336
	s_waitcnt lgkmcnt(4)
	v_mfma_f32_16x16x32_bf16 v[0:3], v[184:187], v[136:139], v[0:3]
	v_mfma_f32_16x16x32_bf16 v[4:7], v[192:195], v[136:139], v[4:7]
	v_mfma_f32_16x16x32_bf16 v[8:11], v[184:187], v[140:143], v[8:11]
	v_mfma_f32_16x16x32_bf16 v[12:15], v[192:195], v[140:143], v[12:15]
	v_mfma_f32_16x16x32_bf16 v[16:19], v[184:187], v[144:147], v[16:19]
	v_mfma_f32_16x16x32_bf16 v[20:23], v[192:195], v[144:147], v[20:23]
	v_mfma_f32_16x16x32_bf16 v[24:27], v[184:187], v[148:151], v[24:27]
	v_mfma_f32_16x16x32_bf16 v[28:31], v[192:195], v[148:151], v[28:31]
	ds_read_b128 v[136:139], v156 offset:16384
	ds_read_b128 v[140:143], v156 offset:18432
	ds_read_b128 v[144:147], v156 offset:20480
	ds_read_b128 v[148:151], v156 offset:22528
	s_waitcnt lgkmcnt(4)
	v_mfma_f32_16x16x32_bf16 v[32:35], v[184:187], v[164:167], v[32:35]
	v_mfma_f32_16x16x32_bf16 v[36:39], v[192:195], v[164:167], v[36:39]
	v_mfma_f32_16x16x32_bf16 v[40:43], v[184:187], v[168:171], v[40:43]
	v_mfma_f32_16x16x32_bf16 v[44:47], v[192:195], v[168:171], v[44:47]
	v_mfma_f32_16x16x32_bf16 v[48:51], v[184:187], v[172:175], v[48:51]
	v_mfma_f32_16x16x32_bf16 v[52:55], v[192:195], v[172:175], v[52:55]
	v_mfma_f32_16x16x32_bf16 v[56:59], v[184:187], v[176:179], v[56:59]
	v_mfma_f32_16x16x32_bf16 v[60:63], v[192:195], v[176:179], v[60:63]
	ds_read_b128 v[164:167], v156 offset:24576
	ds_read_b128 v[168:171], v156 offset:26624
	ds_read_b128 v[172:175], v156 offset:28672
	ds_read_b128 v[176:179], v156 offset:30720
	s_waitcnt lgkmcnt(4)
	v_mfma_f32_16x16x32_bf16 v[64:67], v[184:187], v[136:139], v[64:67]
	v_mfma_f32_16x16x32_bf16 v[68:71], v[192:195], v[136:139], v[68:71]
	v_mfma_f32_16x16x32_bf16 v[72:75], v[184:187], v[140:143], v[72:75]
	v_mfma_f32_16x16x32_bf16 v[76:79], v[192:195], v[140:143], v[76:79]
	v_mfma_f32_16x16x32_bf16 v[80:83], v[184:187], v[144:147], v[80:83]
	v_mfma_f32_16x16x32_bf16 v[84:87], v[192:195], v[144:147], v[84:87]
	v_mfma_f32_16x16x32_bf16 v[88:91], v[184:187], v[148:151], v[88:91]
	v_mfma_f32_16x16x32_bf16 v[92:95], v[192:195], v[148:151], v[92:95]
	ds_read_b128 v[136:139], v157 offset:0
	ds_read_b128 v[140:143], v157 offset:2048
	ds_read_b128 v[144:147], v157 offset:4096
	ds_read_b128 v[148:151], v157 offset:6144
	s_waitcnt lgkmcnt(4)
	v_mfma_f32_16x16x32_bf16 v[96:99], v[184:187], v[164:167], v[96:99]
	v_mfma_f32_16x16x32_bf16 v[100:103], v[192:195], v[164:167], v[100:103]
	v_mfma_f32_16x16x32_bf16 v[104:107], v[184:187], v[168:171], v[104:107]
	v_mfma_f32_16x16x32_bf16 v[108:111], v[192:195], v[168:171], v[108:111]
	v_mfma_f32_16x16x32_bf16 v[112:115], v[184:187], v[172:175], v[112:115]
	v_mfma_f32_16x16x32_bf16 v[116:119], v[192:195], v[172:175], v[116:119]
	v_mfma_f32_16x16x32_bf16 v[120:123], v[184:187], v[176:179], v[120:123]
	v_mfma_f32_16x16x32_bf16 v[124:127], v[192:195], v[176:179], v[124:127]
	ds_read_b128 v[164:167], v157 offset:8192
	ds_read_b128 v[168:171], v157 offset:10240
	ds_read_b128 v[172:175], v157 offset:12288
	ds_read_b128 v[176:179], v157 offset:14336
	s_waitcnt lgkmcnt(4)
	v_mfma_f32_16x16x32_bf16 v[0:3], v[188:191], v[136:139], v[0:3]
	v_mfma_f32_16x16x32_bf16 v[4:7], v[196:199], v[136:139], v[4:7]
	v_mfma_f32_16x16x32_bf16 v[8:11], v[188:191], v[140:143], v[8:11]
	v_mfma_f32_16x16x32_bf16 v[12:15], v[196:199], v[140:143], v[12:15]
	v_mfma_f32_16x16x32_bf16 v[16:19], v[188:191], v[144:147], v[16:19]
	v_mfma_f32_16x16x32_bf16 v[20:23], v[196:199], v[144:147], v[20:23]
	v_mfma_f32_16x16x32_bf16 v[24:27], v[188:191], v[148:151], v[24:27]
	v_mfma_f32_16x16x32_bf16 v[28:31], v[196:199], v[148:151], v[28:31]
	ds_read_b128 v[136:139], v157 offset:16384
	ds_read_b128 v[140:143], v157 offset:18432
	ds_read_b128 v[144:147], v157 offset:20480
	ds_read_b128 v[148:151], v157 offset:22528
	s_waitcnt lgkmcnt(4)
	v_mfma_f32_16x16x32_bf16 v[32:35], v[188:191], v[164:167], v[32:35]
	v_mfma_f32_16x16x32_bf16 v[36:39], v[196:199], v[164:167], v[36:39]
	v_mfma_f32_16x16x32_bf16 v[40:43], v[188:191], v[168:171], v[40:43]
	v_mfma_f32_16x16x32_bf16 v[44:47], v[196:199], v[168:171], v[44:47]
	v_mfma_f32_16x16x32_bf16 v[48:51], v[188:191], v[172:175], v[48:51]
	v_mfma_f32_16x16x32_bf16 v[52:55], v[196:199], v[172:175], v[52:55]
	v_mfma_f32_16x16x32_bf16 v[56:59], v[188:191], v[176:179], v[56:59]
	v_mfma_f32_16x16x32_bf16 v[60:63], v[196:199], v[176:179], v[60:63]
	ds_read_b128 v[164:167], v157 offset:24576
	ds_read_b128 v[168:171], v157 offset:26624
	ds_read_b128 v[172:175], v157 offset:28672
	ds_read_b128 v[176:179], v157 offset:30720
	s_waitcnt lgkmcnt(4)
	v_mfma_f32_16x16x32_bf16 v[64:67], v[188:191], v[136:139], v[64:67]
	v_mfma_f32_16x16x32_bf16 v[68:71], v[196:199], v[136:139], v[68:71]
	v_mfma_f32_16x16x32_bf16 v[72:75], v[188:191], v[140:143], v[72:75]
	v_mfma_f32_16x16x32_bf16 v[76:79], v[196:199], v[140:143], v[76:79]
	v_mfma_f32_16x16x32_bf16 v[80:83], v[188:191], v[144:147], v[80:83]
	v_mfma_f32_16x16x32_bf16 v[84:87], v[196:199], v[144:147], v[84:87]
	v_mfma_f32_16x16x32_bf16 v[88:91], v[188:191], v[148:151], v[88:91]
	v_mfma_f32_16x16x32_bf16 v[92:95], v[196:199], v[148:151], v[92:95]
	s_waitcnt lgkmcnt(0)
	v_mfma_f32_16x16x32_bf16 v[96:99], v[188:191], v[164:167], v[96:99]
	v_mfma_f32_16x16x32_bf16 v[100:103], v[196:199], v[164:167], v[100:103]
	v_mfma_f32_16x16x32_bf16 v[104:107], v[188:191], v[168:171], v[104:107]
	v_mfma_f32_16x16x32_bf16 v[108:111], v[196:199], v[168:171], v[108:111]
	v_mfma_f32_16x16x32_bf16 v[112:115], v[188:191], v[172:175], v[112:115]
	v_mfma_f32_16x16x32_bf16 v[116:119], v[196:199], v[172:175], v[116:119]
	v_mfma_f32_16x16x32_bf16 v[120:123], v[188:191], v[176:179], v[120:123]
	v_mfma_f32_16x16x32_bf16 v[124:127], v[196:199], v[176:179], v[124:127]
	s_waitcnt vmcnt(0)
	s_barrier
	s_cmp_ge_u32 s63, 14
	s_cbranch_scc1 .Lg2_ff1_noissue16
	s_add_u32 s56, s56, 0x80
	s_addc_u32 s57, s57, 0
	s_add_u32 s58, s58, 0x800
	s_addc_u32 s59, s59, 0
	s_add_u32 s4, s56, 0x0
	s_addc_u32 s5, s57, 0
	s_add_u32 m0, s62, 0x0
	s_nop 0
	global_load_lds_dwordx4 v162, s[4:5]
	s_add_u32 s4, s56, 0x10000
	s_addc_u32 s5, s57, 0
	s_add_u32 m0, s62, 0x1000
	s_nop 0
	global_load_lds_dwordx4 v162, s[4:5]
	s_add_u32 s4, s56, 0x20000
	s_addc_u32 s5, s57, 0
	s_add_u32 m0, s62, 0x2000
	s_nop 0
	global_load_lds_dwordx4 v162, s[4:5]
	s_add_u32 s4, s56, 0x30000
	s_addc_u32 s5, s57, 0
	s_add_u32 m0, s62, 0x3000
	s_nop 0
	global_load_lds_dwordx4 v162, s[4:5]
	s_add_u32 s4, s56, 0x40000
	s_addc_u32 s5, s57, 0
	s_add_u32 m0, s62, 0x4000
	s_nop 0
	global_load_lds_dwordx4 v162, s[4:5]
	s_add_u32 s4, s56, 0x50000
	s_addc_u32 s5, s57, 0
	s_add_u32 m0, s62, 0x5000
	s_nop 0
	global_load_lds_dwordx4 v162, s[4:5]
	s_add_u32 s4, s56, 0x60000
	s_addc_u32 s5, s57, 0
	s_add_u32 m0, s62, 0x6000
	s_nop 0
	global_load_lds_dwordx4 v162, s[4:5]
	s_add_u32 s4, s56, 0x70000
	s_addc_u32 s5, s57, 0
	s_add_u32 m0, s62, 0x7000
	s_nop 0
	global_load_lds_dwordx4 v162, s[4:5]
	global_load_dwordx4 v[184:187], v160, s[58:59] offset:0
	global_load_dwordx4 v[188:191], v160, s[58:59] offset:1024
	global_load_dwordx4 v[192:195], v161, s[58:59] offset:0
	global_load_dwordx4 v[196:199], v161, s[58:59] offset:1024
.Lg2_ff1_noissue16:
	ds_read_b128 v[136:139], v158 offset:0
	ds_read_b128 v[140:143], v158 offset:2048
	ds_read_b128 v[144:147], v158 offset:4096
	ds_read_b128 v[148:151], v158 offset:6144
	ds_read_b128 v[164:167], v158 offset:8192
	ds_read_b128 v[168:171], v158 offset:10240
	ds_read_b128 v[172:175], v158 offset:12288
	ds_read_b128 v[176:179], v158 offset:14336
	s_waitcnt lgkmcnt(4)
	v_mfma_f32_16x16x32_bf16 v[0:3], v[200:203], v[136:139], v[0:3]
	v_mfma_f32_16x16x32_bf16 v[4:7], v[208:211], v[136:139], v[4:7]
	v_mfma_f32_16x16x32_bf16 v[8:11], v[200:203], v[140:143], v[8:11]
	v_mfma_f32_16x16x32_bf16 v[12:15], v[208:211], v[140:143], v[12:15]
	v_mfma_f32_16x16x32_bf16 v[16:19], v[200:203], v[144:147], v[16:19]
	v_mfma_f32_16x16x32_bf16 v[20:23], v[208:211], v[144:147], v[20:23]
	v_mfma_f32_16x16x32_bf16 v[24:27], v[200:203], v[148:151], v[24:27]
	v_mfma_f32_16x16x32_bf16 v[28:31], v[208:211], v[148:151], v[28:31]
	ds_read_b128 v[136:139], v158 offset:16384
	ds_read_b128 v[140:143], v158 offset:18432
	ds_read_b128 v[144:147], v158 offset:20480
	ds_read_b128 v[148:151], v158 offset:22528
	s_waitcnt lgkmcnt(4)
	v_mfma_f32_16x16x32_bf16 v[32:35], v[200:203], v[164:167], v[32:35]
	v_mfma_f32_16x16x32_bf16 v[36:39], v[208:211], v[164:167], v[36:39]
	v_mfma_f32_16x16x32_bf16 v[40:43], v[200:203], v[168:171], v[40:43]
	v_mfma_f32_16x16x32_bf16 v[44:47], v[208:211], v[168:171], v[44:47]
	v_mfma_f32_16x16x32_bf16 v[48:51], v[200:203], v[172:175], v[48:51]
	v_mfma_f32_16x16x32_bf16 v[52:55], v[208:211], v[172:175], v[52:55]
	v_mfma_f32_16x16x32_bf16 v[56:59], v[200:203], v[176:179], v[56:59]
	v_mfma_f32_16x16x32_bf16 v[60:63], v[208:211], v[176:179], v[60:63]
	ds_read_b128 v[164:167], v158 offset:24576
	ds_read_b128 v[168:171], v158 offset:26624
	ds_read_b128 v[172:175], v158 offset:28672
	ds_read_b128 v[176:179], v158 offset:30720
	s_waitcnt lgkmcnt(4)
	v_mfma_f32_16x16x32_bf16 v[64:67], v[200:203], v[136:139], v[64:67]
	v_mfma_f32_16x16x32_bf16 v[68:71], v[208:211], v[136:139], v[68:71]
	v_mfma_f32_16x16x32_bf16 v[72:75], v[200:203], v[140:143], v[72:75]
	v_mfma_f32_16x16x32_bf16 v[76:79], v[208:211], v[140:143], v[76:79]
	v_mfma_f32_16x16x32_bf16 v[80:83], v[200:203], v[144:147], v[80:83]
	v_mfma_f32_16x16x32_bf16 v[84:87], v[208:211], v[144:147], v[84:87]
	v_mfma_f32_16x16x32_bf16 v[88:91], v[200:203], v[148:151], v[88:91]
	v_mfma_f32_16x16x32_bf16 v[92:95], v[208:211], v[148:151], v[92:95]
	ds_read_b128 v[136:139], v159 offset:0
	ds_read_b128 v[140:143], v159 offset:2048
	ds_read_b128 v[144:147], v159 offset:4096
	ds_read_b128 v[148:151], v159 offset:6144
	s_waitcnt lgkmcnt(4)
	v_mfma_f32_16x16x32_bf16 v[96:99], v[200:203], v[164:167], v[96:99]
	v_mfma_f32_16x16x32_bf16 v[100:103], v[208:211], v[164:167], v[100:103]
	v_mfma_f32_16x16x32_bf16 v[104:107], v[200:203], v[168:171], v[104:107]
	v_mfma_f32_16x16x32_bf16 v[108:111], v[208:211], v[168:171], v[108:111]
	v_mfma_f32_16x16x32_bf16 v[112:115], v[200:203], v[172:175], v[112:115]
	v_mfma_f32_16x16x32_bf16 v[116:119], v[208:211], v[172:175], v[116:119]
	v_mfma_f32_16x16x32_bf16 v[120:123], v[200:203], v[176:179], v[120:123]
	v_mfma_f32_16x16x32_bf16 v[124:127], v[208:211], v[176:179], v[124:127]
	ds_read_b128 v[164:167], v159 offset:8192
	ds_read_b128 v[168:171], v159 offset:10240
	ds_read_b128 v[172:175], v159 offset:12288
	ds_read_b128 v[176:179], v159 offset:14336
	s_waitcnt lgkmcnt(4)
	v_mfma_f32_16x16x32_bf16 v[0:3], v[204:207], v[136:139], v[0:3]
	v_mfma_f32_16x16x32_bf16 v[4:7], v[240:243], v[136:139], v[4:7]
	v_mfma_f32_16x16x32_bf16 v[8:11], v[204:207], v[140:143], v[8:11]
	v_mfma_f32_16x16x32_bf16 v[12:15], v[240:243], v[140:143], v[12:15]
	v_mfma_f32_16x16x32_bf16 v[16:19], v[204:207], v[144:147], v[16:19]
	v_mfma_f32_16x16x32_bf16 v[20:23], v[240:243], v[144:147], v[20:23]
	v_mfma_f32_16x16x32_bf16 v[24:27], v[204:207], v[148:151], v[24:27]
	v_mfma_f32_16x16x32_bf16 v[28:31], v[240:243], v[148:151], v[28:31]
	ds_read_b128 v[136:139], v159 offset:16384
	ds_read_b128 v[140:143], v159 offset:18432
	ds_read_b128 v[144:147], v159 offset:20480
	ds_read_b128 v[148:151], v159 offset:22528
	s_waitcnt lgkmcnt(4)
	v_mfma_f32_16x16x32_bf16 v[32:35], v[204:207], v[164:167], v[32:35]
	v_mfma_f32_16x16x32_bf16 v[36:39], v[240:243], v[164:167], v[36:39]
	v_mfma_f32_16x16x32_bf16 v[40:43], v[204:207], v[168:171], v[40:43]
	v_mfma_f32_16x16x32_bf16 v[44:47], v[240:243], v[168:171], v[44:47]
	v_mfma_f32_16x16x32_bf16 v[48:51], v[204:207], v[172:175], v[48:51]
	v_mfma_f32_16x16x32_bf16 v[52:55], v[240:243], v[172:175], v[52:55]
	v_mfma_f32_16x16x32_bf16 v[56:59], v[204:207], v[176:179], v[56:59]
	v_mfma_f32_16x16x32_bf16 v[60:63], v[240:243], v[176:179], v[60:63]
	ds_read_b128 v[164:167], v159 offset:24576
	ds_read_b128 v[168:171], v159 offset:26624
	ds_read_b128 v[172:175], v159 offset:28672
	ds_read_b128 v[176:179], v159 offset:30720
	s_waitcnt lgkmcnt(4)
	v_mfma_f32_16x16x32_bf16 v[64:67], v[204:207], v[136:139], v[64:67]
	v_mfma_f32_16x16x32_bf16 v[68:71], v[240:243], v[136:139], v[68:71]
	v_mfma_f32_16x16x32_bf16 v[72:75], v[204:207], v[140:143], v[72:75]
	v_mfma_f32_16x16x32_bf16 v[76:79], v[240:243], v[140:143], v[76:79]
	v_mfma_f32_16x16x32_bf16 v[80:83], v[204:207], v[144:147], v[80:83]
	v_mfma_f32_16x16x32_bf16 v[84:87], v[240:243], v[144:147], v[84:87]
	v_mfma_f32_16x16x32_bf16 v[88:91], v[204:207], v[148:151], v[88:91]
	v_mfma_f32_16x16x32_bf16 v[92:95], v[240:243], v[148:151], v[92:95]
	s_waitcnt lgkmcnt(0)
	v_mfma_f32_16x16x32_bf16 v[96:99], v[204:207], v[164:167], v[96:99]
	v_mfma_f32_16x16x32_bf16 v[100:103], v[240:243], v[164:167], v[100:103]
	v_mfma_f32_16x16x32_bf16 v[104:107], v[204:207], v[168:171], v[104:107]
	v_mfma_f32_16x16x32_bf16 v[108:111], v[240:243], v[168:171], v[108:111]
	v_mfma_f32_16x16x32_bf16 v[112:115], v[204:207], v[172:175], v[112:115]
	v_mfma_f32_16x16x32_bf16 v[116:119], v[240:243], v[172:175], v[116:119]
	v_mfma_f32_16x16x32_bf16 v[120:123], v[204:207], v[176:179], v[120:123]
	v_mfma_f32_16x16x32_bf16 v[124:127], v[240:243], v[176:179], v[124:127]
	s_add_i32 s63, s63, 2
	s_cmp_lt_u32 s63, 16
	s_cbranch_scc1 .Lg2_ff1_loop16
	s_branch .Lg2_ff1_episel
.Lg2_ff1_episel:
.Lg2_ff1_epiP:
	s_nop 7
	s_nop 7
	s_barrier
	v_max_f32_e32 v0, 0, v0
	v_max_f32_e32 v1, 0, v1
	v_max_f32_e32 v2, 0, v2
	v_max_f32_e32 v3, 0, v3
	v_mul_f32_e32 v0, v0, v0
	v_mul_f32_e32 v1, v1, v1
	v_mul_f32_e32 v2, v2, v2
	v_mul_f32_e32 v3, v3, v3
	v_cvt_pk_bf16_f32 v0, v0, v1
	v_cvt_pk_bf16_f32 v1, v2, v3
	ds_write_b64 v212, v[0:1] offset:0
	v_max_f32_e32 v4, 0, v4
	v_max_f32_e32 v5, 0, v5
	v_max_f32_e32 v6, 0, v6
	v_max_f32_e32 v7, 0, v7
	v_mul_f32_e32 v4, v4, v4
	v_mul_f32_e32 v5, v5, v5
	v_mul_f32_e32 v6, v6, v6
	v_mul_f32_e32 v7, v7, v7
	v_cvt_pk_bf16_f32 v4, v4, v5
	v_cvt_pk_bf16_f32 v5, v6, v7
	ds_write_b64 v213, v[4:5] offset:0
	v_max_f32_e32 v8, 0, v8
	v_max_f32_e32 v9, 0, v9
	v_max_f32_e32 v10, 0, v10
	v_max_f32_e32 v11, 0, v11
	v_mul_f32_e32 v8, v8, v8
	v_mul_f32_e32 v9, v9, v9
	v_mul_f32_e32 v10, v10, v10
	v_mul_f32_e32 v11, v11, v11
	v_cvt_pk_bf16_f32 v8, v8, v9
	v_cvt_pk_bf16_f32 v9, v10, v11
	ds_write_b64 v212, v[8:9] offset:4096
	v_max_f32_e32 v12, 0, v12
	v_max_f32_e32 v13, 0, v13
	v_max_f32_e32 v14, 0, v14
	v_max_f32_e32 v15, 0, v15
	v_mul_f32_e32 v12, v12, v12
	v_mul_f32_e32 v13, v13, v13
	v_mul_f32_e32 v14, v14, v14
	v_mul_f32_e32 v15, v15, v15
	v_cvt_pk_bf16_f32 v12, v12, v13
	v_cvt_pk_bf16_f32 v13, v14, v15
	ds_write_b64 v213, v[12:13] offset:4096
	v_max_f32_e32 v16, 0, v16
	v_max_f32_e32 v17, 0, v17
	v_max_f32_e32 v18, 0, v18
	v_max_f32_e32 v19, 0, v19
	v_mul_f32_e32 v16, v16, v16
	v_mul_f32_e32 v17, v17, v17
	v_mul_f32_e32 v18, v18, v18
	v_mul_f32_e32 v19, v19, v19
	v_cvt_pk_bf16_f32 v16, v16, v17
	v_cvt_pk_bf16_f32 v17, v18, v19
	ds_write_b64 v212, v[16:17] offset:8192
	v_max_f32_e32 v20, 0, v20
	v_max_f32_e32 v21, 0, v21
	v_max_f32_e32 v22, 0, v22
	v_max_f32_e32 v23, 0, v23
	v_mul_f32_e32 v20, v20, v20
	v_mul_f32_e32 v21, v21, v21
	v_mul_f32_e32 v22, v22, v22
	v_mul_f32_e32 v23, v23, v23
	v_cvt_pk_bf16_f32 v20, v20, v21
	v_cvt_pk_bf16_f32 v21, v22, v23
	ds_write_b64 v213, v[20:21] offset:8192
	v_max_f32_e32 v24, 0, v24
	v_max_f32_e32 v25, 0, v25
	v_max_f32_e32 v26, 0, v26
	v_max_f32_e32 v27, 0, v27
	v_mul_f32_e32 v24, v24, v24
	v_mul_f32_e32 v25, v25, v25
	v_mul_f32_e32 v26, v26, v26
	v_mul_f32_e32 v27, v27, v27
	v_cvt_pk_bf16_f32 v24, v24, v25
	v_cvt_pk_bf16_f32 v25, v26, v27
	ds_write_b64 v212, v[24:25] offset:12288
	v_max_f32_e32 v28, 0, v28
	v_max_f32_e32 v29, 0, v29
	v_max_f32_e32 v30, 0, v30
	v_max_f32_e32 v31, 0, v31
	v_mul_f32_e32 v28, v28, v28
	v_mul_f32_e32 v29, v29, v29
	v_mul_f32_e32 v30, v30, v30
	v_mul_f32_e32 v31, v31, v31
	v_cvt_pk_bf16_f32 v28, v28, v29
	v_cvt_pk_bf16_f32 v29, v30, v31
	ds_write_b64 v213, v[28:29] offset:12288
	v_max_f32_e32 v32, 0, v32
	v_max_f32_e32 v33, 0, v33
	v_max_f32_e32 v34, 0, v34
	v_max_f32_e32 v35, 0, v35
	v_mul_f32_e32 v32, v32, v32
	v_mul_f32_e32 v33, v33, v33
	v_mul_f32_e32 v34, v34, v34
	v_mul_f32_e32 v35, v35, v35
	v_cvt_pk_bf16_f32 v32, v32, v33
	v_cvt_pk_bf16_f32 v33, v34, v35
	ds_write_b64 v212, v[32:33] offset:16384
	v_max_f32_e32 v36, 0, v36
	v_max_f32_e32 v37, 0, v37
	v_max_f32_e32 v38, 0, v38
	v_max_f32_e32 v39, 0, v39
	v_mul_f32_e32 v36, v36, v36
	v_mul_f32_e32 v37, v37, v37
	v_mul_f32_e32 v38, v38, v38
	v_mul_f32_e32 v39, v39, v39
	v_cvt_pk_bf16_f32 v36, v36, v37
	v_cvt_pk_bf16_f32 v37, v38, v39
	ds_write_b64 v213, v[36:37] offset:16384
	v_max_f32_e32 v40, 0, v40
	v_max_f32_e32 v41, 0, v41
	v_max_f32_e32 v42, 0, v42
	v_max_f32_e32 v43, 0, v43
	v_mul_f32_e32 v40, v40, v40
	v_mul_f32_e32 v41, v41, v41
	v_mul_f32_e32 v42, v42, v42
	v_mul_f32_e32 v43, v43, v43
	v_cvt_pk_bf16_f32 v40, v40, v41
	v_cvt_pk_bf16_f32 v41, v42, v43
	ds_write_b64 v212, v[40:41] offset:20480
	v_max_f32_e32 v44, 0, v44
	v_max_f32_e32 v45, 0, v45
	v_max_f32_e32 v46, 0, v46
	v_max_f32_e32 v47, 0, v47
	v_mul_f32_e32 v44, v44, v44
	v_mul_f32_e32 v45, v45, v45
	v_mul_f32_e32 v46, v46, v46
	v_mul_f32_e32 v47, v47, v47
	v_cvt_pk_bf16_f32 v44, v44, v45
	v_cvt_pk_bf16_f32 v45, v46, v47
	ds_write_b64 v213, v[44:45] offset:20480
	v_max_f32_e32 v48, 0, v48
	v_max_f32_e32 v49, 0, v49
	v_max_f32_e32 v50, 0, v50
	v_max_f32_e32 v51, 0, v51
	v_mul_f32_e32 v48, v48, v48
	v_mul_f32_e32 v49, v49, v49
	v_mul_f32_e32 v50, v50, v50
	v_mul_f32_e32 v51, v51, v51
	v_cvt_pk_bf16_f32 v48, v48, v49
	v_cvt_pk_bf16_f32 v49, v50, v51
	ds_write_b64 v212, v[48:49] offset:24576
	v_max_f32_e32 v52, 0, v52
	v_max_f32_e32 v53, 0, v53
	v_max_f32_e32 v54, 0, v54
	v_max_f32_e32 v55, 0, v55
	v_mul_f32_e32 v52, v52, v52
	v_mul_f32_e32 v53, v53, v53
	v_mul_f32_e32 v54, v54, v54
	v_mul_f32_e32 v55, v55, v55
	v_cvt_pk_bf16_f32 v52, v52, v53
	v_cvt_pk_bf16_f32 v53, v54, v55
	ds_write_b64 v213, v[52:53] offset:24576
	v_max_f32_e32 v56, 0, v56
	v_max_f32_e32 v57, 0, v57
	v_max_f32_e32 v58, 0, v58
	v_max_f32_e32 v59, 0, v59
	v_mul_f32_e32 v56, v56, v56
	v_mul_f32_e32 v57, v57, v57
	v_mul_f32_e32 v58, v58, v58
	v_mul_f32_e32 v59, v59, v59
	v_cvt_pk_bf16_f32 v56, v56, v57
	v_cvt_pk_bf16_f32 v57, v58, v59
	ds_write_b64 v212, v[56:57] offset:28672
	v_max_f32_e32 v60, 0, v60
	v_max_f32_e32 v61, 0, v61
	v_max_f32_e32 v62, 0, v62
	v_max_f32_e32 v63, 0, v63
	v_mul_f32_e32 v60, v60, v60
	v_mul_f32_e32 v61, v61, v61
	v_mul_f32_e32 v62, v62, v62
	v_mul_f32_e32 v63, v63, v63
	v_cvt_pk_bf16_f32 v60, v60, v61
	v_cvt_pk_bf16_f32 v61, v62, v63
	ds_write_b64 v213, v[60:61] offset:28672
	v_max_f32_e32 v64, 0, v64
	v_max_f32_e32 v65, 0, v65
	v_max_f32_e32 v66, 0, v66
	v_max_f32_e32 v67, 0, v67
	v_mul_f32_e32 v64, v64, v64
	v_mul_f32_e32 v65, v65, v65
	v_mul_f32_e32 v66, v66, v66
	v_mul_f32_e32 v67, v67, v67
	v_cvt_pk_bf16_f32 v64, v64, v65
	v_cvt_pk_bf16_f32 v65, v66, v67
	ds_write_b64 v253, v[64:65] offset:0
	v_max_f32_e32 v68, 0, v68
	v_max_f32_e32 v69, 0, v69
	v_max_f32_e32 v70, 0, v70
	v_max_f32_e32 v71, 0, v71
	v_mul_f32_e32 v68, v68, v68
	v_mul_f32_e32 v69, v69, v69
	v_mul_f32_e32 v70, v70, v70
	v_mul_f32_e32 v71, v71, v71
	v_cvt_pk_bf16_f32 v68, v68, v69
	v_cvt_pk_bf16_f32 v69, v70, v71
	ds_write_b64 v254, v[68:69] offset:0
	v_max_f32_e32 v72, 0, v72
	v_max_f32_e32 v73, 0, v73
	v_max_f32_e32 v74, 0, v74
	v_max_f32_e32 v75, 0, v75
	v_mul_f32_e32 v72, v72, v72
	v_mul_f32_e32 v73, v73, v73
	v_mul_f32_e32 v74, v74, v74
	v_mul_f32_e32 v75, v75, v75
	v_cvt_pk_bf16_f32 v72, v72, v73
	v_cvt_pk_bf16_f32 v73, v74, v75
	ds_write_b64 v253, v[72:73] offset:4096
	v_max_f32_e32 v76, 0, v76
	v_max_f32_e32 v77, 0, v77
	v_max_f32_e32 v78, 0, v78
	v_max_f32_e32 v79, 0, v79
	v_mul_f32_e32 v76, v76, v76
	v_mul_f32_e32 v77, v77, v77
	v_mul_f32_e32 v78, v78, v78
	v_mul_f32_e32 v79, v79, v79
	v_cvt_pk_bf16_f32 v76, v76, v77
	v_cvt_pk_bf16_f32 v77, v78, v79
	ds_write_b64 v254, v[76:77] offset:4096
	v_max_f32_e32 v80, 0, v80
	v_max_f32_e32 v81, 0, v81
	v_max_f32_e32 v82, 0, v82
	v_max_f32_e32 v83, 0, v83
	v_mul_f32_e32 v80, v80, v80
	v_mul_f32_e32 v81, v81, v81
	v_mul_f32_e32 v82, v82, v82
	v_mul_f32_e32 v83, v83, v83
	v_cvt_pk_bf16_f32 v80, v80, v81
	v_cvt_pk_bf16_f32 v81, v82, v83
	ds_write_b64 v253, v[80:81] offset:8192
	v_max_f32_e32 v84, 0, v84
	v_max_f32_e32 v85, 0, v85
	v_max_f32_e32 v86, 0, v86
	v_max_f32_e32 v87, 0, v87
	v_mul_f32_e32 v84, v84, v84
	v_mul_f32_e32 v85, v85, v85
	v_mul_f32_e32 v86, v86, v86
	v_mul_f32_e32 v87, v87, v87
	v_cvt_pk_bf16_f32 v84, v84, v85
	v_cvt_pk_bf16_f32 v85, v86, v87
	ds_write_b64 v254, v[84:85] offset:8192
	v_max_f32_e32 v88, 0, v88
	v_max_f32_e32 v89, 0, v89
	v_max_f32_e32 v90, 0, v90
	v_max_f32_e32 v91, 0, v91
	v_mul_f32_e32 v88, v88, v88
	v_mul_f32_e32 v89, v89, v89
	v_mul_f32_e32 v90, v90, v90
	v_mul_f32_e32 v91, v91, v91
	v_cvt_pk_bf16_f32 v88, v88, v89
	v_cvt_pk_bf16_f32 v89, v90, v91
	ds_write_b64 v253, v[88:89] offset:12288
	v_max_f32_e32 v92, 0, v92
	v_max_f32_e32 v93, 0, v93
	v_max_f32_e32 v94, 0, v94
	v_max_f32_e32 v95, 0, v95
	v_mul_f32_e32 v92, v92, v92
	v_mul_f32_e32 v93, v93, v93
	v_mul_f32_e32 v94, v94, v94
	v_mul_f32_e32 v95, v95, v95
	v_cvt_pk_bf16_f32 v92, v92, v93
	v_cvt_pk_bf16_f32 v93, v94, v95
	ds_write_b64 v254, v[92:93] offset:12288
	v_max_f32_e32 v96, 0, v96
	v_max_f32_e32 v97, 0, v97
	v_max_f32_e32 v98, 0, v98
	v_max_f32_e32 v99, 0, v99
	v_mul_f32_e32 v96, v96, v96
	v_mul_f32_e32 v97, v97, v97
	v_mul_f32_e32 v98, v98, v98
	v_mul_f32_e32 v99, v99, v99
	v_cvt_pk_bf16_f32 v96, v96, v97
	v_cvt_pk_bf16_f32 v97, v98, v99
	ds_write_b64 v253, v[96:97] offset:16384
	v_max_f32_e32 v100, 0, v100
	v_max_f32_e32 v101, 0, v101
	v_max_f32_e32 v102, 0, v102
	v_max_f32_e32 v103, 0, v103
	v_mul_f32_e32 v100, v100, v100
	v_mul_f32_e32 v101, v101, v101
	v_mul_f32_e32 v102, v102, v102
	v_mul_f32_e32 v103, v103, v103
	v_cvt_pk_bf16_f32 v100, v100, v101
	v_cvt_pk_bf16_f32 v101, v102, v103
	ds_write_b64 v254, v[100:101] offset:16384
	v_max_f32_e32 v104, 0, v104
	v_max_f32_e32 v105, 0, v105
	v_max_f32_e32 v106, 0, v106
	v_max_f32_e32 v107, 0, v107
	v_mul_f32_e32 v104, v104, v104
	v_mul_f32_e32 v105, v105, v105
	v_mul_f32_e32 v106, v106, v106
	v_mul_f32_e32 v107, v107, v107
	v_cvt_pk_bf16_f32 v104, v104, v105
	v_cvt_pk_bf16_f32 v105, v106, v107
	ds_write_b64 v253, v[104:105] offset:20480
	v_max_f32_e32 v108, 0, v108
	v_max_f32_e32 v109, 0, v109
	v_max_f32_e32 v110, 0, v110
	v_max_f32_e32 v111, 0, v111
	v_mul_f32_e32 v108, v108, v108
	v_mul_f32_e32 v109, v109, v109
	v_mul_f32_e32 v110, v110, v110
	v_mul_f32_e32 v111, v111, v111
	v_cvt_pk_bf16_f32 v108, v108, v109
	v_cvt_pk_bf16_f32 v109, v110, v111
	ds_write_b64 v254, v[108:109] offset:20480
	v_max_f32_e32 v112, 0, v112
	v_max_f32_e32 v113, 0, v113
	v_max_f32_e32 v114, 0, v114
	v_max_f32_e32 v115, 0, v115
	v_mul_f32_e32 v112, v112, v112
	v_mul_f32_e32 v113, v113, v113
	v_mul_f32_e32 v114, v114, v114
	v_mul_f32_e32 v115, v115, v115
	v_cvt_pk_bf16_f32 v112, v112, v113
	v_cvt_pk_bf16_f32 v113, v114, v115
	ds_write_b64 v253, v[112:113] offset:24576
	v_max_f32_e32 v116, 0, v116
	v_max_f32_e32 v117, 0, v117
	v_max_f32_e32 v118, 0, v118
	v_max_f32_e32 v119, 0, v119
	v_mul_f32_e32 v116, v116, v116
	v_mul_f32_e32 v117, v117, v117
	v_mul_f32_e32 v118, v118, v118
	v_mul_f32_e32 v119, v119, v119
	v_cvt_pk_bf16_f32 v116, v116, v117
	v_cvt_pk_bf16_f32 v117, v118, v119
	ds_write_b64 v254, v[116:117] offset:24576
	v_max_f32_e32 v120, 0, v120
	v_max_f32_e32 v121, 0, v121
	v_max_f32_e32 v122, 0, v122
	v_max_f32_e32 v123, 0, v123
	v_mul_f32_e32 v120, v120, v120
	v_mul_f32_e32 v121, v121, v121
	v_mul_f32_e32 v122, v122, v122
	v_mul_f32_e32 v123, v123, v123
	v_cvt_pk_bf16_f32 v120, v120, v121
	v_cvt_pk_bf16_f32 v121, v122, v123
	ds_write_b64 v253, v[120:121] offset:28672
	v_max_f32_e32 v124, 0, v124
	v_max_f32_e32 v125, 0, v125
	v_max_f32_e32 v126, 0, v126
	v_max_f32_e32 v127, 0, v127
	v_mul_f32_e32 v124, v124, v124
	v_mul_f32_e32 v125, v125, v125
	v_mul_f32_e32 v126, v126, v126
	v_mul_f32_e32 v127, v127, v127
	v_cvt_pk_bf16_f32 v124, v124, v125
	v_cvt_pk_bf16_f32 v125, v126, v127
	ds_write_b64 v254, v[124:125] offset:28672
	s_cmp_eq_u32 s65, 0
	s_cbranch_scc1 .Lg2_ff1_st_lastP
	v_max_f32_e32 v128, 0, v128
	v_max_f32_e32 v129, 0, v129
	v_max_f32_e32 v130, 0, v130
	v_max_f32_e32 v131, 0, v131
	v_mul_f32_e32 v128, v128, v128
	v_mul_f32_e32 v129, v129, v129
	v_mul_f32_e32 v130, v130, v130
	v_mul_f32_e32 v131, v131, v131
	v_cvt_pk_bf16_f32 v128, v128, v129
	v_cvt_pk_bf16_f32 v129, v130, v131
	ds_write_b64 v253, v[128:129] offset:32768
	v_max_f32_e32 v132, 0, v132
	v_max_f32_e32 v133, 0, v133
	v_max_f32_e32 v134, 0, v134
	v_max_f32_e32 v135, 0, v135
	v_mul_f32_e32 v132, v132, v132
	v_mul_f32_e32 v133, v133, v133
	v_mul_f32_e32 v134, v134, v134
	v_mul_f32_e32 v135, v135, v135
	v_cvt_pk_bf16_f32 v132, v132, v133
	v_cvt_pk_bf16_f32 v133, v134, v135
	ds_write_b64 v254, v[132:133] offset:32768

.Lg2_ff1_next:
	s_add_i32 s64, s64, 1
	s_cmp_lt_u32 s64, 4
	s_cbranch_scc1 .Lg2_ff1_tile

.Lg2_out_entry:
	s_waitcnt vmcnt(0) lgkmcnt(0)
	s_barrier
	v_mov_b32_e32 v2, 0x10200
	ds_read_b64 v[2:3], v2
	v_readlane_b32 s0, v246, 0
	v_lshrrev_b32_e32 v4, 6, v163
	v_and_b32_e32 v5, 63, v163
	s_and_b32 s1, s0, 7
	s_lshr_b32 s0, s0, 3
	s_lshr_b32 s68, s0, 3
	s_and_b32 s0, s0, 7
	s_lshl_b32 s0, s0, 3
	s_add_i32 s0, s0, s1
	s_cmp_lt_u32 s0, 32
	s_cselect_b32 s43, 1, 0
	s_min_u32 s1, s0, 32
	s_lshl_b32 s0, s0, 4
	s_add_i32 s0, s0, s1
	s_lshl_b32 s42, s0, 4
	v_readfirstlane_b32 s70, v4
	v_and_b32_e32 v6, 15, v5
	v_lshrrev_b32_e32 v7, 4, v5
	s_waitcnt lgkmcnt(0)
	v_readfirstlane_b32 s66, v2
	v_readfirstlane_b32 s67, v3
	s_lshl_b32 s62, s70, 10
	v_and_b32_e32 v8, 7, v6
	v_xor_b32_e32 v9, v7, v8
	v_lshlrev_b32_e32 v9, 4, v9
	v_lshl_add_u32 v156, v6, 7, v9
	v_add_u32_e32 v10, 4, v7
	v_xor_b32_e32 v10, v10, v8
	v_lshlrev_b32_e32 v10, 4, v10
	v_lshl_add_u32 v157, v6, 7, v10
	v_add_u32_e32 v158, 0x8800, v156
	v_add_u32_e32 v159, 0x8800, v157
	v_lshrrev_b32_e32 v11, 3, v163
	v_and_b32_e32 v12, 7, v163
	v_and_b32_e32 v13, 7, v11
	v_xor_b32_e32 v12, v12, v13
	v_lshlrev_b32_e32 v12, 4, v12
	s_mov_b32 s2, 0x800
	v_mul_lo_u32 v11, v11, s2
	v_add_u32_e32 v162, v11, v12
	v_lshrrev_b32_e32 v11, 4, v163
	v_and_b32_e32 v12, 15, v163
	v_xor_b32_e32 v13, v12, v11
	v_lshlrev_b32_e32 v13, 4, v13
	v_lshl_add_u32 v247, v11, 8, v13
	s_mov_b32 s2, 0x800
	v_mul_lo_u32 v11, v11, s2
	v_lshl_add_u32 v252, v12, 4, v11
	v_add_u32_e32 v255, 0x8000, v247
	v_lshlrev_b32_e32 v11, 1, v4
	s_mov_b32 s2, 0x8000
	v_mul_lo_u32 v12, v11, s2
	v_lshl_add_u32 v160, v5, 4, v12
	v_add_u32_e32 v161, 0x8000, v160
	v_lshrrev_b32_e32 v12, 1, v7
	v_lshl_add_u32 v12, v11, 1, v12
	v_and_b32_e32 v13, 1, v7
	v_lshlrev_b32_e32 v13, 3, v13
	v_lshl_add_u32 v14, v6, 8, v13
	v_xor_b32_e32 v15, v12, v6
	v_lshlrev_b32_e32 v15, 4, v15
	v_add_u32_e32 v212, v14, v15
	v_add_u32_e32 v12, 2, v12
	v_xor_b32_e32 v15, v12, v6
	v_lshlrev_b32_e32 v15, 4, v15
	v_add_u32_e32 v213, v14, v15
	v_add_u32_e32 v253, 0x8000, v212
	v_add_u32_e32 v254, 0x8000, v213
	s_mov_b32 s64, 0
.Lg2_out_tile:
	s_lshl_b32 s0, s64, 3
	s_add_i32 s38, s0, s68
	s_mov_b32 s69, s42
	s_mov_b32 s65, s43
	s_lshl_b32 s0, s38, 7
	s_mul_i32 s2, s69, 0x800
	s_mul_hi_u32 s3, s69, 0x800
	s_add_u32 s56, s26, s2
	s_addc_u32 s57, s27, s3
	s_add_u32 s56, s56, 0x13240000
	s_addc_u32 s57, s57, 0
	s_mul_i32 s2, s0, 0x800
	s_mul_hi_u32 s3, s0, 0x800
	s_add_u32 s58, s26, s2
	s_addc_u32 s59, s27, s3
	s_add_u32 s58, s58, 0xfd40000
	s_addc_u32 s59, s59, 0
	s_mul_i32 s2, s69, 0x800
	s_mul_hi_u32 s3, s69, 0x800
	s_lshl_b32 s0, s0, 1
	s_add_u32 s2, s2, s0
	s_addc_u32 s3, s3, 0
	s_add_u32 s60, s26, s2
	s_addc_u32 s61, s27, s3
	s_add_u32 s60, s60, 0x11140000
	s_addc_u32 s61, s61, 0
	s_cmp_eq_u32 s65, 0
	s_cbranch_scc1 .Lg2_out_k16
	v_mov_b32_e32 v0, 0
	v_mov_b32_e32 v1, 0
	v_mov_b32_e32 v2, 0
	v_mov_b32_e32 v3, 0
	v_mov_b32_e32 v4, 0
	v_mov_b32_e32 v5, 0
	v_mov_b32_e32 v6, 0
	v_mov_b32_e32 v7, 0
	v_mov_b32_e32 v8, 0
	v_mov_b32_e32 v9, 0
	v_mov_b32_e32 v10, 0
	v_mov_b32_e32 v11, 0
	v_mov_b32_e32 v12, 0
	v_mov_b32_e32 v13, 0
	v_mov_b32_e32 v14, 0
	v_mov_b32_e32 v15, 0
	v_mov_b32_e32 v16, 0
	v_mov_b32_e32 v17, 0
	v_mov_b32_e32 v18, 0
	v_mov_b32_e32 v19, 0
	v_mov_b32_e32 v20, 0
	v_mov_b32_e32 v21, 0
	v_mov_b32_e32 v22, 0
	v_mov_b32_e32 v23, 0
	v_mov_b32_e32 v24, 0
	v_mov_b32_e32 v25, 0
	v_mov_b32_e32 v26, 0
	v_mov_b32_e32 v27, 0
	v_mov_b32_e32 v28, 0
	v_mov_b32_e32 v29, 0
	v_mov_b32_e32 v30, 0
	v_mov_b32_e32 v31, 0
	v_mov_b32_e32 v32, 0
	v_mov_b32_e32 v33, 0
	v_mov_b32_e32 v34, 0
	v_mov_b32_e32 v35, 0
	v_mov_b32_e32 v36, 0
	v_mov_b32_e32 v37, 0
	v_mov_b32_e32 v38, 0
	v_mov_b32_e32 v39, 0
	v_mov_b32_e32 v40, 0
	v_mov_b32_e32 v41, 0
	v_mov_b32_e32 v42, 0
	v_mov_b32_e32 v43, 0
	v_mov_b32_e32 v44, 0
	v_mov_b32_e32 v45, 0
	v_mov_b32_e32 v46, 0
	v_mov_b32_e32 v47, 0
	v_mov_b32_e32 v48, 0
	v_mov_b32_e32 v49, 0
	v_mov_b32_e32 v50, 0
	v_mov_b32_e32 v51, 0
	v_mov_b32_e32 v52, 0
	v_mov_b32_e32 v53, 0
	v_mov_b32_e32 v54, 0
	v_mov_b32_e32 v55, 0
	v_mov_b32_e32 v56, 0
	v_mov_b32_e32 v57, 0
	v_mov_b32_e32 v58, 0
	v_mov_b32_e32 v59, 0
	v_mov_b32_e32 v60, 0
	v_mov_b32_e32 v61, 0
	v_mov_b32_e32 v62, 0
	v_mov_b32_e32 v63, 0
	v_mov_b32_e32 v64, 0
	v_mov_b32_e32 v65, 0
	v_mov_b32_e32 v66, 0
	v_mov_b32_e32 v67, 0
	v_mov_b32_e32 v68, 0
	v_mov_b32_e32 v69, 0
	v_mov_b32_e32 v70, 0
	v_mov_b32_e32 v71, 0
	v_mov_b32_e32 v72, 0
	v_mov_b32_e32 v73, 0
	v_mov_b32_e32 v74, 0
	v_mov_b32_e32 v75, 0
	v_mov_b32_e32 v76, 0
	v_mov_b32_e32 v77, 0
	v_mov_b32_e32 v78, 0
	v_mov_b32_e32 v79, 0
	v_mov_b32_e32 v80, 0
	v_mov_b32_e32 v81, 0
	v_mov_b32_e32 v82, 0
	v_mov_b32_e32 v83, 0
	v_mov_b32_e32 v84, 0
	v_mov_b32_e32 v85, 0
	v_mov_b32_e32 v86, 0
	v_mov_b32_e32 v87, 0
	v_mov_b32_e32 v88, 0
	v_mov_b32_e32 v89, 0
	v_mov_b32_e32 v90, 0
	v_mov_b32_e32 v91, 0
	v_mov_b32_e32 v92, 0
	v_mov_b32_e32 v93, 0
	v_mov_b32_e32 v94, 0
	v_mov_b32_e32 v95, 0
	v_mov_b32_e32 v96, 0
	v_mov_b32_e32 v97, 0
	v_mov_b32_e32 v98, 0
	v_mov_b32_e32 v99, 0
	v_mov_b32_e32 v100, 0
	v_mov_b32_e32 v101, 0
	v_mov_b32_e32 v102, 0
	v_mov_b32_e32 v103, 0
	v_mov_b32_e32 v104, 0
	v_mov_b32_e32 v105, 0
	v_mov_b32_e32 v106, 0
	v_mov_b32_e32 v107, 0
	v_mov_b32_e32 v108, 0
	v_mov_b32_e32 v109, 0
	v_mov_b32_e32 v110, 0
	v_mov_b32_e32 v111, 0
	v_mov_b32_e32 v112, 0
	v_mov_b32_e32 v113, 0
	v_mov_b32_e32 v114, 0
	v_mov_b32_e32 v115, 0
	v_mov_b32_e32 v116, 0
	v_mov_b32_e32 v117, 0
	v_mov_b32_e32 v118, 0
	v_mov_b32_e32 v119, 0
	v_mov_b32_e32 v120, 0
	v_mov_b32_e32 v121, 0
	v_mov_b32_e32 v122, 0
	v_mov_b32_e32 v123, 0
	v_mov_b32_e32 v124, 0
	v_mov_b32_e32 v125, 0
	v_mov_b32_e32 v126, 0
	v_mov_b32_e32 v127, 0
	v_mov_b32_e32 v128, 0
	v_mov_b32_e32 v129, 0
	v_mov_b32_e32 v130, 0
	v_mov_b32_e32 v131, 0
	v_mov_b32_e32 v132, 0
	v_mov_b32_e32 v133, 0
	v_mov_b32_e32 v134, 0
	v_mov_b32_e32 v135, 0
	s_add_u32 s4, s56, 0x0
	s_addc_u32 s5, s57, 0
	s_add_u32 m0, s62, 0x0
	s_nop 0
	global_load_lds_dwordx4 v162, s[4:5]
	s_add_u32 s4, s56, 0x10000
	s_addc_u32 s5, s57, 0
	s_add_u32 m0, s62, 0x1000
	s_nop 0
	global_load_lds_dwordx4 v162, s[4:5]
	s_add_u32 s4, s56, 0x20000
	s_addc_u32 s5, s57, 0
	s_add_u32 m0, s62, 0x2000
	s_nop 0
	global_load_lds_dwordx4 v162, s[4:5]
	s_add_u32 s4, s56, 0x30000
	s_addc_u32 s5, s57, 0
	s_add_u32 m0, s62, 0x3000
	s_nop 0
	global_load_lds_dwordx4 v162, s[4:5]
	s_add_u32 s4, s56, 0x40000
	s_addc_u32 s5, s57, 0
	s_add_u32 m0, s62, 0x4000
	s_nop 0
	global_load_lds_dwordx4 v162, s[4:5]
	s_add_u32 s4, s56, 0x50000
	s_addc_u32 s5, s57, 0
	s_add_u32 m0, s62, 0x5000
	s_nop 0
	global_load_lds_dwordx4 v162, s[4:5]
	s_add_u32 s4, s56, 0x60000
	s_addc_u32 s5, s57, 0
	s_add_u32 m0, s62, 0x6000
	s_nop 0
	global_load_lds_dwordx4 v162, s[4:5]
	s_add_u32 s4, s56, 0x70000
	s_addc_u32 s5, s57, 0
	s_add_u32 m0, s62, 0x7000
	s_nop 0
	global_load_lds_dwordx4 v162, s[4:5]
	s_cmp_gt_u32 s70, 1
	s_cbranch_scc1 .Lg2_out_nodma_0
	s_add_u32 s4, s56, 0x80000
	s_addc_u32 s5, s57, 0
	s_add_u32 m0, s62, 0x8000
	s_nop 0
	global_load_lds_dwordx4 v162, s[4:5]

.Lg2_win_entry:
	s_waitcnt vmcnt(0) lgkmcnt(0)
	s_barrier
	v_mov_b32_e32 v2, 0x10200
	ds_read_b64 v[2:3], v2
	v_readlane_b32 s0, v246, 0
	v_lshrrev_b32_e32 v4, 6, v163
	v_and_b32_e32 v5, 63, v163
	s_and_b32 s1, s0, 7
	s_lshr_b32 s0, s0, 3
	s_lshr_b32 s68, s0, 3
	s_and_b32 s0, s0, 7
	s_lshl_b32 s0, s0, 3
	s_add_i32 s0, s0, s1
	s_cmp_lt_u32 s0, 32
	s_cselect_b32 s43, 1, 0
	s_min_u32 s1, s0, 32
	s_lshl_b32 s0, s0, 4
	s_add_i32 s0, s0, s1
	s_lshl_b32 s42, s0, 4
	v_readfirstlane_b32 s70, v4
	v_and_b32_e32 v6, 15, v5
	v_lshrrev_b32_e32 v7, 4, v5
	s_waitcnt lgkmcnt(0)
	v_readfirstlane_b32 s66, v2
	v_readfirstlane_b32 s67, v3
	s_lshl_b32 s62, s70, 10
	v_and_b32_e32 v8, 7, v6
	v_xor_b32_e32 v9, v7, v8
	v_lshlrev_b32_e32 v9, 4, v9
	v_lshl_add_u32 v156, v6, 7, v9
	v_add_u32_e32 v10, 4, v7
	v_xor_b32_e32 v10, v10, v8
	v_lshlrev_b32_e32 v10, 4, v10
	v_lshl_add_u32 v157, v6, 7, v10
	v_add_u32_e32 v158, 0x8800, v156
	v_add_u32_e32 v159, 0x8800, v157
	v_lshrrev_b32_e32 v11, 3, v163
	v_and_b32_e32 v12, 7, v163
	v_and_b32_e32 v13, 7, v11
	v_xor_b32_e32 v12, v12, v13
	v_lshlrev_b32_e32 v12, 4, v12
	s_mov_b32 s2, 0x800
	v_mul_lo_u32 v11, v11, s2
	v_add_u32_e32 v162, v11, v12
	v_lshrrev_b32_e32 v11, 4, v163
	v_and_b32_e32 v12, 15, v163
	v_xor_b32_e32 v13, v12, v11
	v_lshlrev_b32_e32 v13, 4, v13
	v_lshl_add_u32 v247, v11, 8, v13
	s_mov_b32 s2, 0x3900
	v_mul_lo_u32 v11, v11, s2
	v_lshl_add_u32 v252, v12, 4, v11
	v_add_u32_e32 v255, 0x8000, v247
	v_lshrrev_b32_e32 v11, 1, v4
	v_and_b32_e32 v12, 1, v4
	v_lshl_add_u32 v11, v11, 2, v12
	s_mov_b32 s2, 0x8000
	v_mul_lo_u32 v12, v11, s2
	v_lshl_add_u32 v160, v5, 4, v12
	v_add_u32_e32 v161, 0x10000, v160
	v_lshrrev_b32_e32 v12, 1, v7
	v_lshl_add_u32 v12, v11, 1, v12
	v_and_b32_e32 v13, 1, v7
	v_lshlrev_b32_e32 v13, 3, v13
	v_lshl_add_u32 v14, v6, 8, v13
	v_xor_b32_e32 v15, v12, v6
	v_lshlrev_b32_e32 v15, 4, v15
	v_add_u32_e32 v212, v14, v15
	v_add_u32_e32 v12, 4, v12
	v_xor_b32_e32 v15, v12, v6
	v_lshlrev_b32_e32 v15, 4, v15
	v_add_u32_e32 v213, v14, v15
	v_add_u32_e32 v253, 0x8000, v212
	v_add_u32_e32 v254, 0x8000, v213
	s_mov_b32 s64, 0
.Lg2_win_tile:
	s_lshl_b32 s0, s64, 3
	s_add_i32 s38, s0, s68
	s_mov_b32 s69, s42
	s_mov_b32 s65, s43
	s_lshl_b32 s0, s38, 7
	s_mul_i32 s2, s69, 0x800
	s_mul_hi_u32 s3, s69, 0x800
	s_add_u32 s56, s26, s2
	s_addc_u32 s57, s27, s3
	s_add_u32 s56, s56, 0x11140000
	s_addc_u32 s57, s57, 0
	s_mul_i32 s2, s0, 0x800
	s_mul_hi_u32 s3, s0, 0x800
	s_add_u32 s58, s26, s2
	s_addc_u32 s59, s27, s3
	s_add_u32 s58, s58, 0xeb20000
	s_addc_u32 s59, s59, 0
	s_mul_i32 s2, s69, 0x3900
	s_mul_hi_u32 s3, s69, 0x3900
	s_lshl_b32 s0, s0, 1
	s_add_u32 s2, s2, s0
	s_addc_u32 s3, s3, 0
	s_add_u32 s60, s26, s2
	s_addc_u32 s61, s27, s3
	s_add_u32 s60, s60, 0x0
	s_addc_u32 s61, s61, 0
	s_cmp_eq_u32 s65, 0
	s_cbranch_scc1 .Lg2_win_k16
	v_mov_b32_e32 v0, 0
	v_mov_b32_e32 v1, 0
	v_mov_b32_e32 v2, 0
	v_mov_b32_e32 v3, 0
	v_mov_b32_e32 v4, 0
	v_mov_b32_e32 v5, 0
	v_mov_b32_e32 v6, 0
	v_mov_b32_e32 v7, 0
	v_mov_b32_e32 v8, 0
	v_mov_b32_e32 v9, 0
	v_mov_b32_e32 v10, 0
	v_mov_b32_e32 v11, 0
	v_mov_b32_e32 v12, 0
	v_mov_b32_e32 v13, 0
	v_mov_b32_e32 v14, 0
	v_mov_b32_e32 v15, 0
	v_mov_b32_e32 v16, 0
	v_mov_b32_e32 v17, 0
	v_mov_b32_e32 v18, 0
	v_mov_b32_e32 v19, 0
	v_mov_b32_e32 v20, 0
	v_mov_b32_e32 v21, 0
	v_mov_b32_e32 v22, 0
	v_mov_b32_e32 v23, 0
	v_mov_b32_e32 v24, 0
	v_mov_b32_e32 v25, 0
	v_mov_b32_e32 v26, 0
	v_mov_b32_e32 v27, 0
	v_mov_b32_e32 v28, 0
	v_mov_b32_e32 v29, 0
	v_mov_b32_e32 v30, 0
	v_mov_b32_e32 v31, 0
	v_mov_b32_e32 v32, 0
	v_mov_b32_e32 v33, 0
	v_mov_b32_e32 v34, 0
	v_mov_b32_e32 v35, 0
	v_mov_b32_e32 v36, 0
	v_mov_b32_e32 v37, 0
	v_mov_b32_e32 v38, 0
	v_mov_b32_e32 v39, 0
	v_mov_b32_e32 v40, 0
	v_mov_b32_e32 v41, 0
	v_mov_b32_e32 v42, 0
	v_mov_b32_e32 v43, 0
	v_mov_b32_e32 v44, 0
	v_mov_b32_e32 v45, 0
	v_mov_b32_e32 v46, 0
	v_mov_b32_e32 v47, 0
	v_mov_b32_e32 v48, 0
	v_mov_b32_e32 v49, 0
	v_mov_b32_e32 v50, 0
	v_mov_b32_e32 v51, 0
	v_mov_b32_e32 v52, 0
	v_mov_b32_e32 v53, 0
	v_mov_b32_e32 v54, 0
	v_mov_b32_e32 v55, 0
	v_mov_b32_e32 v56, 0
	v_mov_b32_e32 v57, 0
	v_mov_b32_e32 v58, 0
	v_mov_b32_e32 v59, 0
	v_mov_b32_e32 v60, 0
	v_mov_b32_e32 v61, 0
	v_mov_b32_e32 v62, 0
	v_mov_b32_e32 v63, 0
	v_mov_b32_e32 v64, 0
	v_mov_b32_e32 v65, 0
	v_mov_b32_e32 v66, 0
	v_mov_b32_e32 v67, 0
	v_mov_b32_e32 v68, 0
	v_mov_b32_e32 v69, 0
	v_mov_b32_e32 v70, 0
	v_mov_b32_e32 v71, 0
	v_mov_b32_e32 v72, 0
	v_mov_b32_e32 v73, 0
	v_mov_b32_e32 v74, 0
	v_mov_b32_e32 v75, 0
	v_mov_b32_e32 v76, 0
	v_mov_b32_e32 v77, 0
	v_mov_b32_e32 v78, 0
	v_mov_b32_e32 v79, 0
	v_mov_b32_e32 v80, 0
	v_mov_b32_e32 v81, 0
	v_mov_b32_e32 v82, 0
	v_mov_b32_e32 v83, 0
	v_mov_b32_e32 v84, 0
	v_mov_b32_e32 v85, 0
	v_mov_b32_e32 v86, 0
	v_mov_b32_e32 v87, 0
	v_mov_b32_e32 v88, 0
	v_mov_b32_e32 v89, 0
	v_mov_b32_e32 v90, 0
	v_mov_b32_e32 v91, 0
	v_mov_b32_e32 v92, 0
	v_mov_b32_e32 v93, 0
	v_mov_b32_e32 v94, 0
	v_mov_b32_e32 v95, 0
	v_mov_b32_e32 v96, 0
	v_mov_b32_e32 v97, 0
	v_mov_b32_e32 v98, 0
	v_mov_b32_e32 v99, 0
	v_mov_b32_e32 v100, 0
	v_mov_b32_e32 v101, 0
	v_mov_b32_e32 v102, 0
	v_mov_b32_e32 v103, 0
	v_mov_b32_e32 v104, 0
	v_mov_b32_e32 v105, 0
	v_mov_b32_e32 v106, 0
	v_mov_b32_e32 v107, 0
	v_mov_b32_e32 v108, 0
	v_mov_b32_e32 v109, 0
	v_mov_b32_e32 v110, 0
	v_mov_b32_e32 v111, 0
	v_mov_b32_e32 v112, 0
	v_mov_b32_e32 v113, 0
	v_mov_b32_e32 v114, 0
	v_mov_b32_e32 v115, 0
	v_mov_b32_e32 v116, 0
	v_mov_b32_e32 v117, 0
	v_mov_b32_e32 v118, 0
	v_mov_b32_e32 v119, 0
	v_mov_b32_e32 v120, 0
	v_mov_b32_e32 v121, 0
	v_mov_b32_e32 v122, 0
	v_mov_b32_e32 v123, 0
	v_mov_b32_e32 v124, 0
	v_mov_b32_e32 v125, 0
	v_mov_b32_e32 v126, 0
	v_mov_b32_e32 v127, 0
	v_mov_b32_e32 v128, 0
	v_mov_b32_e32 v129, 0
	v_mov_b32_e32 v130, 0
	v_mov_b32_e32 v131, 0
	v_mov_b32_e32 v132, 0
	v_mov_b32_e32 v133, 0
	v_mov_b32_e32 v134, 0
	v_mov_b32_e32 v135, 0
	s_add_u32 s4, s56, 0x0
	s_addc_u32 s5, s57, 0
	s_add_u32 m0, s62, 0x0
	s_nop 0
	global_load_lds_dwordx4 v162, s[4:5]
	s_add_u32 s4, s56, 0x10000
	s_addc_u32 s5, s57, 0
	s_add_u32 m0, s62, 0x1000
	s_nop 0
	global_load_lds_dwordx4 v162, s[4:5]
	s_add_u32 s4, s56, 0x20000
	s_addc_u32 s5, s57, 0
	s_add_u32 m0, s62, 0x2000
	s_nop 0
	global_load_lds_dwordx4 v162, s[4:5]
	s_add_u32 s4, s56, 0x30000
	s_addc_u32 s5, s57, 0
	s_add_u32 m0, s62, 0x3000
	s_nop 0
	global_load_lds_dwordx4 v162, s[4:5]
	s_add_u32 s4, s56, 0x40000
	s_addc_u32 s5, s57, 0
	s_add_u32 m0, s62, 0x4000
	s_nop 0
	global_load_lds_dwordx4 v162, s[4:5]
	s_add_u32 s4, s56, 0x50000
	s_addc_u32 s5, s57, 0
	s_add_u32 m0, s62, 0x5000
	s_nop 0
	global_load_lds_dwordx4 v162, s[4:5]
	s_add_u32 s4, s56, 0x60000
	s_addc_u32 s5, s57, 0
	s_add_u32 m0, s62, 0x6000
	s_nop 0
	global_load_lds_dwordx4 v162, s[4:5]
	s_add_u32 s4, s56, 0x70000
	s_addc_u32 s5, s57, 0
	s_add_u32 m0, s62, 0x7000
	s_nop 0
	global_load_lds_dwordx4 v162, s[4:5]
	s_cmp_gt_u32 s70, 1
	s_cbranch_scc1 .Lg2_win_nodma_0
	s_add_u32 s4, s56, 0x80000
	s_addc_u32 s5, s57, 0
	s_add_u32 m0, s62, 0x8000
	s_nop 0
	global_load_lds_dwordx4 v162, s[4:5]

.Lg2_win_episel:
	s_cmp_lt_u32 s38, 4
	s_cbranch_scc1 .Lg2_win_epiR_pre
	s_sub_u32 s0, s38, 16
	s_cmp_lt_u32 s0, 4
	s_cbranch_scc1 .Lg2_win_epiS
	s_branch .Lg2_win_epiP
.Lg2_win_epiR_pre:
	s_and_b32 s0, s70, 1
	s_cmp_eq_u32 s0, 0
	s_cselect_b32 s39, 6, 0
	s_cselect_b32 s40, 0x7f, 0x3f
	s_cmp_lt_u32 s38, 2
	s_cselect_b32 s41, 1.0, 0x3e000000
.Lg2_win_epiR:
	s_nop 7
	s_nop 7
	s_barrier
	v_and_b32_e32 v148, 15, v163
	v_bfe_u32 v149, v163, 4, 2
	v_cmp_gt_u32_e32 vcc, 2, v149
	s_nop 1
	v_cndmask_b32_e64 v150, 0, 1, vcc
	v_lshlrev_b32_e32 v149, 4, v149
	s_add_u32 s2, s26, 0x19dc8000
	s_addc_u32 s3, s27, 0
	s_add_u32 s4, s26, 0x19dca000
	s_addc_u32 s5, s27, 0
	s_add_i32 s0, s69, 0
	v_add_u32_e32 v140, s0, v148
	v_subrev_u32_e32 v141, 0x2100, v140
	v_cmp_gt_u32_e32 vcc, 0x2100, v140
	s_nop 1
	v_cndmask_b32_e32 v141, v141, v140, vcc
	v_subrev_u32_e32 v142, 0x100, v141
	v_lshrrev_b32_e32 v143, s39, v142
	v_and_b32_e32 v143, s40, v143
	v_cmp_le_u32_e32 vcc, 0x100, v141
	s_nop 1
	v_cndmask_b32_e32 v143, 0, v143, vcc
	v_lshl_add_u32 v151, v143, 6, v149
	global_load_dwordx4 v[164:167], v151, s[2:3]
	global_load_dwordx4 v[168:171], v151, s[4:5]
	s_add_i32 s0, s69, 16
	v_add_u32_e32 v140, s0, v148
	v_subrev_u32_e32 v141, 0x2100, v140
	v_cmp_gt_u32_e32 vcc, 0x2100, v140
	s_nop 1
	v_cndmask_b32_e32 v141, v141, v140, vcc
	v_subrev_u32_e32 v142, 0x100, v141
	v_lshrrev_b32_e32 v143, s39, v142
	v_and_b32_e32 v143, s40, v143
	v_cmp_le_u32_e32 vcc, 0x100, v141
	s_nop 1
	v_cndmask_b32_e32 v143, 0, v143, vcc
	v_lshl_add_u32 v151, v143, 6, v149
	global_load_dwordx4 v[172:175], v151, s[2:3]
	global_load_dwordx4 v[176:179], v151, s[4:5]
	s_waitcnt vmcnt(2)
	v_mul_f32_e32 v152, v4, v168
	v_mul_f32_e32 v153, v4, v164
	v_fma_f32 v4, v0, v168, v153
	v_fma_f32 v0, v0, v164, -v152
	v_mul_f32_e32 v152, v5, v169
	v_mul_f32_e32 v153, v5, v165
	v_fma_f32 v5, v1, v169, v153
	v_fma_f32 v1, v1, v165, -v152
	v_mul_f32_e32 v152, v6, v170
	v_mul_f32_e32 v153, v6, v166
	v_fma_f32 v6, v2, v170, v153
	v_fma_f32 v2, v2, v166, -v152
	v_mul_f32_e32 v152, v7, v171
	v_mul_f32_e32 v153, v7, v167
	v_fma_f32 v7, v3, v171, v153
	v_fma_f32 v3, v3, v167, -v152
	v_mul_f32_e32 v0, s41, v0
	v_mul_f32_e32 v4, s41, v4
	v_mul_f32_e32 v1, s41, v1
	v_mul_f32_e32 v5, s41, v5
	v_mul_f32_e32 v2, s41, v2
	v_mul_f32_e32 v6, s41, v6
	v_mul_f32_e32 v3, s41, v3
	v_mul_f32_e32 v7, s41, v7
	v_cvt_pk_bf16_f32 v0, v0, v1
	v_cvt_pk_bf16_f32 v1, v2, v3
	ds_write_b64 v212, v[0:1] offset:0
	v_cvt_pk_bf16_f32 v4, v4, v5
	v_cvt_pk_bf16_f32 v5, v6, v7
	ds_write_b64 v213, v[4:5] offset:0
	s_add_i32 s0, s69, 32
	v_add_u32_e32 v140, s0, v148
	v_subrev_u32_e32 v141, 0x2100, v140
	v_cmp_gt_u32_e32 vcc, 0x2100, v140
	s_nop 1
	v_cndmask_b32_e32 v141, v141, v140, vcc
	v_subrev_u32_e32 v142, 0x100, v141
	v_lshrrev_b32_e32 v143, s39, v142
	v_and_b32_e32 v143, s40, v143
	v_cmp_le_u32_e32 vcc, 0x100, v141
	s_nop 1
	v_cndmask_b32_e32 v143, 0, v143, vcc
	v_lshl_add_u32 v151, v143, 6, v149
	global_load_dwordx4 v[164:167], v151, s[2:3]
	global_load_dwordx4 v[168:171], v151, s[4:5]
	s_waitcnt vmcnt(2)
	v_mul_f32_e32 v152, v12, v176
	v_mul_f32_e32 v153, v12, v172
	v_fma_f32 v12, v8, v176, v153
	v_fma_f32 v8, v8, v172, -v152
	v_mul_f32_e32 v152, v13, v177
	v_mul_f32_e32 v153, v13, v173
	v_fma_f32 v13, v9, v177, v153
	v_fma_f32 v9, v9, v173, -v152
	v_mul_f32_e32 v152, v14, v178
	v_mul_f32_e32 v153, v14, v174
	v_fma_f32 v14, v10, v178, v153
	v_fma_f32 v10, v10, v174, -v152
	v_mul_f32_e32 v152, v15, v179
	v_mul_f32_e32 v153, v15, v175
	v_fma_f32 v15, v11, v179, v153
	v_fma_f32 v11, v11, v175, -v152
	v_mul_f32_e32 v8, s41, v8
	v_mul_f32_e32 v12, s41, v12
	v_mul_f32_e32 v9, s41, v9
	v_mul_f32_e32 v13, s41, v13
	v_mul_f32_e32 v10, s41, v10
	v_mul_f32_e32 v14, s41, v14
	v_mul_f32_e32 v11, s41, v11
	v_mul_f32_e32 v15, s41, v15
	v_cvt_pk_bf16_f32 v8, v8, v9
	v_cvt_pk_bf16_f32 v9, v10, v11
	ds_write_b64 v212, v[8:9] offset:4096
	v_cvt_pk_bf16_f32 v12, v12, v13
	v_cvt_pk_bf16_f32 v13, v14, v15
	ds_write_b64 v213, v[12:13] offset:4096
	s_add_i32 s0, s69, 48
	v_add_u32_e32 v140, s0, v148
	v_subrev_u32_e32 v141, 0x2100, v140
	v_cmp_gt_u32_e32 vcc, 0x2100, v140
	s_nop 1
	v_cndmask_b32_e32 v141, v141, v140, vcc
	v_subrev_u32_e32 v142, 0x100, v141
	v_lshrrev_b32_e32 v143, s39, v142
	v_and_b32_e32 v143, s40, v143
	v_cmp_le_u32_e32 vcc, 0x100, v141
	s_nop 1
	v_cndmask_b32_e32 v143, 0, v143, vcc
	v_lshl_add_u32 v151, v143, 6, v149
	global_load_dwordx4 v[172:175], v151, s[2:3]
	global_load_dwordx4 v[176:179], v151, s[4:5]
	s_waitcnt vmcnt(2)
	v_mul_f32_e32 v152, v20, v168
	v_mul_f32_e32 v153, v20, v164
	v_fma_f32 v20, v16, v168, v153
	v_fma_f32 v16, v16, v164, -v152
	v_mul_f32_e32 v152, v21, v169
	v_mul_f32_e32 v153, v21, v165
	v_fma_f32 v21, v17, v169, v153
	v_fma_f32 v17, v17, v165, -v152
	v_mul_f32_e32 v152, v22, v170
	v_mul_f32_e32 v153, v22, v166
	v_fma_f32 v22, v18, v170, v153
	v_fma_f32 v18, v18, v166, -v152
	v_mul_f32_e32 v152, v23, v171
	v_mul_f32_e32 v153, v23, v167
	v_fma_f32 v23, v19, v171, v153
	v_fma_f32 v19, v19, v167, -v152
	v_mul_f32_e32 v16, s41, v16
	v_mul_f32_e32 v20, s41, v20
	v_mul_f32_e32 v17, s41, v17
	v_mul_f32_e32 v21, s41, v21
	v_mul_f32_e32 v18, s41, v18
	v_mul_f32_e32 v22, s41, v22
	v_mul_f32_e32 v19, s41, v19
	v_mul_f32_e32 v23, s41, v23
	v_cvt_pk_bf16_f32 v16, v16, v17
	v_cvt_pk_bf16_f32 v17, v18, v19
	ds_write_b64 v212, v[16:17] offset:8192
	v_cvt_pk_bf16_f32 v20, v20, v21
	v_cvt_pk_bf16_f32 v21, v22, v23
	ds_write_b64 v213, v[20:21] offset:8192
	s_add_i32 s0, s69, 64
	v_add_u32_e32 v140, s0, v148
	v_subrev_u32_e32 v141, 0x2100, v140
	v_cmp_gt_u32_e32 vcc, 0x2100, v140
	s_nop 1
	v_cndmask_b32_e32 v141, v141, v140, vcc
	v_subrev_u32_e32 v142, 0x100, v141
	v_lshrrev_b32_e32 v143, s39, v142
	v_and_b32_e32 v143, s40, v143
	v_cmp_le_u32_e32 vcc, 0x100, v141
	s_nop 1
	v_cndmask_b32_e32 v143, 0, v143, vcc
	v_lshl_add_u32 v151, v143, 6, v149
	global_load_dwordx4 v[164:167], v151, s[2:3]
	global_load_dwordx4 v[168:171], v151, s[4:5]
	s_waitcnt vmcnt(2)
	v_mul_f32_e32 v152, v28, v176
	v_mul_f32_e32 v153, v28, v172
	v_fma_f32 v28, v24, v176, v153
	v_fma_f32 v24, v24, v172, -v152
	v_mul_f32_e32 v152, v29, v177
	v_mul_f32_e32 v153, v29, v173
	v_fma_f32 v29, v25, v177, v153
	v_fma_f32 v25, v25, v173, -v152
	v_mul_f32_e32 v152, v30, v178
	v_mul_f32_e32 v153, v30, v174
	v_fma_f32 v30, v26, v178, v153
	v_fma_f32 v26, v26, v174, -v152
	v_mul_f32_e32 v152, v31, v179
	v_mul_f32_e32 v153, v31, v175
	v_fma_f32 v31, v27, v179, v153
	v_fma_f32 v27, v27, v175, -v152
	v_mul_f32_e32 v24, s41, v24
	v_mul_f32_e32 v28, s41, v28
	v_mul_f32_e32 v25, s41, v25
	v_mul_f32_e32 v29, s41, v29
	v_mul_f32_e32 v26, s41, v26
	v_mul_f32_e32 v30, s41, v30
	v_mul_f32_e32 v27, s41, v27
	v_mul_f32_e32 v31, s41, v31
	v_cvt_pk_bf16_f32 v24, v24, v25
	v_cvt_pk_bf16_f32 v25, v26, v27
	ds_write_b64 v212, v[24:25] offset:12288
	v_cvt_pk_bf16_f32 v28, v28, v29
	v_cvt_pk_bf16_f32 v29, v30, v31
	ds_write_b64 v213, v[28:29] offset:12288
	s_add_i32 s0, s69, 80
	v_add_u32_e32 v140, s0, v148
	v_subrev_u32_e32 v141, 0x2100, v140
	v_cmp_gt_u32_e32 vcc, 0x2100, v140
	s_nop 1
	v_cndmask_b32_e32 v141, v141, v140, vcc
	v_subrev_u32_e32 v142, 0x100, v141
	v_lshrrev_b32_e32 v143, s39, v142
	v_and_b32_e32 v143, s40, v143
	v_cmp_le_u32_e32 vcc, 0x100, v141
	s_nop 1
	v_cndmask_b32_e32 v143, 0, v143, vcc
	v_lshl_add_u32 v151, v143, 6, v149
	global_load_dwordx4 v[172:175], v151, s[2:3]
	global_load_dwordx4 v[176:179], v151, s[4:5]
	s_waitcnt vmcnt(2)
	v_mul_f32_e32 v152, v36, v168
	v_mul_f32_e32 v153, v36, v164
	v_fma_f32 v36, v32, v168, v153
	v_fma_f32 v32, v32, v164, -v152
	v_mul_f32_e32 v152, v37, v169
	v_mul_f32_e32 v153, v37, v165
	v_fma_f32 v37, v33, v169, v153
	v_fma_f32 v33, v33, v165, -v152
	v_mul_f32_e32 v152, v38, v170
	v_mul_f32_e32 v153, v38, v166
	v_fma_f32 v38, v34, v170, v153
	v_fma_f32 v34, v34, v166, -v152
	v_mul_f32_e32 v152, v39, v171
	v_mul_f32_e32 v153, v39, v167
	v_fma_f32 v39, v35, v171, v153
	v_fma_f32 v35, v35, v167, -v152
	v_mul_f32_e32 v32, s41, v32
	v_mul_f32_e32 v36, s41, v36
	v_mul_f32_e32 v33, s41, v33
	v_mul_f32_e32 v37, s41, v37
	v_mul_f32_e32 v34, s41, v34
	v_mul_f32_e32 v38, s41, v38
	v_mul_f32_e32 v35, s41, v35
	v_mul_f32_e32 v39, s41, v39
	v_cvt_pk_bf16_f32 v32, v32, v33
	v_cvt_pk_bf16_f32 v33, v34, v35
	ds_write_b64 v212, v[32:33] offset:16384
	v_cvt_pk_bf16_f32 v36, v36, v37
	v_cvt_pk_bf16_f32 v37, v38, v39
	ds_write_b64 v213, v[36:37] offset:16384
	s_add_i32 s0, s69, 96
	v_add_u32_e32 v140, s0, v148
	v_subrev_u32_e32 v141, 0x2100, v140
	v_cmp_gt_u32_e32 vcc, 0x2100, v140
	s_nop 1
	v_cndmask_b32_e32 v141, v141, v140, vcc
	v_subrev_u32_e32 v142, 0x100, v141
	v_lshrrev_b32_e32 v143, s39, v142
	v_and_b32_e32 v143, s40, v143
	v_cmp_le_u32_e32 vcc, 0x100, v141
	s_nop 1
	v_cndmask_b32_e32 v143, 0, v143, vcc
	v_lshl_add_u32 v151, v143, 6, v149
	global_load_dwordx4 v[164:167], v151, s[2:3]
	global_load_dwordx4 v[168:171], v151, s[4:5]
	s_waitcnt vmcnt(2)
	v_mul_f32_e32 v152, v44, v176
	v_mul_f32_e32 v153, v44, v172
	v_fma_f32 v44, v40, v176, v153
	v_fma_f32 v40, v40, v172, -v152
	v_mul_f32_e32 v152, v45, v177
	v_mul_f32_e32 v153, v45, v173
	v_fma_f32 v45, v41, v177, v153
	v_fma_f32 v41, v41, v173, -v152
	v_mul_f32_e32 v152, v46, v178
	v_mul_f32_e32 v153, v46, v174
	v_fma_f32 v46, v42, v178, v153
	v_fma_f32 v42, v42, v174, -v152
	v_mul_f32_e32 v152, v47, v179
	v_mul_f32_e32 v153, v47, v175
	v_fma_f32 v47, v43, v179, v153
	v_fma_f32 v43, v43, v175, -v152
	v_mul_f32_e32 v40, s41, v40
	v_mul_f32_e32 v44, s41, v44
	v_mul_f32_e32 v41, s41, v41
	v_mul_f32_e32 v45, s41, v45
	v_mul_f32_e32 v42, s41, v42
	v_mul_f32_e32 v46, s41, v46
	v_mul_f32_e32 v43, s41, v43
	v_mul_f32_e32 v47, s41, v47
	v_cvt_pk_bf16_f32 v40, v40, v41
	v_cvt_pk_bf16_f32 v41, v42, v43
	ds_write_b64 v212, v[40:41] offset:20480
	v_cvt_pk_bf16_f32 v44, v44, v45
	v_cvt_pk_bf16_f32 v45, v46, v47
	ds_write_b64 v213, v[44:45] offset:20480
	s_add_i32 s0, s69, 112
	v_add_u32_e32 v140, s0, v148
	v_subrev_u32_e32 v141, 0x2100, v140
	v_cmp_gt_u32_e32 vcc, 0x2100, v140
	s_nop 1
	v_cndmask_b32_e32 v141, v141, v140, vcc
	v_subrev_u32_e32 v142, 0x100, v141
	v_lshrrev_b32_e32 v143, s39, v142
	v_and_b32_e32 v143, s40, v143
	v_cmp_le_u32_e32 vcc, 0x100, v141
	s_nop 1
	v_cndmask_b32_e32 v143, 0, v143, vcc
	v_lshl_add_u32 v151, v143, 6, v149
	global_load_dwordx4 v[172:175], v151, s[2:3]
	global_load_dwordx4 v[176:179], v151, s[4:5]
	s_waitcnt vmcnt(2)
	v_mul_f32_e32 v152, v52, v168
	v_mul_f32_e32 v153, v52, v164
	v_fma_f32 v52, v48, v168, v153
	v_fma_f32 v48, v48, v164, -v152
	v_mul_f32_e32 v152, v53, v169
	v_mul_f32_e32 v153, v53, v165
	v_fma_f32 v53, v49, v169, v153
	v_fma_f32 v49, v49, v165, -v152
	v_mul_f32_e32 v152, v54, v170
	v_mul_f32_e32 v153, v54, v166
	v_fma_f32 v54, v50, v170, v153
	v_fma_f32 v50, v50, v166, -v152
	v_mul_f32_e32 v152, v55, v171
	v_mul_f32_e32 v153, v55, v167
	v_fma_f32 v55, v51, v171, v153
	v_fma_f32 v51, v51, v167, -v152
	v_mul_f32_e32 v48, s41, v48
	v_mul_f32_e32 v52, s41, v52
	v_mul_f32_e32 v49, s41, v49
	v_mul_f32_e32 v53, s41, v53
	v_mul_f32_e32 v50, s41, v50
	v_mul_f32_e32 v54, s41, v54
	v_mul_f32_e32 v51, s41, v51
	v_mul_f32_e32 v55, s41, v55
	v_cvt_pk_bf16_f32 v48, v48, v49
	v_cvt_pk_bf16_f32 v49, v50, v51
	ds_write_b64 v212, v[48:49] offset:24576
	v_cvt_pk_bf16_f32 v52, v52, v53
	v_cvt_pk_bf16_f32 v53, v54, v55
	ds_write_b64 v213, v[52:53] offset:24576
	s_add_i32 s0, s69, 128
	v_add_u32_e32 v140, s0, v148
	v_subrev_u32_e32 v141, 0x2100, v140
	v_cmp_gt_u32_e32 vcc, 0x2100, v140
	s_nop 1
	v_cndmask_b32_e32 v141, v141, v140, vcc
	v_subrev_u32_e32 v142, 0x100, v141
	v_lshrrev_b32_e32 v143, s39, v142
	v_and_b32_e32 v143, s40, v143
	v_cmp_le_u32_e32 vcc, 0x100, v141
	s_nop 1
	v_cndmask_b32_e32 v143, 0, v143, vcc
	v_lshl_add_u32 v151, v143, 6, v149
	global_load_dwordx4 v[164:167], v151, s[2:3]
	global_load_dwordx4 v[168:171], v151, s[4:5]
	s_waitcnt vmcnt(2)
	v_mul_f32_e32 v152, v60, v176
	v_mul_f32_e32 v153, v60, v172
	v_fma_f32 v60, v56, v176, v153
	v_fma_f32 v56, v56, v172, -v152
	v_mul_f32_e32 v152, v61, v177
	v_mul_f32_e32 v153, v61, v173
	v_fma_f32 v61, v57, v177, v153
	v_fma_f32 v57, v57, v173, -v152
	v_mul_f32_e32 v152, v62, v178
	v_mul_f32_e32 v153, v62, v174
	v_fma_f32 v62, v58, v178, v153
	v_fma_f32 v58, v58, v174, -v152
	v_mul_f32_e32 v152, v63, v179
	v_mul_f32_e32 v153, v63, v175
	v_fma_f32 v63, v59, v179, v153
	v_fma_f32 v59, v59, v175, -v152
	v_mul_f32_e32 v56, s41, v56
	v_mul_f32_e32 v60, s41, v60
	v_mul_f32_e32 v57, s41, v57
	v_mul_f32_e32 v61, s41, v61
	v_mul_f32_e32 v58, s41, v58
	v_mul_f32_e32 v62, s41, v62
	v_mul_f32_e32 v59, s41, v59
	v_mul_f32_e32 v63, s41, v63
	v_cvt_pk_bf16_f32 v56, v56, v57
	v_cvt_pk_bf16_f32 v57, v58, v59
	ds_write_b64 v212, v[56:57] offset:28672
	v_cvt_pk_bf16_f32 v60, v60, v61
	v_cvt_pk_bf16_f32 v61, v62, v63
	ds_write_b64 v213, v[60:61] offset:28672
	s_add_i32 s0, s69, 144
	v_add_u32_e32 v140, s0, v148
	v_subrev_u32_e32 v141, 0x2100, v140
	v_cmp_gt_u32_e32 vcc, 0x2100, v140
	s_nop 1
	v_cndmask_b32_e32 v141, v141, v140, vcc
	v_subrev_u32_e32 v142, 0x100, v141
	v_lshrrev_b32_e32 v143, s39, v142
	v_and_b32_e32 v143, s40, v143
	v_cmp_le_u32_e32 vcc, 0x100, v141
	s_nop 1
	v_cndmask_b32_e32 v143, 0, v143, vcc
	v_lshl_add_u32 v151, v143, 6, v149
	global_load_dwordx4 v[172:175], v151, s[2:3]
	global_load_dwordx4 v[176:179], v151, s[4:5]
	s_waitcnt vmcnt(2)
	v_mul_f32_e32 v152, v68, v168
	v_mul_f32_e32 v153, v68, v164
	v_fma_f32 v68, v64, v168, v153
	v_fma_f32 v64, v64, v164, -v152
	v_mul_f32_e32 v152, v69, v169
	v_mul_f32_e32 v153, v69, v165
	v_fma_f32 v69, v65, v169, v153
	v_fma_f32 v65, v65, v165, -v152
	v_mul_f32_e32 v152, v70, v170
	v_mul_f32_e32 v153, v70, v166
	v_fma_f32 v70, v66, v170, v153
	v_fma_f32 v66, v66, v166, -v152
	v_mul_f32_e32 v152, v71, v171
	v_mul_f32_e32 v153, v71, v167
	v_fma_f32 v71, v67, v171, v153
	v_fma_f32 v67, v67, v167, -v152
	v_mul_f32_e32 v64, s41, v64
	v_mul_f32_e32 v68, s41, v68
	v_mul_f32_e32 v65, s41, v65
	v_mul_f32_e32 v69, s41, v69
	v_mul_f32_e32 v66, s41, v66
	v_mul_f32_e32 v70, s41, v70
	v_mul_f32_e32 v67, s41, v67
	v_mul_f32_e32 v71, s41, v71
	v_cvt_pk_bf16_f32 v64, v64, v65
	v_cvt_pk_bf16_f32 v65, v66, v67
	ds_write_b64 v253, v[64:65] offset:0
	v_cvt_pk_bf16_f32 v68, v68, v69
	v_cvt_pk_bf16_f32 v69, v70, v71
	ds_write_b64 v254, v[68:69] offset:0
	s_add_i32 s0, s69, 160
	v_add_u32_e32 v140, s0, v148
	v_subrev_u32_e32 v141, 0x2100, v140
	v_cmp_gt_u32_e32 vcc, 0x2100, v140
	s_nop 1
	v_cndmask_b32_e32 v141, v141, v140, vcc
	v_subrev_u32_e32 v142, 0x100, v141
	v_lshrrev_b32_e32 v143, s39, v142
	v_and_b32_e32 v143, s40, v143
	v_cmp_le_u32_e32 vcc, 0x100, v141
	s_nop 1
	v_cndmask_b32_e32 v143, 0, v143, vcc
	v_lshl_add_u32 v151, v143, 6, v149
	global_load_dwordx4 v[164:167], v151, s[2:3]
	global_load_dwordx4 v[168:171], v151, s[4:5]
	s_waitcnt vmcnt(2)
	v_mul_f32_e32 v152, v76, v176
	v_mul_f32_e32 v153, v76, v172
	v_fma_f32 v76, v72, v176, v153
	v_fma_f32 v72, v72, v172, -v152
	v_mul_f32_e32 v152, v77, v177
	v_mul_f32_e32 v153, v77, v173
	v_fma_f32 v77, v73, v177, v153
	v_fma_f32 v73, v73, v173, -v152
	v_mul_f32_e32 v152, v78, v178
	v_mul_f32_e32 v153, v78, v174
	v_fma_f32 v78, v74, v178, v153
	v_fma_f32 v74, v74, v174, -v152
	v_mul_f32_e32 v152, v79, v179
	v_mul_f32_e32 v153, v79, v175
	v_fma_f32 v79, v75, v179, v153
	v_fma_f32 v75, v75, v175, -v152
	v_mul_f32_e32 v72, s41, v72
	v_mul_f32_e32 v76, s41, v76
	v_mul_f32_e32 v73, s41, v73
	v_mul_f32_e32 v77, s41, v77
	v_mul_f32_e32 v74, s41, v74
	v_mul_f32_e32 v78, s41, v78
	v_mul_f32_e32 v75, s41, v75
	v_mul_f32_e32 v79, s41, v79
	v_cvt_pk_bf16_f32 v72, v72, v73
	v_cvt_pk_bf16_f32 v73, v74, v75
	ds_write_b64 v253, v[72:73] offset:4096
	v_cvt_pk_bf16_f32 v76, v76, v77
	v_cvt_pk_bf16_f32 v77, v78, v79
	ds_write_b64 v254, v[76:77] offset:4096
	s_add_i32 s0, s69, 176
	v_add_u32_e32 v140, s0, v148
	v_subrev_u32_e32 v141, 0x2100, v140
	v_cmp_gt_u32_e32 vcc, 0x2100, v140
	s_nop 1
	v_cndmask_b32_e32 v141, v141, v140, vcc
	v_subrev_u32_e32 v142, 0x100, v141
	v_lshrrev_b32_e32 v143, s39, v142
	v_and_b32_e32 v143, s40, v143
	v_cmp_le_u32_e32 vcc, 0x100, v141
	s_nop 1
	v_cndmask_b32_e32 v143, 0, v143, vcc
	v_lshl_add_u32 v151, v143, 6, v149
	global_load_dwordx4 v[172:175], v151, s[2:3]
	global_load_dwordx4 v[176:179], v151, s[4:5]
	s_waitcnt vmcnt(2)
	v_mul_f32_e32 v152, v84, v168
	v_mul_f32_e32 v153, v84, v164
	v_fma_f32 v84, v80, v168, v153
	v_fma_f32 v80, v80, v164, -v152
	v_mul_f32_e32 v152, v85, v169
	v_mul_f32_e32 v153, v85, v165
	v_fma_f32 v85, v81, v169, v153
	v_fma_f32 v81, v81, v165, -v152
	v_mul_f32_e32 v152, v86, v170
	v_mul_f32_e32 v153, v86, v166
	v_fma_f32 v86, v82, v170, v153
	v_fma_f32 v82, v82, v166, -v152
	v_mul_f32_e32 v152, v87, v171
	v_mul_f32_e32 v153, v87, v167
	v_fma_f32 v87, v83, v171, v153
	v_fma_f32 v83, v83, v167, -v152
	v_mul_f32_e32 v80, s41, v80
	v_mul_f32_e32 v84, s41, v84
	v_mul_f32_e32 v81, s41, v81
	v_mul_f32_e32 v85, s41, v85
	v_mul_f32_e32 v82, s41, v82
	v_mul_f32_e32 v86, s41, v86
	v_mul_f32_e32 v83, s41, v83
	v_mul_f32_e32 v87, s41, v87
	v_cvt_pk_bf16_f32 v80, v80, v81
	v_cvt_pk_bf16_f32 v81, v82, v83
	ds_write_b64 v253, v[80:81] offset:8192
	v_cvt_pk_bf16_f32 v84, v84, v85
	v_cvt_pk_bf16_f32 v85, v86, v87
	ds_write_b64 v254, v[84:85] offset:8192
	s_add_i32 s0, s69, 192
	v_add_u32_e32 v140, s0, v148
	v_subrev_u32_e32 v141, 0x2100, v140
	v_cmp_gt_u32_e32 vcc, 0x2100, v140
	s_nop 1
	v_cndmask_b32_e32 v141, v141, v140, vcc
	v_subrev_u32_e32 v142, 0x100, v141
	v_lshrrev_b32_e32 v143, s39, v142
	v_and_b32_e32 v143, s40, v143
	v_cmp_le_u32_e32 vcc, 0x100, v141
	s_nop 1
	v_cndmask_b32_e32 v143, 0, v143, vcc
	v_lshl_add_u32 v151, v143, 6, v149
	global_load_dwordx4 v[164:167], v151, s[2:3]
	global_load_dwordx4 v[168:171], v151, s[4:5]
	s_waitcnt vmcnt(2)
	v_mul_f32_e32 v152, v92, v176
	v_mul_f32_e32 v153, v92, v172
	v_fma_f32 v92, v88, v176, v153
	v_fma_f32 v88, v88, v172, -v152
	v_mul_f32_e32 v152, v93, v177
	v_mul_f32_e32 v153, v93, v173
	v_fma_f32 v93, v89, v177, v153
	v_fma_f32 v89, v89, v173, -v152
	v_mul_f32_e32 v152, v94, v178
	v_mul_f32_e32 v153, v94, v174
	v_fma_f32 v94, v90, v178, v153
	v_fma_f32 v90, v90, v174, -v152
	v_mul_f32_e32 v152, v95, v179
	v_mul_f32_e32 v153, v95, v175
	v_fma_f32 v95, v91, v179, v153
	v_fma_f32 v91, v91, v175, -v152
	v_mul_f32_e32 v88, s41, v88
	v_mul_f32_e32 v92, s41, v92
	v_mul_f32_e32 v89, s41, v89
	v_mul_f32_e32 v93, s41, v93
	v_mul_f32_e32 v90, s41, v90
	v_mul_f32_e32 v94, s41, v94
	v_mul_f32_e32 v91, s41, v91
	v_mul_f32_e32 v95, s41, v95
	v_cvt_pk_bf16_f32 v88, v88, v89
	v_cvt_pk_bf16_f32 v89, v90, v91
	ds_write_b64 v253, v[88:89] offset:12288
	v_cvt_pk_bf16_f32 v92, v92, v93
	v_cvt_pk_bf16_f32 v93, v94, v95
	ds_write_b64 v254, v[92:93] offset:12288
	s_add_i32 s0, s69, 208
	v_add_u32_e32 v140, s0, v148
	v_subrev_u32_e32 v141, 0x2100, v140
	v_cmp_gt_u32_e32 vcc, 0x2100, v140
	s_nop 1
	v_cndmask_b32_e32 v141, v141, v140, vcc
	v_subrev_u32_e32 v142, 0x100, v141
	v_lshrrev_b32_e32 v143, s39, v142
	v_and_b32_e32 v143, s40, v143
	v_cmp_le_u32_e32 vcc, 0x100, v141
	s_nop 1
	v_cndmask_b32_e32 v143, 0, v143, vcc
	v_lshl_add_u32 v151, v143, 6, v149
	global_load_dwordx4 v[172:175], v151, s[2:3]
	global_load_dwordx4 v[176:179], v151, s[4:5]
	s_waitcnt vmcnt(2)
	v_mul_f32_e32 v152, v100, v168
	v_mul_f32_e32 v153, v100, v164
	v_fma_f32 v100, v96, v168, v153
	v_fma_f32 v96, v96, v164, -v152
	v_mul_f32_e32 v152, v101, v169
	v_mul_f32_e32 v153, v101, v165
	v_fma_f32 v101, v97, v169, v153
	v_fma_f32 v97, v97, v165, -v152
	v_mul_f32_e32 v152, v102, v170
	v_mul_f32_e32 v153, v102, v166
	v_fma_f32 v102, v98, v170, v153
	v_fma_f32 v98, v98, v166, -v152
	v_mul_f32_e32 v152, v103, v171
	v_mul_f32_e32 v153, v103, v167
	v_fma_f32 v103, v99, v171, v153
	v_fma_f32 v99, v99, v167, -v152
	v_mul_f32_e32 v96, s41, v96
	v_mul_f32_e32 v100, s41, v100
	v_mul_f32_e32 v97, s41, v97
	v_mul_f32_e32 v101, s41, v101
	v_mul_f32_e32 v98, s41, v98
	v_mul_f32_e32 v102, s41, v102
	v_mul_f32_e32 v99, s41, v99
	v_mul_f32_e32 v103, s41, v103
	v_cvt_pk_bf16_f32 v96, v96, v97
	v_cvt_pk_bf16_f32 v97, v98, v99
	ds_write_b64 v253, v[96:97] offset:16384
	v_cvt_pk_bf16_f32 v100, v100, v101
	v_cvt_pk_bf16_f32 v101, v102, v103
	ds_write_b64 v254, v[100:101] offset:16384
	s_add_i32 s0, s69, 224
	v_add_u32_e32 v140, s0, v148
	v_subrev_u32_e32 v141, 0x2100, v140
	v_cmp_gt_u32_e32 vcc, 0x2100, v140
	s_nop 1
	v_cndmask_b32_e32 v141, v141, v140, vcc
	v_subrev_u32_e32 v142, 0x100, v141
	v_lshrrev_b32_e32 v143, s39, v142
	v_and_b32_e32 v143, s40, v143
	v_cmp_le_u32_e32 vcc, 0x100, v141
	s_nop 1
	v_cndmask_b32_e32 v143, 0, v143, vcc
	v_lshl_add_u32 v151, v143, 6, v149
	global_load_dwordx4 v[164:167], v151, s[2:3]
	global_load_dwordx4 v[168:171], v151, s[4:5]
	s_waitcnt vmcnt(2)
	v_mul_f32_e32 v152, v108, v176
	v_mul_f32_e32 v153, v108, v172
	v_fma_f32 v108, v104, v176, v153
	v_fma_f32 v104, v104, v172, -v152
	v_mul_f32_e32 v152, v109, v177
	v_mul_f32_e32 v153, v109, v173
	v_fma_f32 v109, v105, v177, v153
	v_fma_f32 v105, v105, v173, -v152
	v_mul_f32_e32 v152, v110, v178
	v_mul_f32_e32 v153, v110, v174
	v_fma_f32 v110, v106, v178, v153
	v_fma_f32 v106, v106, v174, -v152
	v_mul_f32_e32 v152, v111, v179
	v_mul_f32_e32 v153, v111, v175
	v_fma_f32 v111, v107, v179, v153
	v_fma_f32 v107, v107, v175, -v152
	v_mul_f32_e32 v104, s41, v104
	v_mul_f32_e32 v108, s41, v108
	v_mul_f32_e32 v105, s41, v105
	v_mul_f32_e32 v109, s41, v109
	v_mul_f32_e32 v106, s41, v106
	v_mul_f32_e32 v110, s41, v110
	v_mul_f32_e32 v107, s41, v107
	v_mul_f32_e32 v111, s41, v111
	v_cvt_pk_bf16_f32 v104, v104, v105
	v_cvt_pk_bf16_f32 v105, v106, v107
	ds_write_b64 v253, v[104:105] offset:20480
	v_cvt_pk_bf16_f32 v108, v108, v109
	v_cvt_pk_bf16_f32 v109, v110, v111
	ds_write_b64 v254, v[108:109] offset:20480
	s_add_i32 s0, s69, 240
	v_add_u32_e32 v140, s0, v148
	v_subrev_u32_e32 v141, 0x2100, v140
	v_cmp_gt_u32_e32 vcc, 0x2100, v140
	s_nop 1
	v_cndmask_b32_e32 v141, v141, v140, vcc
	v_subrev_u32_e32 v142, 0x100, v141
	v_lshrrev_b32_e32 v143, s39, v142
	v_and_b32_e32 v143, s40, v143
	v_cmp_le_u32_e32 vcc, 0x100, v141
	s_nop 1
	v_cndmask_b32_e32 v143, 0, v143, vcc
	v_lshl_add_u32 v151, v143, 6, v149
	global_load_dwordx4 v[172:175], v151, s[2:3]
	global_load_dwordx4 v[176:179], v151, s[4:5]
	s_waitcnt vmcnt(2)
	v_mul_f32_e32 v152, v116, v168
	v_mul_f32_e32 v153, v116, v164
	v_fma_f32 v116, v112, v168, v153
	v_fma_f32 v112, v112, v164, -v152
	v_mul_f32_e32 v152, v117, v169
	v_mul_f32_e32 v153, v117, v165
	v_fma_f32 v117, v113, v169, v153
	v_fma_f32 v113, v113, v165, -v152
	v_mul_f32_e32 v152, v118, v170
	v_mul_f32_e32 v153, v118, v166
	v_fma_f32 v118, v114, v170, v153
	v_fma_f32 v114, v114, v166, -v152
	v_mul_f32_e32 v152, v119, v171
	v_mul_f32_e32 v153, v119, v167
	v_fma_f32 v119, v115, v171, v153
	v_fma_f32 v115, v115, v167, -v152
	v_mul_f32_e32 v112, s41, v112
	v_mul_f32_e32 v116, s41, v116
	v_mul_f32_e32 v113, s41, v113
	v_mul_f32_e32 v117, s41, v117
	v_mul_f32_e32 v114, s41, v114
	v_mul_f32_e32 v118, s41, v118
	v_mul_f32_e32 v115, s41, v115
	v_mul_f32_e32 v119, s41, v119
	v_cvt_pk_bf16_f32 v112, v112, v113
	v_cvt_pk_bf16_f32 v113, v114, v115
	ds_write_b64 v253, v[112:113] offset:24576
	v_cvt_pk_bf16_f32 v116, v116, v117
	v_cvt_pk_bf16_f32 v117, v118, v119
	ds_write_b64 v254, v[116:117] offset:24576
	s_add_i32 s0, s69, 256
	v_add_u32_e32 v140, s0, v148
	v_subrev_u32_e32 v141, 0x2100, v140
	v_cmp_gt_u32_e32 vcc, 0x2100, v140
	s_nop 1
	v_cndmask_b32_e32 v141, v141, v140, vcc
	v_subrev_u32_e32 v142, 0x100, v141
	v_lshrrev_b32_e32 v143, s39, v142
	v_and_b32_e32 v143, s40, v143
	v_cmp_le_u32_e32 vcc, 0x100, v141
	s_nop 1
	v_cndmask_b32_e32 v143, 0, v143, vcc
	v_lshl_add_u32 v151, v143, 6, v149
	global_load_dwordx4 v[164:167], v151, s[2:3]
	global_load_dwordx4 v[168:171], v151, s[4:5]
	s_waitcnt vmcnt(2)
	v_mul_f32_e32 v152, v124, v176
	v_mul_f32_e32 v153, v124, v172
	v_fma_f32 v124, v120, v176, v153
	v_fma_f32 v120, v120, v172, -v152
	v_mul_f32_e32 v152, v125, v177
	v_mul_f32_e32 v153, v125, v173
	v_fma_f32 v125, v121, v177, v153
	v_fma_f32 v121, v121, v173, -v152
	v_mul_f32_e32 v152, v126, v178
	v_mul_f32_e32 v153, v126, v174
	v_fma_f32 v126, v122, v178, v153
	v_fma_f32 v122, v122, v174, -v152
	v_mul_f32_e32 v152, v127, v179
	v_mul_f32_e32 v153, v127, v175
	v_fma_f32 v127, v123, v179, v153
	v_fma_f32 v123, v123, v175, -v152
	v_mul_f32_e32 v120, s41, v120
	v_mul_f32_e32 v124, s41, v124
	v_mul_f32_e32 v121, s41, v121
	v_mul_f32_e32 v125, s41, v125
	v_mul_f32_e32 v122, s41, v122
	v_mul_f32_e32 v126, s41, v126
	v_mul_f32_e32 v123, s41, v123
	v_mul_f32_e32 v127, s41, v127
	v_cvt_pk_bf16_f32 v120, v120, v121
	v_cvt_pk_bf16_f32 v121, v122, v123
	ds_write_b64 v253, v[120:121] offset:28672
	v_cvt_pk_bf16_f32 v124, v124, v125
	v_cvt_pk_bf16_f32 v125, v126, v127
	ds_write_b64 v254, v[124:125] offset:28672
	s_cmp_eq_u32 s65, 0
	s_cbranch_scc1 .Lg2_win_st_lastR
	s_waitcnt vmcnt(0)
	v_mul_f32_e32 v152, v132, v168
	v_mul_f32_e32 v153, v132, v164
	v_fma_f32 v132, v128, v168, v153
	v_fma_f32 v128, v128, v164, -v152
	v_mul_f32_e32 v152, v133, v169
	v_mul_f32_e32 v153, v133, v165
	v_fma_f32 v133, v129, v169, v153
	v_fma_f32 v129, v129, v165, -v152
	v_mul_f32_e32 v152, v134, v170
	v_mul_f32_e32 v153, v134, v166
	v_fma_f32 v134, v130, v170, v153
	v_fma_f32 v130, v130, v166, -v152
	v_mul_f32_e32 v152, v135, v171
	v_mul_f32_e32 v153, v135, v167
	v_fma_f32 v135, v131, v171, v153
	v_fma_f32 v131, v131, v167, -v152
	v_mul_f32_e32 v128, s41, v128
	v_mul_f32_e32 v132, s41, v132
	v_mul_f32_e32 v129, s41, v129
	v_mul_f32_e32 v133, s41, v133
	v_mul_f32_e32 v130, s41, v130
	v_mul_f32_e32 v134, s41, v134
	v_mul_f32_e32 v131, s41, v131
	v_mul_f32_e32 v135, s41, v135
	v_cvt_pk_bf16_f32 v128, v128, v129
	v_cvt_pk_bf16_f32 v129, v130, v131
	ds_write_b64 v253, v[128:129] offset:32768
	v_cvt_pk_bf16_f32 v132, v132, v133
	v_cvt_pk_bf16_f32 v133, v134, v135
	ds_write_b64 v254, v[132:133] offset:32768

.Lg2_win_rd_lastaR:
	s_waitcnt lgkmcnt(0)
	global_store_dwordx4 v252, v[0:3], s[60:61]
	s_add_u32 s60, s60, 0x39000
	s_addc_u32 s61, s61, 0
	global_store_dwordx4 v252, v[4:7], s[60:61]
	s_add_u32 s60, s60, 0x39000
	s_addc_u32 s61, s61, 0
	global_store_dwordx4 v252, v[8:11], s[60:61]
	s_add_u32 s60, s60, 0x39000
	s_addc_u32 s61, s61, 0
	global_store_dwordx4 v252, v[12:15], s[60:61]
	s_add_u32 s60, s60, 0x39000
	s_addc_u32 s61, s61, 0
	global_store_dwordx4 v252, v[16:19], s[60:61]
	s_add_u32 s60, s60, 0x39000
	s_addc_u32 s61, s61, 0
	global_store_dwordx4 v252, v[20:23], s[60:61]
	s_add_u32 s60, s60, 0x39000
	s_addc_u32 s61, s61, 0
	global_store_dwordx4 v252, v[24:27], s[60:61]
	s_add_u32 s60, s60, 0x39000
	s_addc_u32 s61, s61, 0
	global_store_dwordx4 v252, v[28:31], s[60:61]
	s_add_u32 s60, s60, 0x39000
	s_addc_u32 s61, s61, 0
	global_store_dwordx4 v252, v[32:35], s[60:61]
	s_add_u32 s60, s60, 0x39000
	s_addc_u32 s61, s61, 0
	global_store_dwordx4 v252, v[36:39], s[60:61]
	s_add_u32 s60, s60, 0x39000
	s_addc_u32 s61, s61, 0
	global_store_dwordx4 v252, v[40:43], s[60:61]
	s_add_u32 s60, s60, 0x39000
	s_addc_u32 s61, s61, 0
	global_store_dwordx4 v252, v[44:47], s[60:61]
	s_add_u32 s60, s60, 0x39000
	s_addc_u32 s61, s61, 0
	global_store_dwordx4 v252, v[48:51], s[60:61]
	s_add_u32 s60, s60, 0x39000
	s_addc_u32 s61, s61, 0
	global_store_dwordx4 v252, v[52:55], s[60:61]
	s_add_u32 s60, s60, 0x39000
	s_addc_u32 s61, s61, 0
	global_store_dwordx4 v252, v[56:59], s[60:61]
	s_add_u32 s60, s60, 0x39000
	s_addc_u32 s61, s61, 0
	global_store_dwordx4 v252, v[60:63], s[60:61]
	s_add_u32 s60, s60, 0x39000
	s_addc_u32 s61, s61, 0
	s_cmp_eq_u32 s65, 0
	s_cbranch_scc1 .Lg2_win_rd_lastR
	global_store_dwordx4 v252, v[64:67], s[60:61]
	s_add_u32 s60, s60, 0x39000
	s_addc_u32 s61, s61, 0

.Lg2_win_epiS:
	s_nop 7
	s_nop 7
	s_barrier
	v_mul_f32_e32 v0, 0x3e38aa3b, v0
	v_mul_f32_e32 v1, 0x3e38aa3b, v1
	v_mul_f32_e32 v2, 0x3e38aa3b, v2
	v_mul_f32_e32 v3, 0x3e38aa3b, v3
	v_cvt_pk_bf16_f32 v0, v0, v1
	v_cvt_pk_bf16_f32 v1, v2, v3
	ds_write_b64 v212, v[0:1] offset:0
	v_mul_f32_e32 v4, 0x3e38aa3b, v4
	v_mul_f32_e32 v5, 0x3e38aa3b, v5
	v_mul_f32_e32 v6, 0x3e38aa3b, v6
	v_mul_f32_e32 v7, 0x3e38aa3b, v7
	v_cvt_pk_bf16_f32 v4, v4, v5
	v_cvt_pk_bf16_f32 v5, v6, v7
	ds_write_b64 v213, v[4:5] offset:0
	v_mul_f32_e32 v8, 0x3e38aa3b, v8
	v_mul_f32_e32 v9, 0x3e38aa3b, v9
	v_mul_f32_e32 v10, 0x3e38aa3b, v10
	v_mul_f32_e32 v11, 0x3e38aa3b, v11
	v_cvt_pk_bf16_f32 v8, v8, v9
	v_cvt_pk_bf16_f32 v9, v10, v11
	ds_write_b64 v212, v[8:9] offset:4096
	v_mul_f32_e32 v12, 0x3e38aa3b, v12
	v_mul_f32_e32 v13, 0x3e38aa3b, v13
	v_mul_f32_e32 v14, 0x3e38aa3b, v14
	v_mul_f32_e32 v15, 0x3e38aa3b, v15
	v_cvt_pk_bf16_f32 v12, v12, v13
	v_cvt_pk_bf16_f32 v13, v14, v15
	ds_write_b64 v213, v[12:13] offset:4096
	v_mul_f32_e32 v16, 0x3e38aa3b, v16
	v_mul_f32_e32 v17, 0x3e38aa3b, v17
	v_mul_f32_e32 v18, 0x3e38aa3b, v18
	v_mul_f32_e32 v19, 0x3e38aa3b, v19
	v_cvt_pk_bf16_f32 v16, v16, v17
	v_cvt_pk_bf16_f32 v17, v18, v19
	ds_write_b64 v212, v[16:17] offset:8192
	v_mul_f32_e32 v20, 0x3e38aa3b, v20
	v_mul_f32_e32 v21, 0x3e38aa3b, v21
	v_mul_f32_e32 v22, 0x3e38aa3b, v22
	v_mul_f32_e32 v23, 0x3e38aa3b, v23
	v_cvt_pk_bf16_f32 v20, v20, v21
	v_cvt_pk_bf16_f32 v21, v22, v23
	ds_write_b64 v213, v[20:21] offset:8192
	v_mul_f32_e32 v24, 0x3e38aa3b, v24
	v_mul_f32_e32 v25, 0x3e38aa3b, v25
	v_mul_f32_e32 v26, 0x3e38aa3b, v26
	v_mul_f32_e32 v27, 0x3e38aa3b, v27
	v_cvt_pk_bf16_f32 v24, v24, v25
	v_cvt_pk_bf16_f32 v25, v26, v27
	ds_write_b64 v212, v[24:25] offset:12288
	v_mul_f32_e32 v28, 0x3e38aa3b, v28
	v_mul_f32_e32 v29, 0x3e38aa3b, v29
	v_mul_f32_e32 v30, 0x3e38aa3b, v30
	v_mul_f32_e32 v31, 0x3e38aa3b, v31
	v_cvt_pk_bf16_f32 v28, v28, v29
	v_cvt_pk_bf16_f32 v29, v30, v31
	ds_write_b64 v213, v[28:29] offset:12288
	v_mul_f32_e32 v32, 0x3e38aa3b, v32
	v_mul_f32_e32 v33, 0x3e38aa3b, v33
	v_mul_f32_e32 v34, 0x3e38aa3b, v34
	v_mul_f32_e32 v35, 0x3e38aa3b, v35
	v_cvt_pk_bf16_f32 v32, v32, v33
	v_cvt_pk_bf16_f32 v33, v34, v35
	ds_write_b64 v212, v[32:33] offset:16384
	v_mul_f32_e32 v36, 0x3e38aa3b, v36
	v_mul_f32_e32 v37, 0x3e38aa3b, v37
	v_mul_f32_e32 v38, 0x3e38aa3b, v38
	v_mul_f32_e32 v39, 0x3e38aa3b, v39
	v_cvt_pk_bf16_f32 v36, v36, v37
	v_cvt_pk_bf16_f32 v37, v38, v39
	ds_write_b64 v213, v[36:37] offset:16384
	v_mul_f32_e32 v40, 0x3e38aa3b, v40
	v_mul_f32_e32 v41, 0x3e38aa3b, v41
	v_mul_f32_e32 v42, 0x3e38aa3b, v42
	v_mul_f32_e32 v43, 0x3e38aa3b, v43
	v_cvt_pk_bf16_f32 v40, v40, v41
	v_cvt_pk_bf16_f32 v41, v42, v43
	ds_write_b64 v212, v[40:41] offset:20480
	v_mul_f32_e32 v44, 0x3e38aa3b, v44
	v_mul_f32_e32 v45, 0x3e38aa3b, v45
	v_mul_f32_e32 v46, 0x3e38aa3b, v46
	v_mul_f32_e32 v47, 0x3e38aa3b, v47
	v_cvt_pk_bf16_f32 v44, v44, v45
	v_cvt_pk_bf16_f32 v45, v46, v47
	ds_write_b64 v213, v[44:45] offset:20480
	v_mul_f32_e32 v48, 0x3e38aa3b, v48
	v_mul_f32_e32 v49, 0x3e38aa3b, v49
	v_mul_f32_e32 v50, 0x3e38aa3b, v50
	v_mul_f32_e32 v51, 0x3e38aa3b, v51
	v_cvt_pk_bf16_f32 v48, v48, v49
	v_cvt_pk_bf16_f32 v49, v50, v51
	ds_write_b64 v212, v[48:49] offset:24576
	v_mul_f32_e32 v52, 0x3e38aa3b, v52
	v_mul_f32_e32 v53, 0x3e38aa3b, v53
	v_mul_f32_e32 v54, 0x3e38aa3b, v54
	v_mul_f32_e32 v55, 0x3e38aa3b, v55
	v_cvt_pk_bf16_f32 v52, v52, v53
	v_cvt_pk_bf16_f32 v53, v54, v55
	ds_write_b64 v213, v[52:53] offset:24576
	v_mul_f32_e32 v56, 0x3e38aa3b, v56
	v_mul_f32_e32 v57, 0x3e38aa3b, v57
	v_mul_f32_e32 v58, 0x3e38aa3b, v58
	v_mul_f32_e32 v59, 0x3e38aa3b, v59
	v_cvt_pk_bf16_f32 v56, v56, v57
	v_cvt_pk_bf16_f32 v57, v58, v59
	ds_write_b64 v212, v[56:57] offset:28672
	v_mul_f32_e32 v60, 0x3e38aa3b, v60
	v_mul_f32_e32 v61, 0x3e38aa3b, v61
	v_mul_f32_e32 v62, 0x3e38aa3b, v62
	v_mul_f32_e32 v63, 0x3e38aa3b, v63
	v_cvt_pk_bf16_f32 v60, v60, v61
	v_cvt_pk_bf16_f32 v61, v62, v63
	ds_write_b64 v213, v[60:61] offset:28672
	v_mul_f32_e32 v64, 0x3e38aa3b, v64
	v_mul_f32_e32 v65, 0x3e38aa3b, v65
	v_mul_f32_e32 v66, 0x3e38aa3b, v66
	v_mul_f32_e32 v67, 0x3e38aa3b, v67
	v_cvt_pk_bf16_f32 v64, v64, v65
	v_cvt_pk_bf16_f32 v65, v66, v67
	ds_write_b64 v253, v[64:65] offset:0
	v_mul_f32_e32 v68, 0x3e38aa3b, v68
	v_mul_f32_e32 v69, 0x3e38aa3b, v69
	v_mul_f32_e32 v70, 0x3e38aa3b, v70
	v_mul_f32_e32 v71, 0x3e38aa3b, v71
	v_cvt_pk_bf16_f32 v68, v68, v69
	v_cvt_pk_bf16_f32 v69, v70, v71
	ds_write_b64 v254, v[68:69] offset:0
	v_mul_f32_e32 v72, 0x3e38aa3b, v72
	v_mul_f32_e32 v73, 0x3e38aa3b, v73
	v_mul_f32_e32 v74, 0x3e38aa3b, v74
	v_mul_f32_e32 v75, 0x3e38aa3b, v75
	v_cvt_pk_bf16_f32 v72, v72, v73
	v_cvt_pk_bf16_f32 v73, v74, v75
	ds_write_b64 v253, v[72:73] offset:4096
	v_mul_f32_e32 v76, 0x3e38aa3b, v76
	v_mul_f32_e32 v77, 0x3e38aa3b, v77
	v_mul_f32_e32 v78, 0x3e38aa3b, v78
	v_mul_f32_e32 v79, 0x3e38aa3b, v79
	v_cvt_pk_bf16_f32 v76, v76, v77
	v_cvt_pk_bf16_f32 v77, v78, v79
	ds_write_b64 v254, v[76:77] offset:4096
	v_mul_f32_e32 v80, 0x3e38aa3b, v80
	v_mul_f32_e32 v81, 0x3e38aa3b, v81
	v_mul_f32_e32 v82, 0x3e38aa3b, v82
	v_mul_f32_e32 v83, 0x3e38aa3b, v83
	v_cvt_pk_bf16_f32 v80, v80, v81
	v_cvt_pk_bf16_f32 v81, v82, v83
	ds_write_b64 v253, v[80:81] offset:8192
	v_mul_f32_e32 v84, 0x3e38aa3b, v84
	v_mul_f32_e32 v85, 0x3e38aa3b, v85
	v_mul_f32_e32 v86, 0x3e38aa3b, v86
	v_mul_f32_e32 v87, 0x3e38aa3b, v87
	v_cvt_pk_bf16_f32 v84, v84, v85
	v_cvt_pk_bf16_f32 v85, v86, v87
	ds_write_b64 v254, v[84:85] offset:8192
	v_mul_f32_e32 v88, 0x3e38aa3b, v88
	v_mul_f32_e32 v89, 0x3e38aa3b, v89
	v_mul_f32_e32 v90, 0x3e38aa3b, v90
	v_mul_f32_e32 v91, 0x3e38aa3b, v91
	v_cvt_pk_bf16_f32 v88, v88, v89
	v_cvt_pk_bf16_f32 v89, v90, v91
	ds_write_b64 v253, v[88:89] offset:12288
	v_mul_f32_e32 v92, 0x3e38aa3b, v92
	v_mul_f32_e32 v93, 0x3e38aa3b, v93
	v_mul_f32_e32 v94, 0x3e38aa3b, v94
	v_mul_f32_e32 v95, 0x3e38aa3b, v95
	v_cvt_pk_bf16_f32 v92, v92, v93
	v_cvt_pk_bf16_f32 v93, v94, v95
	ds_write_b64 v254, v[92:93] offset:12288
	v_mul_f32_e32 v96, 0x3e38aa3b, v96
	v_mul_f32_e32 v97, 0x3e38aa3b, v97
	v_mul_f32_e32 v98, 0x3e38aa3b, v98
	v_mul_f32_e32 v99, 0x3e38aa3b, v99
	v_cvt_pk_bf16_f32 v96, v96, v97
	v_cvt_pk_bf16_f32 v97, v98, v99
	ds_write_b64 v253, v[96:97] offset:16384
	v_mul_f32_e32 v100, 0x3e38aa3b, v100
	v_mul_f32_e32 v101, 0x3e38aa3b, v101
	v_mul_f32_e32 v102, 0x3e38aa3b, v102
	v_mul_f32_e32 v103, 0x3e38aa3b, v103
	v_cvt_pk_bf16_f32 v100, v100, v101
	v_cvt_pk_bf16_f32 v101, v102, v103
	ds_write_b64 v254, v[100:101] offset:16384
	v_mul_f32_e32 v104, 0x3e38aa3b, v104
	v_mul_f32_e32 v105, 0x3e38aa3b, v105
	v_mul_f32_e32 v106, 0x3e38aa3b, v106
	v_mul_f32_e32 v107, 0x3e38aa3b, v107
	v_cvt_pk_bf16_f32 v104, v104, v105
	v_cvt_pk_bf16_f32 v105, v106, v107
	ds_write_b64 v253, v[104:105] offset:20480
	v_mul_f32_e32 v108, 0x3e38aa3b, v108
	v_mul_f32_e32 v109, 0x3e38aa3b, v109
	v_mul_f32_e32 v110, 0x3e38aa3b, v110
	v_mul_f32_e32 v111, 0x3e38aa3b, v111
	v_cvt_pk_bf16_f32 v108, v108, v109
	v_cvt_pk_bf16_f32 v109, v110, v111
	ds_write_b64 v254, v[108:109] offset:20480
	v_mul_f32_e32 v112, 0x3e38aa3b, v112
	v_mul_f32_e32 v113, 0x3e38aa3b, v113
	v_mul_f32_e32 v114, 0x3e38aa3b, v114
	v_mul_f32_e32 v115, 0x3e38aa3b, v115
	v_cvt_pk_bf16_f32 v112, v112, v113
	v_cvt_pk_bf16_f32 v113, v114, v115
	ds_write_b64 v253, v[112:113] offset:24576
	v_mul_f32_e32 v116, 0x3e38aa3b, v116
	v_mul_f32_e32 v117, 0x3e38aa3b, v117
	v_mul_f32_e32 v118, 0x3e38aa3b, v118
	v_mul_f32_e32 v119, 0x3e38aa3b, v119
	v_cvt_pk_bf16_f32 v116, v116, v117
	v_cvt_pk_bf16_f32 v117, v118, v119
	ds_write_b64 v254, v[116:117] offset:24576
	v_mul_f32_e32 v120, 0x3e38aa3b, v120
	v_mul_f32_e32 v121, 0x3e38aa3b, v121
	v_mul_f32_e32 v122, 0x3e38aa3b, v122
	v_mul_f32_e32 v123, 0x3e38aa3b, v123
	v_cvt_pk_bf16_f32 v120, v120, v121
	v_cvt_pk_bf16_f32 v121, v122, v123
	ds_write_b64 v253, v[120:121] offset:28672
	v_mul_f32_e32 v124, 0x3e38aa3b, v124
	v_mul_f32_e32 v125, 0x3e38aa3b, v125
	v_mul_f32_e32 v126, 0x3e38aa3b, v126
	v_mul_f32_e32 v127, 0x3e38aa3b, v127
	v_cvt_pk_bf16_f32 v124, v124, v125
	v_cvt_pk_bf16_f32 v125, v126, v127
	ds_write_b64 v254, v[124:125] offset:28672
	s_cmp_eq_u32 s65, 0
	s_cbranch_scc1 .Lg2_win_st_lastS
	v_mul_f32_e32 v128, 0x3e38aa3b, v128
	v_mul_f32_e32 v129, 0x3e38aa3b, v129
	v_mul_f32_e32 v130, 0x3e38aa3b, v130
	v_mul_f32_e32 v131, 0x3e38aa3b, v131
	v_cvt_pk_bf16_f32 v128, v128, v129
	v_cvt_pk_bf16_f32 v129, v130, v131
	ds_write_b64 v253, v[128:129] offset:32768
	v_mul_f32_e32 v132, 0x3e38aa3b, v132
	v_mul_f32_e32 v133, 0x3e38aa3b, v133
	v_mul_f32_e32 v134, 0x3e38aa3b, v134
	v_mul_f32_e32 v135, 0x3e38aa3b, v135
	v_cvt_pk_bf16_f32 v132, v132, v133
	v_cvt_pk_bf16_f32 v133, v134, v135
	ds_write_b64 v254, v[132:133] offset:32768

.Lg2_win_epiP:
	s_nop 7
	s_nop 7
	s_barrier
	v_cvt_pk_bf16_f32 v0, v0, v1
	v_cvt_pk_bf16_f32 v1, v2, v3
	ds_write_b64 v212, v[0:1] offset:0
	v_cvt_pk_bf16_f32 v4, v4, v5
	v_cvt_pk_bf16_f32 v5, v6, v7
	ds_write_b64 v213, v[4:5] offset:0
	v_cvt_pk_bf16_f32 v8, v8, v9
	v_cvt_pk_bf16_f32 v9, v10, v11
	ds_write_b64 v212, v[8:9] offset:4096
	v_cvt_pk_bf16_f32 v12, v12, v13
	v_cvt_pk_bf16_f32 v13, v14, v15
	ds_write_b64 v213, v[12:13] offset:4096
	v_cvt_pk_bf16_f32 v16, v16, v17
	v_cvt_pk_bf16_f32 v17, v18, v19
	ds_write_b64 v212, v[16:17] offset:8192
	v_cvt_pk_bf16_f32 v20, v20, v21
	v_cvt_pk_bf16_f32 v21, v22, v23
	ds_write_b64 v213, v[20:21] offset:8192
	v_cvt_pk_bf16_f32 v24, v24, v25
	v_cvt_pk_bf16_f32 v25, v26, v27
	ds_write_b64 v212, v[24:25] offset:12288
	v_cvt_pk_bf16_f32 v28, v28, v29
	v_cvt_pk_bf16_f32 v29, v30, v31
	ds_write_b64 v213, v[28:29] offset:12288
	v_cvt_pk_bf16_f32 v32, v32, v33
	v_cvt_pk_bf16_f32 v33, v34, v35
	ds_write_b64 v212, v[32:33] offset:16384
	v_cvt_pk_bf16_f32 v36, v36, v37
	v_cvt_pk_bf16_f32 v37, v38, v39
	ds_write_b64 v213, v[36:37] offset:16384
	v_cvt_pk_bf16_f32 v40, v40, v41
	v_cvt_pk_bf16_f32 v41, v42, v43
	ds_write_b64 v212, v[40:41] offset:20480
	v_cvt_pk_bf16_f32 v44, v44, v45
	v_cvt_pk_bf16_f32 v45, v46, v47
	ds_write_b64 v213, v[44:45] offset:20480
	v_cvt_pk_bf16_f32 v48, v48, v49
	v_cvt_pk_bf16_f32 v49, v50, v51
	ds_write_b64 v212, v[48:49] offset:24576
	v_cvt_pk_bf16_f32 v52, v52, v53
	v_cvt_pk_bf16_f32 v53, v54, v55
	ds_write_b64 v213, v[52:53] offset:24576
	v_cvt_pk_bf16_f32 v56, v56, v57
	v_cvt_pk_bf16_f32 v57, v58, v59
	ds_write_b64 v212, v[56:57] offset:28672
	v_cvt_pk_bf16_f32 v60, v60, v61
	v_cvt_pk_bf16_f32 v61, v62, v63
	ds_write_b64 v213, v[60:61] offset:28672
	v_cvt_pk_bf16_f32 v64, v64, v65
	v_cvt_pk_bf16_f32 v65, v66, v67
	ds_write_b64 v253, v[64:65] offset:0
	v_cvt_pk_bf16_f32 v68, v68, v69
	v_cvt_pk_bf16_f32 v69, v70, v71
	ds_write_b64 v254, v[68:69] offset:0
	v_cvt_pk_bf16_f32 v72, v72, v73
	v_cvt_pk_bf16_f32 v73, v74, v75
	ds_write_b64 v253, v[72:73] offset:4096
	v_cvt_pk_bf16_f32 v76, v76, v77
	v_cvt_pk_bf16_f32 v77, v78, v79
	ds_write_b64 v254, v[76:77] offset:4096
	v_cvt_pk_bf16_f32 v80, v80, v81
	v_cvt_pk_bf16_f32 v81, v82, v83
	ds_write_b64 v253, v[80:81] offset:8192
	v_cvt_pk_bf16_f32 v84, v84, v85
	v_cvt_pk_bf16_f32 v85, v86, v87
	ds_write_b64 v254, v[84:85] offset:8192
	v_cvt_pk_bf16_f32 v88, v88, v89
	v_cvt_pk_bf16_f32 v89, v90, v91
	ds_write_b64 v253, v[88:89] offset:12288
	v_cvt_pk_bf16_f32 v92, v92, v93
	v_cvt_pk_bf16_f32 v93, v94, v95
	ds_write_b64 v254, v[92:93] offset:12288
	v_cvt_pk_bf16_f32 v96, v96, v97
	v_cvt_pk_bf16_f32 v97, v98, v99
	ds_write_b64 v253, v[96:97] offset:16384
	v_cvt_pk_bf16_f32 v100, v100, v101
	v_cvt_pk_bf16_f32 v101, v102, v103
	ds_write_b64 v254, v[100:101] offset:16384
	v_cvt_pk_bf16_f32 v104, v104, v105
	v_cvt_pk_bf16_f32 v105, v106, v107
	ds_write_b64 v253, v[104:105] offset:20480
	v_cvt_pk_bf16_f32 v108, v108, v109
	v_cvt_pk_bf16_f32 v109, v110, v111
	ds_write_b64 v254, v[108:109] offset:20480
	v_cvt_pk_bf16_f32 v112, v112, v113
	v_cvt_pk_bf16_f32 v113, v114, v115
	ds_write_b64 v253, v[112:113] offset:24576
	v_cvt_pk_bf16_f32 v116, v116, v117
	v_cvt_pk_bf16_f32 v117, v118, v119
	ds_write_b64 v254, v[116:117] offset:24576
	v_cvt_pk_bf16_f32 v120, v120, v121
	v_cvt_pk_bf16_f32 v121, v122, v123
	ds_write_b64 v253, v[120:121] offset:28672
	v_cvt_pk_bf16_f32 v124, v124, v125
	v_cvt_pk_bf16_f32 v125, v126, v127
	ds_write_b64 v254, v[124:125] offset:28672
	s_cmp_eq_u32 s65, 0
	s_cbranch_scc1 .Lg2_win_st_lastP
	v_cvt_pk_bf16_f32 v128, v128, v129
	v_cvt_pk_bf16_f32 v129, v130, v131
	ds_write_b64 v253, v[128:129] offset:32768
	v_cvt_pk_bf16_f32 v132, v132, v133
	v_cvt_pk_bf16_f32 v133, v134, v135
	ds_write_b64 v254, v[132:133] offset:32768

.Lg2_win_next:
	s_add_i32 s64, s64, 1
	s_cmp_lt_u32 s64, 7
	s_cbranch_scc1 .Lg2_win_tile
	v_lshrrev_b32_e32 v4, 6, v163
	v_and_b32_e32 v5, 63, v163
	v_and_b32_e32 v6, 15, v5
	v_lshrrev_b32_e32 v7, 4, v5
	v_lshlrev_b32_e32 v11, 1, v4
	s_mov_b32 s2, 0x8000
	v_mul_lo_u32 v12, v11, s2
	v_lshl_add_u32 v160, v5, 4, v12
	v_add_u32_e32 v161, 0x8000, v160
	v_lshrrev_b32_e32 v12, 1, v7
	v_lshl_add_u32 v12, v11, 1, v12
	v_and_b32_e32 v13, 1, v7
	v_lshlrev_b32_e32 v13, 3, v13
	v_lshl_add_u32 v14, v6, 8, v13
	v_xor_b32_e32 v15, v12, v6
	v_lshlrev_b32_e32 v15, 4, v15
	v_add_u32_e32 v212, v14, v15
	v_add_u32_e32 v12, 2, v12
	v_xor_b32_e32 v15, v12, v6
	v_lshlrev_b32_e32 v15, 4, v15
	v_add_u32_e32 v213, v14, v15
	v_add_u32_e32 v253, 0x8000, v212
	v_add_u32_e32 v254, 0x8000, v213
	s_mov_b32 s38, 56
	s_lshl_b32 s0, s68, 5
	s_add_i32 s69, s42, s0
	s_cmp_eq_u32 s68, 7
	s_cselect_b32 s0, 1, 0
	s_and_b32 s65, s0, s43
	s_lshl_b32 s0, s38, 7
	s_mul_i32 s2, s69, 0x800
	s_mul_hi_u32 s3, s69, 0x800
	s_add_u32 s56, s26, s2
	s_addc_u32 s57, s27, s3
	s_add_u32 s56, s56, 0x11140000
	s_addc_u32 s57, s57, 0
	s_mul_i32 s2, s0, 0x800
	s_mul_hi_u32 s3, s0, 0x800
	s_add_u32 s58, s26, s2
	s_addc_u32 s59, s27, s3
	s_add_u32 s58, s58, 0xeb20000
	s_addc_u32 s59, s59, 0
	s_mul_i32 s2, s69, 0x3900
	s_mul_hi_u32 s3, s69, 0x3900
	s_lshl_b32 s0, s0, 1
	s_add_u32 s2, s2, s0
	s_addc_u32 s3, s3, 0
	s_add_u32 s60, s26, s2
	s_addc_u32 s61, s27, s3
	s_add_u32 s60, s60, 0x0
	s_addc_u32 s61, s61, 0
	s_cmp_eq_u32 s65, 0
	s_cbranch_scc1 .Lg2_win_k2
	v_mov_b32_e32 v0, 0
	v_mov_b32_e32 v1, 0
	v_mov_b32_e32 v2, 0
	v_mov_b32_e32 v3, 0
	v_mov_b32_e32 v4, 0
	v_mov_b32_e32 v5, 0
	v_mov_b32_e32 v6, 0
	v_mov_b32_e32 v7, 0
	v_mov_b32_e32 v8, 0
	v_mov_b32_e32 v9, 0
	v_mov_b32_e32 v10, 0
	v_mov_b32_e32 v11, 0
	v_mov_b32_e32 v12, 0
	v_mov_b32_e32 v13, 0
	v_mov_b32_e32 v14, 0
	v_mov_b32_e32 v15, 0
	v_mov_b32_e32 v16, 0
	v_mov_b32_e32 v17, 0
	v_mov_b32_e32 v18, 0
	v_mov_b32_e32 v19, 0
	v_mov_b32_e32 v20, 0
	v_mov_b32_e32 v21, 0
	v_mov_b32_e32 v22, 0
	v_mov_b32_e32 v23, 0
	s_add_u32 s4, s56, 0x0
	s_addc_u32 s5, s57, 0
	s_add_u32 m0, s62, 0x0
	s_nop 0
	global_load_lds_dwordx4 v162, s[4:5]
	s_cmp_gt_u32 s70, 1
	s_cbranch_scc1 .Lg2_win_nodma_3
	s_add_u32 s4, s56, 0x10000
	s_addc_u32 s5, s57, 0
	s_add_u32 m0, s62, 0x1000
	s_nop 0
	global_load_lds_dwordx4 v162, s[4:5]

.Lg2_win_loop3:
	s_waitcnt vmcnt(0)
	s_barrier
	s_add_u32 s56, s56, 0x80
	s_addc_u32 s57, s57, 0
	s_add_u32 s58, s58, 0x800
	s_addc_u32 s59, s59, 0
	s_add_u32 s4, s56, 0x0
	s_addc_u32 s5, s57, 0
	s_add_u32 m0, s62, 0x8800
	s_nop 0
	global_load_lds_dwordx4 v162, s[4:5]
	s_cmp_gt_u32 s70, 1
	s_cbranch_scc1 .Lg2_win_nodma_4
	s_add_u32 s4, s56, 0x10000
	s_addc_u32 s5, s57, 0
	s_add_u32 m0, s62, 0x9800
	s_nop 0
	global_load_lds_dwordx4 v162, s[4:5]
.Lg2_win_nodma_4:
	global_load_dwordx4 v[200:203], v160, s[58:59] offset:0
	global_load_dwordx4 v[204:207], v160, s[58:59] offset:1024
	global_load_dwordx4 v[208:211], v161, s[58:59] offset:0
	global_load_dwordx4 v[240:243], v161, s[58:59] offset:1024
	ds_read_b128 v[136:139], v156 offset:0
	ds_read_b128 v[140:143], v156 offset:2048
	ds_read_b128 v[144:147], v156 offset:4096
	ds_read_b128 v[164:167], v157 offset:0
	ds_read_b128 v[168:171], v157 offset:2048
	ds_read_b128 v[172:175], v157 offset:4096
	s_waitcnt lgkmcnt(3)
	v_mfma_f32_16x16x32_bf16 v[0:3], v[184:187], v[136:139], v[0:3]
	v_mfma_f32_16x16x32_bf16 v[4:7], v[192:195], v[136:139], v[4:7]
	v_mfma_f32_16x16x32_bf16 v[8:11], v[184:187], v[140:143], v[8:11]
	v_mfma_f32_16x16x32_bf16 v[12:15], v[192:195], v[140:143], v[12:15]
	v_mfma_f32_16x16x32_bf16 v[16:19], v[184:187], v[144:147], v[16:19]
	v_mfma_f32_16x16x32_bf16 v[20:23], v[192:195], v[144:147], v[20:23]
	s_waitcnt lgkmcnt(0)
	v_mfma_f32_16x16x32_bf16 v[0:3], v[188:191], v[164:167], v[0:3]
	v_mfma_f32_16x16x32_bf16 v[4:7], v[196:199], v[164:167], v[4:7]
	v_mfma_f32_16x16x32_bf16 v[8:11], v[188:191], v[168:171], v[8:11]
	v_mfma_f32_16x16x32_bf16 v[12:15], v[196:199], v[168:171], v[12:15]
	v_mfma_f32_16x16x32_bf16 v[16:19], v[188:191], v[172:175], v[16:19]
	v_mfma_f32_16x16x32_bf16 v[20:23], v[196:199], v[172:175], v[20:23]
	s_waitcnt vmcnt(0)
	s_barrier
	s_cmp_ge_u32 s63, 14
	s_cbranch_scc1 .Lg2_win_noissue3
	s_add_u32 s56, s56, 0x80
	s_addc_u32 s57, s57, 0
	s_add_u32 s58, s58, 0x800
	s_addc_u32 s59, s59, 0
	s_add_u32 s4, s56, 0x0
	s_addc_u32 s5, s57, 0
	s_add_u32 m0, s62, 0x0
	s_nop 0
	global_load_lds_dwordx4 v162, s[4:5]
	s_cmp_gt_u32 s70, 1
	s_cbranch_scc1 .Lg2_win_nodma_5
	s_add_u32 s4, s56, 0x10000
	s_addc_u32 s5, s57, 0
	s_add_u32 m0, s62, 0x1000
	s_nop 0
	global_load_lds_dwordx4 v162, s[4:5]

.Lg2_win_noissue3:
	ds_read_b128 v[136:139], v158 offset:0
	ds_read_b128 v[140:143], v158 offset:2048
	ds_read_b128 v[144:147], v158 offset:4096
	ds_read_b128 v[164:167], v159 offset:0
	ds_read_b128 v[168:171], v159 offset:2048
	ds_read_b128 v[172:175], v159 offset:4096
	s_waitcnt lgkmcnt(3)
	v_mfma_f32_16x16x32_bf16 v[0:3], v[200:203], v[136:139], v[0:3]
	v_mfma_f32_16x16x32_bf16 v[4:7], v[208:211], v[136:139], v[4:7]
	v_mfma_f32_16x16x32_bf16 v[8:11], v[200:203], v[140:143], v[8:11]
	v_mfma_f32_16x16x32_bf16 v[12:15], v[208:211], v[140:143], v[12:15]
	v_mfma_f32_16x16x32_bf16 v[16:19], v[200:203], v[144:147], v[16:19]
	v_mfma_f32_16x16x32_bf16 v[20:23], v[208:211], v[144:147], v[20:23]
	s_waitcnt lgkmcnt(0)
	v_mfma_f32_16x16x32_bf16 v[0:3], v[204:207], v[164:167], v[0:3]
	v_mfma_f32_16x16x32_bf16 v[4:7], v[240:243], v[164:167], v[4:7]
	v_mfma_f32_16x16x32_bf16 v[8:11], v[204:207], v[168:171], v[8:11]
	v_mfma_f32_16x16x32_bf16 v[12:15], v[240:243], v[168:171], v[12:15]
	v_mfma_f32_16x16x32_bf16 v[16:19], v[204:207], v[172:175], v[16:19]
	v_mfma_f32_16x16x32_bf16 v[20:23], v[240:243], v[172:175], v[20:23]
	s_add_i32 s63, s63, 2
	s_cmp_lt_u32 s63, 16
	s_cbranch_scc1 .Lg2_win_loop3
	s_branch .Lg2_win_epiK
.Lg2_win_k2:
	v_mov_b32_e32 v0, 0
	v_mov_b32_e32 v1, 0
	v_mov_b32_e32 v2, 0
	v_mov_b32_e32 v3, 0
	v_mov_b32_e32 v4, 0
	v_mov_b32_e32 v5, 0
	v_mov_b32_e32 v6, 0
	v_mov_b32_e32 v7, 0
	v_mov_b32_e32 v8, 0
	v_mov_b32_e32 v9, 0
	v_mov_b32_e32 v10, 0
	v_mov_b32_e32 v11, 0
	v_mov_b32_e32 v12, 0
	v_mov_b32_e32 v13, 0
	v_mov_b32_e32 v14, 0
	v_mov_b32_e32 v15, 0
	s_add_u32 s4, s56, 0x0
	s_addc_u32 s5, s57, 0
	s_add_u32 m0, s62, 0x0
	s_nop 0
	global_load_lds_dwordx4 v162, s[4:5]
	global_load_dwordx4 v[184:187], v160, s[58:59] offset:0
	global_load_dwordx4 v[188:191], v160, s[58:59] offset:1024
	global_load_dwordx4 v[192:195], v161, s[58:59] offset:0
	global_load_dwordx4 v[196:199], v161, s[58:59] offset:1024
	s_mov_b32 s63, 0
.Lg2_win_loop2:
	s_waitcnt vmcnt(0)
	s_barrier
	s_add_u32 s56, s56, 0x80
	s_addc_u32 s57, s57, 0
	s_add_u32 s58, s58, 0x800
	s_addc_u32 s59, s59, 0
	s_add_u32 s4, s56, 0x0
	s_addc_u32 s5, s57, 0
	s_add_u32 m0, s62, 0x8800
	s_nop 0
	global_load_lds_dwordx4 v162, s[4:5]
	global_load_dwordx4 v[200:203], v160, s[58:59] offset:0
	global_load_dwordx4 v[204:207], v160, s[58:59] offset:1024
	global_load_dwordx4 v[208:211], v161, s[58:59] offset:0
	global_load_dwordx4 v[240:243], v161, s[58:59] offset:1024
	ds_read_b128 v[136:139], v156 offset:0
	ds_read_b128 v[140:143], v156 offset:2048
	ds_read_b128 v[164:167], v157 offset:0
	ds_read_b128 v[168:171], v157 offset:2048
	s_waitcnt lgkmcnt(2)
	v_mfma_f32_16x16x32_bf16 v[0:3], v[184:187], v[136:139], v[0:3]
	v_mfma_f32_16x16x32_bf16 v[4:7], v[192:195], v[136:139], v[4:7]
	v_mfma_f32_16x16x32_bf16 v[8:11], v[184:187], v[140:143], v[8:11]
	v_mfma_f32_16x16x32_bf16 v[12:15], v[192:195], v[140:143], v[12:15]
	s_waitcnt lgkmcnt(0)
	v_mfma_f32_16x16x32_bf16 v[0:3], v[188:191], v[164:167], v[0:3]
	v_mfma_f32_16x16x32_bf16 v[4:7], v[196:199], v[164:167], v[4:7]
	v_mfma_f32_16x16x32_bf16 v[8:11], v[188:191], v[168:171], v[8:11]
	v_mfma_f32_16x16x32_bf16 v[12:15], v[196:199], v[168:171], v[12:15]
	s_waitcnt vmcnt(0)
	s_barrier
	s_cmp_ge_u32 s63, 14
	s_cbranch_scc1 .Lg2_win_noissue2
	s_add_u32 s56, s56, 0x80
	s_addc_u32 s57, s57, 0
	s_add_u32 s58, s58, 0x800
	s_addc_u32 s59, s59, 0
	s_add_u32 s4, s56, 0x0
	s_addc_u32 s5, s57, 0
	s_add_u32 m0, s62, 0x0
	s_nop 0
	global_load_lds_dwordx4 v162, s[4:5]
	global_load_dwordx4 v[184:187], v160, s[58:59] offset:0
	global_load_dwordx4 v[188:191], v160, s[58:59] offset:1024
	global_load_dwordx4 v[192:195], v161, s[58:59] offset:0
	global_load_dwordx4 v[196:199], v161, s[58:59] offset:1024
.Lg2_win_noissue2:
	ds_read_b128 v[136:139], v158 offset:0
	ds_read_b128 v[140:143], v158 offset:2048
	ds_read_b128 v[164:167], v159 offset:0
	ds_read_b128 v[168:171], v159 offset:2048
	s_waitcnt lgkmcnt(2)
	v_mfma_f32_16x16x32_bf16 v[0:3], v[200:203], v[136:139], v[0:3]
	v_mfma_f32_16x16x32_bf16 v[4:7], v[208:211], v[136:139], v[4:7]
	v_mfma_f32_16x16x32_bf16 v[8:11], v[200:203], v[140:143], v[8:11]
	v_mfma_f32_16x16x32_bf16 v[12:15], v[208:211], v[140:143], v[12:15]
	s_waitcnt lgkmcnt(0)
	v_mfma_f32_16x16x32_bf16 v[0:3], v[204:207], v[164:167], v[0:3]
	v_mfma_f32_16x16x32_bf16 v[4:7], v[240:243], v[164:167], v[4:7]
	v_mfma_f32_16x16x32_bf16 v[8:11], v[204:207], v[168:171], v[8:11]
	v_mfma_f32_16x16x32_bf16 v[12:15], v[240:243], v[168:171], v[12:15]
	s_add_i32 s63, s63, 2
	s_cmp_lt_u32 s63, 16
	s_cbranch_scc1 .Lg2_win_loop2
	s_branch .Lg2_win_epiK
.Lg2_win_epiK:
	s_nop 7
	s_nop 7
	s_barrier
	v_and_b32_e32 v148, 15, v163
	v_bfe_u32 v149, v163, 4, 2
	v_cmp_gt_u32_e32 vcc, 2, v149
	s_nop 1
	v_cndmask_b32_e64 v150, 0, 1, vcc
	v_and_b32_e32 v149, 1, v149
	v_lshlrev_b32_e32 v149, 4, v149
	s_add_u32 s2, s26, 0x19dcc000
	s_addc_u32 s3, s27, 0
	s_add_u32 s4, s26, 0x19dcd000
	s_addc_u32 s5, s27, 0
	s_add_i32 s0, s69, 0
	v_add_u32_e32 v140, s0, v148
	v_subrev_u32_e32 v141, 0x2100, v140
	v_cmp_gt_u32_e32 vcc, 0x2100, v140
	s_nop 1
	v_cndmask_b32_e32 v141, v141, v140, vcc
	v_subrev_u32_e32 v142, 0x100, v141
	v_lshrrev_b32_e32 v143, 6, v142
	v_and_b32_e32 v143, 0x7f, v143
	v_and_b32_e32 v140, 63, v142
	v_cmp_eq_u32_e32 vcc, 1, v150
	s_nop 1
	v_cndmask_b32_e32 v143, v140, v143, vcc
	v_cmp_le_u32_e32 vcc, 0x100, v141
	s_nop 1
	v_cndmask_b32_e32 v143, 0, v143, vcc
	v_lshl_add_u32 v151, v143, 5, v149
	global_load_dwordx4 v[164:167], v151, s[2:3]
	global_load_dwordx4 v[168:171], v151, s[4:5]
	s_add_i32 s0, s69, 16
	v_add_u32_e32 v140, s0, v148
	v_subrev_u32_e32 v141, 0x2100, v140
	v_cmp_gt_u32_e32 vcc, 0x2100, v140
	s_nop 1
	v_cndmask_b32_e32 v141, v141, v140, vcc
	v_subrev_u32_e32 v142, 0x100, v141
	v_lshrrev_b32_e32 v143, 6, v142
	v_and_b32_e32 v143, 0x7f, v143
	v_and_b32_e32 v140, 63, v142
	v_cmp_eq_u32_e32 vcc, 1, v150
	s_nop 1
	v_cndmask_b32_e32 v143, v140, v143, vcc
	v_cmp_le_u32_e32 vcc, 0x100, v141
	s_nop 1
	v_cndmask_b32_e32 v143, 0, v143, vcc
	v_lshl_add_u32 v151, v143, 5, v149
	global_load_dwordx4 v[172:175], v151, s[2:3]
	global_load_dwordx4 v[176:179], v151, s[4:5]
	s_waitcnt vmcnt(2)
	v_mul_f32_e32 v152, v4, v168
	v_mul_f32_e32 v153, v4, v164
	v_fma_f32 v4, v0, v168, v153
	v_fma_f32 v0, v0, v164, -v152
	v_mul_f32_e32 v152, v5, v169
	v_mul_f32_e32 v153, v5, v165
	v_fma_f32 v5, v1, v169, v153
	v_fma_f32 v1, v1, v165, -v152
	v_mul_f32_e32 v152, v6, v170
	v_mul_f32_e32 v153, v6, v166
	v_fma_f32 v6, v2, v170, v153
	v_fma_f32 v2, v2, v166, -v152
	v_mul_f32_e32 v152, v7, v171
	v_mul_f32_e32 v153, v7, v167
	v_fma_f32 v7, v3, v171, v153
	v_fma_f32 v3, v3, v167, -v152
	v_cvt_pk_bf16_f32 v0, v0, v1
	v_cvt_pk_bf16_f32 v1, v2, v3
	ds_write_b64 v212, v[0:1] offset:0
	v_cvt_pk_bf16_f32 v4, v4, v5
	v_cvt_pk_bf16_f32 v5, v6, v7
	ds_write_b64 v213, v[4:5] offset:0
	s_add_i32 s0, s69, 32
	v_add_u32_e32 v140, s0, v148
	v_subrev_u32_e32 v141, 0x2100, v140
	v_cmp_gt_u32_e32 vcc, 0x2100, v140
	s_nop 1
	v_cndmask_b32_e32 v141, v141, v140, vcc
	v_subrev_u32_e32 v142, 0x100, v141
	v_lshrrev_b32_e32 v143, 6, v142
	v_and_b32_e32 v143, 0x7f, v143
	v_and_b32_e32 v140, 63, v142
	v_cmp_eq_u32_e32 vcc, 1, v150
	s_nop 1
	v_cndmask_b32_e32 v143, v140, v143, vcc
	v_cmp_le_u32_e32 vcc, 0x100, v141
	s_nop 1
	v_cndmask_b32_e32 v143, 0, v143, vcc
	v_lshl_add_u32 v151, v143, 5, v149
	global_load_dwordx4 v[164:167], v151, s[2:3]
	global_load_dwordx4 v[168:171], v151, s[4:5]
	s_waitcnt vmcnt(2)
	v_mul_f32_e32 v152, v12, v176
	v_mul_f32_e32 v153, v12, v172
	v_fma_f32 v12, v8, v176, v153
	v_fma_f32 v8, v8, v172, -v152
	v_mul_f32_e32 v152, v13, v177
	v_mul_f32_e32 v153, v13, v173
	v_fma_f32 v13, v9, v177, v153
	v_fma_f32 v9, v9, v173, -v152
	v_mul_f32_e32 v152, v14, v178
	v_mul_f32_e32 v153, v14, v174
	v_fma_f32 v14, v10, v178, v153
	v_fma_f32 v10, v10, v174, -v152
	v_mul_f32_e32 v152, v15, v179
	v_mul_f32_e32 v153, v15, v175
	v_fma_f32 v15, v11, v179, v153
	v_fma_f32 v11, v11, v175, -v152
	v_cvt_pk_bf16_f32 v8, v8, v9
	v_cvt_pk_bf16_f32 v9, v10, v11
	ds_write_b64 v212, v[8:9] offset:4096
	v_cvt_pk_bf16_f32 v12, v12, v13
	v_cvt_pk_bf16_f32 v13, v14, v15
	ds_write_b64 v213, v[12:13] offset:4096
	s_cmp_eq_u32 s65, 0
	s_cbranch_scc1 .Lg2_win_st_lastK
	s_waitcnt vmcnt(0)
	v_mul_f32_e32 v152, v20, v168
	v_mul_f32_e32 v153, v20, v164
	v_fma_f32 v20, v16, v168, v153
	v_fma_f32 v16, v16, v164, -v152
	v_mul_f32_e32 v152, v21, v169
	v_mul_f32_e32 v153, v21, v165
	v_fma_f32 v21, v17, v169, v153
	v_fma_f32 v17, v17, v165, -v152
	v_mul_f32_e32 v152, v22, v170
	v_mul_f32_e32 v153, v22, v166
	v_fma_f32 v22, v18, v170, v153
	v_fma_f32 v18, v18, v166, -v152
	v_mul_f32_e32 v152, v23, v171
	v_mul_f32_e32 v153, v23, v167
	v_fma_f32 v23, v19, v171, v153
	v_fma_f32 v19, v19, v167, -v152
	v_cvt_pk_bf16_f32 v16, v16, v17
	v_cvt_pk_bf16_f32 v17, v18, v19
	ds_write_b64 v212, v[16:17] offset:8192
	v_cvt_pk_bf16_f32 v20, v20, v21
	v_cvt_pk_bf16_f32 v21, v22, v23
	ds_write_b64 v213, v[20:21] offset:8192
.Lg2_win_st_lastK:
	s_waitcnt vmcnt(0) lgkmcnt(0)
	s_barrier
	ds_read_b128 v[0:3], v247 offset:0
	ds_read_b128 v[4:7], v247 offset:4096
	s_cmp_eq_u32 s65, 0
	s_cbranch_scc1 .Lg2_win_rd_lastaK
	ds_read_b128 v[8:11], v247 offset:8192
.Lg2_win_rd_lastaK:
	s_waitcnt lgkmcnt(0)
	global_store_dwordx4 v252, v[0:3], s[60:61]
	s_add_u32 s60, s60, 0x39000
	s_addc_u32 s61, s61, 0
	global_store_dwordx4 v252, v[4:7], s[60:61]
	s_add_u32 s60, s60, 0x39000
	s_addc_u32 s61, s61, 0
	s_cmp_eq_u32 s65, 0
	s_cbranch_scc1 .Lg2_win_rd_lastK
	global_store_dwordx4 v252, v[8:11], s[60:61]
	s_add_u32 s60, s60, 0x39000
	s_addc_u32 s61, s61, 0

.Lg2_win_exit:
	v_mov_b32_e32 v2, 0x10200
	v_mov_b32_e32 v4, s66
	v_mov_b32_e32 v5, s67
	ds_write_b64 v2, v[4:5]
	v_mov_b32_e32 v1, 0
	s_waitcnt vmcnt(0) lgkmcnt(0)
	v_readlane_b32 s56, v244, 40
	v_readlane_b32 s57, v244, 41
	v_readlane_b32 s58, v244, 42
	v_readlane_b32 s59, v244, 43
	v_readlane_b32 s60, v244, 44
	v_readlane_b32 s61, v244, 45
	v_readlane_b32 s62, v244, 46
	v_readlane_b32 s63, v244, 47
	v_readlane_b32 s64, v244, 48
	v_readlane_b32 s65, v244, 49
	v_readlane_b32 s66, v244, 50
	v_readlane_b32 s67, v244, 51
	v_readlane_b32 s68, v244, 52
	v_readlane_b32 s69, v244, 53
	v_readlane_b32 s70, v244, 54
	v_readlane_b32 s71, v244, 55
	v_readlane_b32 s44, v235, 8
	v_readlane_b32 s45, v235, 9
	s_branch .LBB0_720

.LBB0_786:
	v_readlane_b32 s0, v235, 17
	v_readlane_b32 s1, v235, 18
	s_mov_b32 s1, s9
	v_writelane_b32 v235, s0, 17
	s_mov_b64 s[2:3], 0
	v_readlane_b32 s4, v246, 13
	v_writelane_b32 v235, s1, 18
	s_add_u32 s0, s26, s2
	v_readlane_b32 s5, v246, 14
	s_addc_u32 s1, s27, s3
	v_mov_b32_e32 v4, v163
	s_andn2_b64 vcc, exec, s[4:5]
	s_movk_i32 s31, 0x7080
	s_cbranch_vccnz .LBB0_789
	v_readlane_b32 s2, v235, 17
	s_mul_hi_u32 s3, s2, 0x1c20000
	s_mul_i32 s2, s2, 0x1c20000
	s_add_u32 s2, s68, s2
	s_addc_u32 s3, s69, s3
	s_add_u32 s4, s26, 0xeb20000
	s_addc_u32 s5, s27, 0
	v_lshrrev_b32_e32 v2, 3, v163
	v_and_b32_e32 v3, 7, v163
	v_lshlrev_b32_e32 v3, 4, v3
	s_mov_b32 s0, 0x7080
	v_mul_lo_u32 v4, v2, s0
	v_add_u32_e32 v4, v4, v3
	v_add_u32_e32 v5, 0xe1000, v4
	s_movk_i32 s0, 0x84
	v_mul_lo_u32 v6, v2, s0
	v_add_u32_e32 v6, v6, v3
	v_and_b32_e32 v9, 31, v163
	v_lshrrev_b32_e32 v18, 5, v163
	s_movk_i32 s0, 0x420
	v_mul_lo_u32 v7, v18, s0
	v_lshl_add_u32 v7, v9, 2, v7
	v_lshrrev_b32_e32 v19, 4, v9
	s_mov_b32 s0, 0x8000
	v_mul_lo_u32 v8, v19, s0
	v_lshrrev_b32_e32 v19, 2, v18
	v_lshl_add_u32 v8, v19, 10, v8
	v_and_b32_e32 v19, 3, v18
	v_lshl_add_u32 v8, v19, 8, v8
	v_and_b32_e32 v19, 15, v9
	v_lshl_add_u32 v8, v19, 4, v8
	v_readlane_b32 s6, v246, 0
.Lfm_a_win_loop:
	s_mul_hi_u32 s7, s6, 0x1234568
	s_mul_i32 s8, s7, 225
	s_sub_u32 s8, s6, s8
	s_mul_i32 s0, s7, 0x1c2000
	s_mul_hi_u32 s1, s7, 0x1c2000
	s_lshl_b32 s29, s8, 7
	s_add_u32 s0, s0, s29
	s_addc_u32 s1, s1, 0
	s_add_u32 s0, s2, s0
	s_addc_u32 s1, s3, s1
	s_sub_u32 s29, s8, 1
	s_cmp_lt_u32 s8, 128
	s_cselect_b32 s29, s8, s29
	s_cmp_eq_u32 s8, 128
	s_cselect_b32 s29, 224, s29
	s_lshl_b32 s29, s29, 16
	s_lshl_b32 s30, s7, 11
	s_add_u32 s29, s29, s30
	s_barrier
	global_load_dwordx4 v[10:13], v4, s[0:1]
	global_load_dwordx4 v[14:17], v5, s[0:1]
	s_waitcnt vmcnt(0)
	ds_write2_b32 v6, v10, v11 offset1:1
	ds_write2_b32 v6, v12, v13 offset0:2 offset1:3
	v_add_u32_e32 v19, 0x1080, v6
	ds_write2_b32 v19, v14, v15 offset1:1
	ds_write2_b32 v19, v16, v17 offset0:2 offset1:3
	s_waitcnt lgkmcnt(0)
	s_barrier
	ds_read_b32 v20, v7
	ds_read_b32 v21, v7 offset:132
	ds_read_b32 v22, v7 offset:264
	ds_read_b32 v23, v7 offset:396
	ds_read_b32 v24, v7 offset:528
	ds_read_b32 v25, v7 offset:660
	ds_read_b32 v26, v7 offset:792
	ds_read_b32 v27, v7 offset:924
	s_waitcnt lgkmcnt(0)
	v_cvt_pk_bf16_f32 v28, v20, v21
	v_cvt_pk_bf16_f32 v29, v22, v23
	v_cvt_pk_bf16_f32 v30, v24, v25
	v_cvt_pk_bf16_f32 v31, v26, v27
	s_add_u32 s0, s4, s29
	s_addc_u32 s1, s5, 0
	global_store_dwordx4 v8, v[28:31], s[0:1]
	s_add_i32 s6, s6, s10
	s_cmp_lt_u32 s6, 3600
	s_cbranch_scc1 .Lfm_a_win_loop
	s_waitcnt vmcnt(0) lgkmcnt(0)
	s_mov_b32 s0, s26
	s_mov_b32 s1, s27
	s_mov_b64 s[2:3], 0

.LBB0_815:
	v_readlane_b32 s2, v235, 17
	v_readlane_b32 s3, v235, 18
	s_lshl_b64 s[2:3], s[2:3], 22
	s_add_u32 s2, s14, s2
	s_addc_u32 s3, s15, s3
	s_add_u32 s4, s26, 0xfd40000
	s_addc_u32 s5, s27, 0
	v_lshrrev_b32_e32 v2, 3, v163
	v_and_b32_e32 v3, 7, v163
	v_lshlrev_b32_e32 v3, 4, v3
	s_mov_b32 s0, 0x1000
	v_mul_lo_u32 v4, v2, s0
	v_add_u32_e32 v4, v4, v3
	v_add_u32_e32 v5, 0x20000, v4
	s_movk_i32 s0, 0x84
	v_mul_lo_u32 v6, v2, s0
	v_add_u32_e32 v6, v6, v3
	v_and_b32_e32 v9, 31, v163
	v_lshrrev_b32_e32 v18, 5, v163
	s_movk_i32 s0, 0x420
	v_mul_lo_u32 v7, v18, s0
	v_lshl_add_u32 v7, v9, 2, v7
	v_lshrrev_b32_e32 v19, 4, v9
	s_mov_b32 s0, 0x8000
	v_mul_lo_u32 v8, v19, s0
	v_lshrrev_b32_e32 v19, 2, v18
	v_lshl_add_u32 v8, v19, 10, v8
	v_and_b32_e32 v19, 3, v18
	v_lshl_add_u32 v8, v19, 8, v8
	v_and_b32_e32 v19, 15, v9
	v_lshl_add_u32 v8, v19, 4, v8
	v_readlane_b32 s6, v246, 0
	s_cmp_lt_u32 s6, 512
	s_cbranch_scc0 .Lfm_a_out_done
.Lfm_a_out_loop:
	s_lshr_b32 s7, s6, 5
	s_and_b32 s8, s6, 31
	s_mul_i32 s0, s7, 0x40000
	s_mul_hi_u32 s1, s7, 0x40000
	s_lshl_b32 s29, s8, 7
	s_add_u32 s0, s0, s29
	s_addc_u32 s1, s1, 0
	s_add_u32 s0, s2, s0
	s_addc_u32 s1, s3, s1
	s_mul_i32 s29, s8, 0x10000
	s_lshl_b32 s30, s7, 11
	s_add_u32 s29, s29, s30
	s_barrier
	global_load_dwordx4 v[10:13], v4, s[0:1]
	global_load_dwordx4 v[14:17], v5, s[0:1]
	s_waitcnt vmcnt(0)
	ds_write2_b32 v6, v10, v11 offset1:1
	ds_write2_b32 v6, v12, v13 offset0:2 offset1:3
	v_add_u32_e32 v19, 0x1080, v6
	ds_write2_b32 v19, v14, v15 offset1:1
	ds_write2_b32 v19, v16, v17 offset0:2 offset1:3
	s_waitcnt lgkmcnt(0)
	s_barrier
	ds_read_b32 v20, v7
	ds_read_b32 v21, v7 offset:132
	ds_read_b32 v22, v7 offset:264
	ds_read_b32 v23, v7 offset:396
	ds_read_b32 v24, v7 offset:528
	ds_read_b32 v25, v7 offset:660
	ds_read_b32 v26, v7 offset:792
	ds_read_b32 v27, v7 offset:924
	s_waitcnt lgkmcnt(0)
	v_cvt_pk_bf16_f32 v28, v20, v21
	v_cvt_pk_bf16_f32 v29, v22, v23
	v_cvt_pk_bf16_f32 v30, v24, v25
	v_cvt_pk_bf16_f32 v31, v26, v27
	s_add_u32 s0, s4, s29
	s_addc_u32 s1, s5, 0
	global_store_dwordx4 v8, v[28:31], s[0:1]
	s_add_i32 s6, s6, s10
	s_cmp_lt_u32 s6, 512
	s_cbranch_scc1 .Lfm_a_out_loop
.Lfm_a_out_done:
	v_readlane_b32 s2, v235, 17
	v_readlane_b32 s3, v235, 18
	s_lshl_b64 s[2:3], s[2:3], 24
	s_add_u32 s2, s16, s2
	s_addc_u32 s3, s17, s3
	s_add_u32 s4, s26, 0xff40000
	s_addc_u32 s5, s27, 0
	v_lshrrev_b32_e32 v2, 3, v163
	v_and_b32_e32 v3, 7, v163
	v_lshlrev_b32_e32 v3, 4, v3
	s_mov_b32 s0, 0x4000
	v_mul_lo_u32 v4, v2, s0
	v_add_u32_e32 v4, v4, v3
	v_add_u32_e32 v5, 0x80000, v4
	s_movk_i32 s0, 0x84
	v_mul_lo_u32 v6, v2, s0
	v_add_u32_e32 v6, v6, v3
	v_and_b32_e32 v9, 31, v163
	v_lshrrev_b32_e32 v18, 5, v163
	s_movk_i32 s0, 0x420
	v_mul_lo_u32 v7, v18, s0
	v_lshl_add_u32 v7, v9, 2, v7
	v_lshrrev_b32_e32 v19, 4, v9
	s_mov_b32 s0, 0x8000
	v_mul_lo_u32 v8, v19, s0
	v_lshrrev_b32_e32 v19, 2, v18
	v_lshl_add_u32 v8, v19, 10, v8
	v_and_b32_e32 v19, 3, v18
	v_lshl_add_u32 v8, v19, 8, v8
	v_and_b32_e32 v19, 15, v9
	v_lshl_add_u32 v8, v19, 4, v8
	v_readlane_b32 s6, v246, 0
	s_cmp_lt_u32 s6, 2048
	s_cbranch_scc0 .Lfm_a_ff1_done
.Lfm_a_ff1_loop:
	s_lshr_b32 s7, s6, 7
	s_and_b32 s8, s6, 127
	s_mul_i32 s0, s7, 0x100000
	s_mul_hi_u32 s1, s7, 0x100000
	s_lshl_b32 s29, s8, 7
	s_add_u32 s0, s0, s29
	s_addc_u32 s1, s1, 0
	s_add_u32 s0, s2, s0
	s_addc_u32 s1, s3, s1
	s_mul_i32 s29, s8, 0x10000
	s_lshl_b32 s30, s7, 11
	s_add_u32 s29, s29, s30
	s_barrier
	global_load_dwordx4 v[10:13], v4, s[0:1]
	global_load_dwordx4 v[14:17], v5, s[0:1]
	s_waitcnt vmcnt(0)
	ds_write2_b32 v6, v10, v11 offset1:1
	ds_write2_b32 v6, v12, v13 offset0:2 offset1:3
	v_add_u32_e32 v19, 0x1080, v6
	ds_write2_b32 v19, v14, v15 offset1:1
	ds_write2_b32 v19, v16, v17 offset0:2 offset1:3
	s_waitcnt lgkmcnt(0)
	s_barrier
	ds_read_b32 v20, v7
	ds_read_b32 v21, v7 offset:132
	ds_read_b32 v22, v7 offset:264
	ds_read_b32 v23, v7 offset:396
	ds_read_b32 v24, v7 offset:528
	ds_read_b32 v25, v7 offset:660
	ds_read_b32 v26, v7 offset:792
	ds_read_b32 v27, v7 offset:924
	s_waitcnt lgkmcnt(0)
	v_cvt_pk_bf16_f32 v28, v20, v21
	v_cvt_pk_bf16_f32 v29, v22, v23
	v_cvt_pk_bf16_f32 v30, v24, v25
	v_cvt_pk_bf16_f32 v31, v26, v27
	s_add_u32 s0, s4, s29
	s_addc_u32 s1, s5, 0
	global_store_dwordx4 v8, v[28:31], s[0:1]
	s_add_i32 s6, s6, s10
	s_cmp_lt_u32 s6, 2048
	s_cbranch_scc1 .Lfm_a_ff1_loop
.Lfm_a_ff1_done:
	v_readlane_b32 s2, v235, 17
	v_readlane_b32 s3, v235, 18
	s_lshl_b64 s[2:3], s[2:3], 24
	s_add_u32 s2, s18, s2
	s_addc_u32 s3, s19, s3
	s_add_u32 s4, s26, 0x10740000
	s_addc_u32 s5, s27, 0
	v_lshrrev_b32_e32 v2, 3, v163
	v_and_b32_e32 v3, 7, v163
	v_lshlrev_b32_e32 v3, 4, v3
	s_mov_b32 s0, 0x1000
	v_mul_lo_u32 v4, v2, s0
	v_add_u32_e32 v4, v4, v3
	v_add_u32_e32 v5, 0x20000, v4
	s_movk_i32 s0, 0x84
	v_mul_lo_u32 v6, v2, s0
	v_add_u32_e32 v6, v6, v3
	v_and_b32_e32 v9, 31, v163
	v_lshrrev_b32_e32 v18, 5, v163
	s_movk_i32 s0, 0x420
	v_mul_lo_u32 v7, v18, s0
	v_lshl_add_u32 v7, v9, 2, v7
	v_lshrrev_b32_e32 v19, 4, v9
	s_mov_b32 s0, 0x20000
	v_mul_lo_u32 v8, v19, s0
	v_lshrrev_b32_e32 v19, 2, v18
	v_lshl_add_u32 v8, v19, 10, v8
	v_and_b32_e32 v19, 3, v18
	v_lshl_add_u32 v8, v19, 8, v8
	v_and_b32_e32 v19, 15, v9
	v_lshl_add_u32 v8, v19, 4, v8
	v_readlane_b32 s6, v246, 0
	s_cmp_lt_u32 s6, 2048
	s_cbranch_scc0 .Lfm_a_ff2_done
.Lfm_a_ff2_loop:
	s_lshr_b32 s7, s6, 5
	s_and_b32 s8, s6, 31
	s_mul_i32 s0, s7, 0x40000
	s_mul_hi_u32 s1, s7, 0x40000
	s_lshl_b32 s29, s8, 7
	s_add_u32 s0, s0, s29
	s_addc_u32 s1, s1, 0
	s_add_u32 s0, s2, s0
	s_addc_u32 s1, s3, s1
	s_mul_i32 s29, s8, 0x40000
	s_lshl_b32 s30, s7, 11
	s_add_u32 s29, s29, s30
	s_barrier
	global_load_dwordx4 v[10:13], v4, s[0:1]
	global_load_dwordx4 v[14:17], v5, s[0:1]
	s_waitcnt vmcnt(0)
	ds_write2_b32 v6, v10, v11 offset1:1
	ds_write2_b32 v6, v12, v13 offset0:2 offset1:3
	v_add_u32_e32 v19, 0x1080, v6
	ds_write2_b32 v19, v14, v15 offset1:1
	ds_write2_b32 v19, v16, v17 offset0:2 offset1:3
	s_waitcnt lgkmcnt(0)
	s_barrier
	ds_read_b32 v20, v7
	ds_read_b32 v21, v7 offset:132
	ds_read_b32 v22, v7 offset:264
	ds_read_b32 v23, v7 offset:396
	ds_read_b32 v24, v7 offset:528
	ds_read_b32 v25, v7 offset:660
	ds_read_b32 v26, v7 offset:792
	ds_read_b32 v27, v7 offset:924
	s_waitcnt lgkmcnt(0)
	v_cvt_pk_bf16_f32 v28, v20, v21
	v_cvt_pk_bf16_f32 v29, v22, v23
	v_cvt_pk_bf16_f32 v30, v24, v25
	v_cvt_pk_bf16_f32 v31, v26, v27
	s_add_u32 s0, s4, s29
	s_addc_u32 s1, s5, 0
	global_store_dwordx4 v8, v[28:31], s[0:1]
	s_add_i32 s6, s6, s10
	s_cmp_lt_u32 s6, 2048
	s_cbranch_scc1 .Lfm_a_ff2_loop
.Lfm_a_ff2_done:
	s_waitcnt vmcnt(0) lgkmcnt(0)
.LBB0_824:
	s_branch .LBB0_896

.LBB0_858:
	s_mov_b64 s[2:3], 0
	v_readlane_b32 s4, v246, 13
	s_barrier
	s_add_u32 s0, s26, s2
	v_readlane_b32 s5, v246, 14
	s_addc_u32 s1, s27, s3
	v_mov_b32_e32 v4, v163
	s_andn2_b64 vcc, exec, s[4:5]
	v_readlane_b32 s44, v235, 8
	v_readlane_b32 s45, v235, 9
	s_cbranch_vccnz .LBB0_861
	s_mov_b32 s2, s68
	s_mov_b32 s3, s69
	s_add_u32 s4, s26, 0xeb20000
	s_addc_u32 s5, s27, 0
	v_lshrrev_b32_e32 v2, 3, v163
	v_and_b32_e32 v3, 7, v163
	v_lshlrev_b32_e32 v3, 4, v3
	s_mov_b32 s0, 0x7080
	v_mul_lo_u32 v4, v2, s0
	v_add_u32_e32 v4, v4, v3
	v_add_u32_e32 v5, 0xe1000, v4
	s_movk_i32 s0, 0x84
	v_mul_lo_u32 v6, v2, s0
	v_add_u32_e32 v6, v6, v3
	v_and_b32_e32 v9, 31, v163
	v_lshrrev_b32_e32 v18, 5, v163
	s_movk_i32 s0, 0x420
	v_mul_lo_u32 v7, v18, s0
	v_lshl_add_u32 v7, v9, 2, v7
	v_lshrrev_b32_e32 v19, 4, v9
	s_mov_b32 s0, 0x8000
	v_mul_lo_u32 v8, v19, s0
	v_lshrrev_b32_e32 v19, 2, v18
	v_lshl_add_u32 v8, v19, 10, v8
	v_and_b32_e32 v19, 3, v18
	v_lshl_add_u32 v8, v19, 8, v8
	v_and_b32_e32 v19, 15, v9
	v_lshl_add_u32 v8, v19, 4, v8
	v_readlane_b32 s6, v246, 0

.LBB0_887:
	s_mov_b32 s2, s14
	s_mov_b32 s3, s15
	s_add_u32 s4, s26, 0xfd40000
	s_addc_u32 s5, s27, 0
	v_lshrrev_b32_e32 v2, 3, v163
	v_and_b32_e32 v3, 7, v163
	v_lshlrev_b32_e32 v3, 4, v3
	s_mov_b32 s0, 0x1000
	v_mul_lo_u32 v4, v2, s0
	v_add_u32_e32 v4, v4, v3
	v_add_u32_e32 v5, 0x20000, v4
	s_movk_i32 s0, 0x84
	v_mul_lo_u32 v6, v2, s0
	v_add_u32_e32 v6, v6, v3
	v_and_b32_e32 v9, 31, v163
	v_lshrrev_b32_e32 v18, 5, v163
	s_movk_i32 s0, 0x420
	v_mul_lo_u32 v7, v18, s0
	v_lshl_add_u32 v7, v9, 2, v7
	v_lshrrev_b32_e32 v19, 4, v9
	s_mov_b32 s0, 0x8000
	v_mul_lo_u32 v8, v19, s0
	v_lshrrev_b32_e32 v19, 2, v18
	v_lshl_add_u32 v8, v19, 10, v8
	v_and_b32_e32 v19, 3, v18
	v_lshl_add_u32 v8, v19, 8, v8
	v_and_b32_e32 v19, 15, v9
	v_lshl_add_u32 v8, v19, 4, v8
	v_readlane_b32 s6, v246, 0
	s_cmp_lt_u32 s6, 512
	s_cbranch_scc0 .Lfm_b_out_done

.Lfm_b_out_done:
	s_mov_b32 s2, s16
	s_mov_b32 s3, s17
	s_add_u32 s4, s26, 0xff40000
	s_addc_u32 s5, s27, 0
	v_lshrrev_b32_e32 v2, 3, v163
	v_and_b32_e32 v3, 7, v163
	v_lshlrev_b32_e32 v3, 4, v3
	s_mov_b32 s0, 0x4000
	v_mul_lo_u32 v4, v2, s0
	v_add_u32_e32 v4, v4, v3
	v_add_u32_e32 v5, 0x80000, v4
	s_movk_i32 s0, 0x84
	v_mul_lo_u32 v6, v2, s0
	v_add_u32_e32 v6, v6, v3
	v_and_b32_e32 v9, 31, v163
	v_lshrrev_b32_e32 v18, 5, v163
	s_movk_i32 s0, 0x420
	v_mul_lo_u32 v7, v18, s0
	v_lshl_add_u32 v7, v9, 2, v7
	v_lshrrev_b32_e32 v19, 4, v9
	s_mov_b32 s0, 0x8000
	v_mul_lo_u32 v8, v19, s0
	v_lshrrev_b32_e32 v19, 2, v18
	v_lshl_add_u32 v8, v19, 10, v8
	v_and_b32_e32 v19, 3, v18
	v_lshl_add_u32 v8, v19, 8, v8
	v_and_b32_e32 v19, 15, v9
	v_lshl_add_u32 v8, v19, 4, v8
	v_readlane_b32 s6, v246, 0
	s_cmp_lt_u32 s6, 2048
	s_cbranch_scc0 .Lfm_b_ff1_done

.Lfm_b_ff1_done:
	s_mov_b32 s2, s18
	s_mov_b32 s3, s19
	s_add_u32 s4, s26, 0x10740000
	s_addc_u32 s5, s27, 0
	v_lshrrev_b32_e32 v2, 3, v163
	v_and_b32_e32 v3, 7, v163
	v_lshlrev_b32_e32 v3, 4, v3
	s_mov_b32 s0, 0x1000
	v_mul_lo_u32 v4, v2, s0
	v_add_u32_e32 v4, v4, v3
	v_add_u32_e32 v5, 0x20000, v4
	s_movk_i32 s0, 0x84
	v_mul_lo_u32 v6, v2, s0
	v_add_u32_e32 v6, v6, v3
	v_and_b32_e32 v9, 31, v163
	v_lshrrev_b32_e32 v18, 5, v163
	s_movk_i32 s0, 0x420
	v_mul_lo_u32 v7, v18, s0
	v_lshl_add_u32 v7, v9, 2, v7
	v_lshrrev_b32_e32 v19, 4, v9
	s_mov_b32 s0, 0x20000
	v_mul_lo_u32 v8, v19, s0
	v_lshrrev_b32_e32 v19, 2, v18
	v_lshl_add_u32 v8, v19, 10, v8
	v_and_b32_e32 v19, 3, v18
	v_lshl_add_u32 v8, v19, 8, v8
	v_and_b32_e32 v19, 15, v9
	v_lshl_add_u32 v8, v19, 4, v8
	v_readlane_b32 s6, v246, 0
	s_cmp_lt_u32 s6, 2048
	s_cbranch_scc0 .Lfm_b_ff2_done

.Lfm_b_ff2_done:
	s_waitcnt vmcnt(0) lgkmcnt(0)
.LBB0_896:
	s_add_i32 s96, s96, 1
	s_cmp_ge_i32 s96, s97
	s_mov_b64 s[0:1], -1
	v_readlane_b32 s2, v235, 14
	v_readlane_b32 s3, v235, 15
	s_cbranch_scc1 .Ltramp_BB0_9
	v_readlane_b32 s0, v246, 62
	v_readlane_b32 s1, v246, 63
	s_andn2_b64 vcc, exec, s[0:1]
	s_cbranch_vccnz .LBB0_909
	s_waitcnt vmcnt(0) lgkmcnt(0)
	s_barrier
	s_mov_b64 s[0:1], exec
	v_readlane_b32 s2, v244, 16
	v_readlane_b32 s3, v244, 17
	s_and_b64 s[2:3], s[0:1], s[2:3]
	s_mov_b64 exec, s[2:3]
	s_cbranch_execz .LBB0_908
	v_readlane_b32 s2, v246, 1
	v_readlane_b32 s3, v246, 2
	buffer_wbl2 sc1
	s_load_dwordx2 s[2:3], s[2:3], 0x58
	s_mov_b64 s[4:5], exec
	v_mbcnt_lo_u32_b32 v2, s4, 0
	v_mbcnt_hi_u32_b32 v2, s5, v2
	v_cmp_eq_u32_e32 vcc, 0, v2
	s_waitcnt lgkmcnt(0)
	global_load_dword v0, v1, s[2:3] offset:40
	s_and_saveexec_b64 s[6:7], vcc
	s_cbranch_execz .LBB0_901
	s_bcnt1_i32_b64 s4, s[4:5]
	v_mov_b32_e32 v3, s4
	global_atomic_add v3, v1, v3, s[2:3] offset:32 sc0
